# q/kv up-projection tiles: first k-loop LDS-DMA stage issued before the row-norm pre-pass
# baseline (speedup 1.0000x reference)
.Lrm_done:
	s_cmpk_gt_i32 s20, 0x21f
	s_mov_b64 s[0:1], -1
	s_cbranch_scc0 .LBB0_906
	s_add_i32 s16, s20, 0xfde0
	s_and_b32 s8, s16, 0xffff
	s_mul_i32 s0, s8, 0xaaab
	v_mov_b32_e32 v128, v167
	s_lshr_b32 s9, s0, 18
	s_lshl_b32 s21, s9, 8
	v_ashrrev_i32_e32 v129, 1, v128
	v_and_b32_e32 v1, 0xffffffe0, v129
	v_add_u32_e32 v62, s21, v1
	v_and_b32_e32 v1, 64, v192
	v_add_u32_e32 v1, 64, v1
	v_xor_b32_e32 v2, 32, v192
	v_cmp_lt_i32_e32 vcc, v2, v1
	v_and_b32_e32 v0, 63, v128
	v_lshlrev_b32_e32 v164, 4, v0
	v_cndmask_b32_e32 v2, v192, v2, vcc
	v_lshlrev_b32_e32 v63, 2, v2
	v_xor_b32_e32 v2, 16, v192
	v_cmp_lt_i32_e32 vcc, v2, v1
	v_readlane_b32 s1, v254, 47
	v_lshl_add_u64 v[60:61], s[22:23], 0, v[164:165]
	v_cndmask_b32_e32 v2, v192, v2, vcc
	v_lshlrev_b32_e32 v64, 2, v2
	v_xor_b32_e32 v2, 8, v192
	v_cmp_lt_i32_e32 vcc, v2, v1
	s_mov_b32 s0, 0
	v_cmp_eq_u32_e64 s[10:11], 0, v0
	v_cndmask_b32_e32 v2, v192, v2, vcc
	v_lshlrev_b32_e32 v65, 2, v2
	v_xor_b32_e32 v2, 4, v192
	v_cmp_lt_i32_e32 vcc, v2, v1
	v_lshl_add_u32 v69, v129, 2, s1
	s_mov_b64 s[2:3], -1
	v_cndmask_b32_e32 v2, v192, v2, vcc
	v_lshlrev_b32_e32 v66, 2, v2
	v_xor_b32_e32 v2, 2, v192
	v_cmp_lt_i32_e32 vcc, v2, v1
	s_nop 1
	v_cndmask_b32_e32 v2, v192, v2, vcc
	v_lshlrev_b32_e32 v67, 2, v2
	v_xor_b32_e32 v2, 1, v192
	v_cmp_lt_i32_e32 vcc, v2, v1
	s_nop 1
	v_cndmask_b32_e32 v1, v192, v2, vcc
	v_lshlrev_b32_e32 v68, 2, v1
	v_lshlrev_b32_e32 v80, 4, v167
	v_and_b32_e32 v81, 32, v167
	v_and_b32_e32 v82, 48, v80
	v_xor_b32_e32 v81, v81, v82
	v_lshrrev_b32_e32 v81, 1, v81
	v_lshrrev_b32_e32 v82, 1, v167
	v_and_b32_e32 v82, 32, v82
	v_or_b32_e32 v81, v81, v82
	v_and_b32_e32 v97, 0xfffffc00, v80
	v_lshrrev_b32_e32 v82, 2, v167
	v_and_b32_e32 v82, 15, v82
	v_lshrrev_b32_e32 v83, 3, v167
	v_and_b32_e32 v84, -16, v83
	v_or_b32_e32 v85, v84, v82
	v_add_u32_e32 v84, 64, v83
	v_and_b32_e32 v84, -16, v84
	v_or_b32_e32 v86, v84, v82
	v_add_u32_e32 v84, 128, v83
	v_and_b32_e32 v84, -16, v84
	v_or_b32_e32 v87, v84, v82
	v_add_u32_e32 v84, 192, v83
	v_and_b32_e32 v84, -16, v84
	v_or_b32_e32 v88, v84, v82
	v_mul_u32_u24_e32 v89, 0xb80, v85
	v_add_lshl_u32 v89, v89, v81, 1
	v_mul_u32_u24_e32 v90, 0xb80, v86
	v_add_lshl_u32 v90, v90, v81, 1
	v_mul_u32_u24_e32 v91, 0xb80, v87
	v_add_lshl_u32 v91, v91, v81, 1
	v_mul_u32_u24_e32 v92, 0xb80, v88
	v_add_lshl_u32 v92, v92, v81, 1
	v_lshl_or_b32 v93, v85, 9, v81
	v_lshlrev_b32_e32 v93, 1, v93
	v_lshl_or_b32 v94, v86, 9, v81
	v_lshlrev_b32_e32 v94, 1, v94
	v_lshl_or_b32 v95, v87, 9, v81
	v_lshlrev_b32_e32 v95, 1, v95
	v_lshl_or_b32 v96, v88, 9, v81
	v_lshlrev_b32_e32 v96, 1, v96
	s_nop 1
	v_readfirstlane_b32 s2, v97
	s_mul_i32 s0, s9, 0x170000
	s_add_u32 s0, s22, s0
	s_addc_u32 s1, s23, 0
	s_mov_b32 m0, s2
	s_nop 0
	global_load_lds_dwordx4 v89, s[0:1]
	s_add_u32 s24, s2, 8192
	s_mov_b32 m0, s24
	s_nop 0
	global_load_lds_dwordx4 v90, s[0:1]
	s_add_u32 s24, s2, 16384
	s_mov_b32 m0, s24
	s_nop 0
	global_load_lds_dwordx4 v91, s[0:1]
	s_add_u32 s24, s2, 24576
	s_mov_b32 m0, s24
	s_nop 0
	global_load_lds_dwordx4 v92, s[0:1]
	s_mul_i32 s0, s9, 6
	s_sub_u32 s0, s16, s0
	s_and_b32 s0, s0, 0xffff
	s_lshl_b32 s0, s0, 18
	s_add_u32 s0, s12, s0
	s_addc_u32 s1, s13, 0
	s_add_u32 s24, s2, 32768
	s_mov_b32 m0, s24
	s_nop 0
	global_load_lds_dwordx4 v93, s[0:1]
	s_add_u32 s24, s2, 40960
	s_mov_b32 m0, s24
	s_nop 0
	global_load_lds_dwordx4 v94, s[0:1]
	s_add_u32 s24, s2, 49152
	s_mov_b32 m0, s24
	s_nop 0
	global_load_lds_dwordx4 v95, s[0:1]
	s_add_u32 s24, s2, 57344
	s_mov_b32 m0, s24
	s_nop 0
	global_load_lds_dwordx4 v96, s[0:1]
	v_readfirstlane_b32 s0, v167
	v_and_b32_e32 v116, 63, v167
	v_and_b32_e32 v118, 15, v167
	s_lshr_b32 s0, s0, 6
	s_lshl_b32 s1, s0, 5
	s_add_u32 s2, s21, s1
	s_mul_i32 s2, s2, 0x1700
	s_add_u32 s24, s22, s2
	s_addc_u32 s25, s23, 0
	v_lshlrev_b32_e32 v116, 4, v116
	v_and_b32_e32 v117, 48, v167
	s_lshl_b32 s1, s0, 7
	v_add_u32_e32 v117, s1, v117
	v_add_u32_e32 v117, 0x20000, v117
	global_load_dwordx4 v[16:19], v116, s[24:25]
	s_add_u32 s24, s24, 0x1700
	s_addc_u32 s25, s25, 0
	global_load_dwordx4 v[20:23], v116, s[24:25]
	s_add_u32 s24, s24, 0x1700
	s_addc_u32 s25, s25, 0
	global_load_dwordx4 v[24:27], v116, s[24:25]
	s_add_u32 s24, s24, 0x1700
	s_addc_u32 s25, s25, 0
	global_load_dwordx4 v[28:31], v116, s[24:25]
	s_add_u32 s24, s24, 0x1700
	s_addc_u32 s25, s25, 0
	global_load_dwordx4 v[32:35], v116, s[24:25]
	s_add_u32 s24, s24, 0x1700
	s_addc_u32 s25, s25, 0
	global_load_dwordx4 v[36:39], v116, s[24:25]
	s_add_u32 s24, s24, 0x1700
	s_addc_u32 s25, s25, 0
	global_load_dwordx4 v[40:43], v116, s[24:25]
	s_add_u32 s24, s24, 0x1700
	s_addc_u32 s25, s25, 0
	global_load_dwordx4 v[44:47], v116, s[24:25]
	s_add_u32 s24, s24, 0x1700
	s_addc_u32 s25, s25, 0
	global_load_dwordx4 v[48:51], v116, s[24:25]
	s_add_u32 s24, s24, 0x1700
	s_addc_u32 s25, s25, 0
	global_load_dwordx4 v[52:55], v116, s[24:25]
	s_add_u32 s24, s24, 0x1700
	s_addc_u32 s25, s25, 0
	global_load_dwordx4 v[56:59], v116, s[24:25]
	s_add_u32 s24, s24, 0x1700
	s_addc_u32 s25, s25, 0
	global_load_dwordx4 v[60:63], v116, s[24:25]
	s_add_u32 s24, s24, 0x1700
	s_addc_u32 s25, s25, 0
	global_load_dwordx4 v[64:67], v116, s[24:25]
	s_add_u32 s24, s24, 0x1700
	s_addc_u32 s25, s25, 0
	global_load_dwordx4 v[68:71], v116, s[24:25]
	s_add_u32 s24, s24, 0x1700
	s_addc_u32 s25, s25, 0
	global_load_dwordx4 v[72:75], v116, s[24:25]
	s_add_u32 s24, s24, 0x1700
	s_addc_u32 s25, s25, 0
	global_load_dwordx4 v[76:79], v116, s[24:25]
	s_add_u32 s24, s24, 0x1700
	s_addc_u32 s25, s25, 0
	s_waitcnt vmcnt(15)
	v_lshlrev_b32_e32 v112, 16, v16
	v_and_b32_e32 v16, 0xffff0000, v16
	v_mul_f32_e32 v16, v16, v16
	v_fmac_f32_e32 v16, v112, v112
	v_lshlrev_b32_e32 v112, 16, v17
	v_and_b32_e32 v17, 0xffff0000, v17
	v_mul_f32_e32 v17, v17, v17
	v_fmac_f32_e32 v17, v112, v112
	v_add_f32_e32 v16, v16, v17
	v_lshlrev_b32_e32 v112, 16, v18
	v_and_b32_e32 v18, 0xffff0000, v18
	v_mul_f32_e32 v18, v18, v18
	v_fmac_f32_e32 v18, v112, v112
	v_add_f32_e32 v16, v16, v18
	v_lshlrev_b32_e32 v112, 16, v19
	v_and_b32_e32 v19, 0xffff0000, v19
	v_mul_f32_e32 v19, v19, v19
	v_fmac_f32_e32 v19, v112, v112
	v_add_f32_e32 v16, v16, v19
	s_waitcnt vmcnt(14)
	v_lshlrev_b32_e32 v112, 16, v20
	v_and_b32_e32 v20, 0xffff0000, v20
	v_mul_f32_e32 v20, v20, v20
	v_fmac_f32_e32 v20, v112, v112
	v_lshlrev_b32_e32 v112, 16, v21
	v_and_b32_e32 v21, 0xffff0000, v21
	v_mul_f32_e32 v21, v21, v21
	v_fmac_f32_e32 v21, v112, v112
	v_add_f32_e32 v20, v20, v21
	v_lshlrev_b32_e32 v112, 16, v22
	v_and_b32_e32 v22, 0xffff0000, v22
	v_mul_f32_e32 v22, v22, v22
	v_fmac_f32_e32 v22, v112, v112
	v_add_f32_e32 v20, v20, v22
	v_lshlrev_b32_e32 v112, 16, v23
	v_and_b32_e32 v23, 0xffff0000, v23
	v_mul_f32_e32 v23, v23, v23
	v_fmac_f32_e32 v23, v112, v112
	v_add_f32_e32 v20, v20, v23
	s_waitcnt vmcnt(13)
	v_lshlrev_b32_e32 v112, 16, v24
	v_and_b32_e32 v24, 0xffff0000, v24
	v_mul_f32_e32 v24, v24, v24
	v_fmac_f32_e32 v24, v112, v112
	v_lshlrev_b32_e32 v112, 16, v25
	v_and_b32_e32 v25, 0xffff0000, v25
	v_mul_f32_e32 v25, v25, v25
	v_fmac_f32_e32 v25, v112, v112
	v_add_f32_e32 v24, v24, v25
	v_lshlrev_b32_e32 v112, 16, v26
	v_and_b32_e32 v26, 0xffff0000, v26
	v_mul_f32_e32 v26, v26, v26
	v_fmac_f32_e32 v26, v112, v112
	v_add_f32_e32 v24, v24, v26
	v_lshlrev_b32_e32 v112, 16, v27
	v_and_b32_e32 v27, 0xffff0000, v27
	v_mul_f32_e32 v27, v27, v27
	v_fmac_f32_e32 v27, v112, v112
	v_add_f32_e32 v24, v24, v27
	s_waitcnt vmcnt(12)
	v_lshlrev_b32_e32 v112, 16, v28
	v_and_b32_e32 v28, 0xffff0000, v28
	v_mul_f32_e32 v28, v28, v28
	v_fmac_f32_e32 v28, v112, v112
	v_lshlrev_b32_e32 v112, 16, v29
	v_and_b32_e32 v29, 0xffff0000, v29
	v_mul_f32_e32 v29, v29, v29
	v_fmac_f32_e32 v29, v112, v112
	v_add_f32_e32 v28, v28, v29
	v_lshlrev_b32_e32 v112, 16, v30
	v_and_b32_e32 v30, 0xffff0000, v30
	v_mul_f32_e32 v30, v30, v30
	v_fmac_f32_e32 v30, v112, v112
	v_add_f32_e32 v28, v28, v30
	v_lshlrev_b32_e32 v112, 16, v31
	v_and_b32_e32 v31, 0xffff0000, v31
	v_mul_f32_e32 v31, v31, v31
	v_fmac_f32_e32 v31, v112, v112
	v_add_f32_e32 v28, v28, v31
	s_waitcnt vmcnt(11)
	v_lshlrev_b32_e32 v112, 16, v32
	v_and_b32_e32 v32, 0xffff0000, v32
	v_mul_f32_e32 v32, v32, v32
	v_fmac_f32_e32 v32, v112, v112
	v_lshlrev_b32_e32 v112, 16, v33
	v_and_b32_e32 v33, 0xffff0000, v33
	v_mul_f32_e32 v33, v33, v33
	v_fmac_f32_e32 v33, v112, v112
	v_add_f32_e32 v32, v32, v33
	v_lshlrev_b32_e32 v112, 16, v34
	v_and_b32_e32 v34, 0xffff0000, v34
	v_mul_f32_e32 v34, v34, v34
	v_fmac_f32_e32 v34, v112, v112
	v_add_f32_e32 v32, v32, v34
	v_lshlrev_b32_e32 v112, 16, v35
	v_and_b32_e32 v35, 0xffff0000, v35
	v_mul_f32_e32 v35, v35, v35
	v_fmac_f32_e32 v35, v112, v112
	v_add_f32_e32 v32, v32, v35
	s_waitcnt vmcnt(10)
	v_lshlrev_b32_e32 v112, 16, v36
	v_and_b32_e32 v36, 0xffff0000, v36
	v_mul_f32_e32 v36, v36, v36
	v_fmac_f32_e32 v36, v112, v112
	v_lshlrev_b32_e32 v112, 16, v37
	v_and_b32_e32 v37, 0xffff0000, v37
	v_mul_f32_e32 v37, v37, v37
	v_fmac_f32_e32 v37, v112, v112
	v_add_f32_e32 v36, v36, v37
	v_lshlrev_b32_e32 v112, 16, v38
	v_and_b32_e32 v38, 0xffff0000, v38
	v_mul_f32_e32 v38, v38, v38
	v_fmac_f32_e32 v38, v112, v112
	v_add_f32_e32 v36, v36, v38
	v_lshlrev_b32_e32 v112, 16, v39
	v_and_b32_e32 v39, 0xffff0000, v39
	v_mul_f32_e32 v39, v39, v39
	v_fmac_f32_e32 v39, v112, v112
	v_add_f32_e32 v36, v36, v39
	s_waitcnt vmcnt(9)
	v_lshlrev_b32_e32 v112, 16, v40
	v_and_b32_e32 v40, 0xffff0000, v40
	v_mul_f32_e32 v40, v40, v40
	v_fmac_f32_e32 v40, v112, v112
	v_lshlrev_b32_e32 v112, 16, v41
	v_and_b32_e32 v41, 0xffff0000, v41
	v_mul_f32_e32 v41, v41, v41
	v_fmac_f32_e32 v41, v112, v112
	v_add_f32_e32 v40, v40, v41
	v_lshlrev_b32_e32 v112, 16, v42
	v_and_b32_e32 v42, 0xffff0000, v42
	v_mul_f32_e32 v42, v42, v42
	v_fmac_f32_e32 v42, v112, v112
	v_add_f32_e32 v40, v40, v42
	v_lshlrev_b32_e32 v112, 16, v43
	v_and_b32_e32 v43, 0xffff0000, v43
	v_mul_f32_e32 v43, v43, v43
	v_fmac_f32_e32 v43, v112, v112
	v_add_f32_e32 v40, v40, v43
	s_waitcnt vmcnt(8)
	v_lshlrev_b32_e32 v112, 16, v44
	v_and_b32_e32 v44, 0xffff0000, v44
	v_mul_f32_e32 v44, v44, v44
	v_fmac_f32_e32 v44, v112, v112
	v_lshlrev_b32_e32 v112, 16, v45
	v_and_b32_e32 v45, 0xffff0000, v45
	v_mul_f32_e32 v45, v45, v45
	v_fmac_f32_e32 v45, v112, v112
	v_add_f32_e32 v44, v44, v45
	v_lshlrev_b32_e32 v112, 16, v46
	v_and_b32_e32 v46, 0xffff0000, v46
	v_mul_f32_e32 v46, v46, v46
	v_fmac_f32_e32 v46, v112, v112
	v_add_f32_e32 v44, v44, v46
	v_lshlrev_b32_e32 v112, 16, v47
	v_and_b32_e32 v47, 0xffff0000, v47
	v_mul_f32_e32 v47, v47, v47
	v_fmac_f32_e32 v47, v112, v112
	v_add_f32_e32 v44, v44, v47
	s_waitcnt vmcnt(7)
	v_lshlrev_b32_e32 v112, 16, v48
	v_and_b32_e32 v48, 0xffff0000, v48
	v_mul_f32_e32 v48, v48, v48
	v_fmac_f32_e32 v48, v112, v112
	v_lshlrev_b32_e32 v112, 16, v49
	v_and_b32_e32 v49, 0xffff0000, v49
	v_mul_f32_e32 v49, v49, v49
	v_fmac_f32_e32 v49, v112, v112
	v_add_f32_e32 v48, v48, v49
	v_lshlrev_b32_e32 v112, 16, v50
	v_and_b32_e32 v50, 0xffff0000, v50
	v_mul_f32_e32 v50, v50, v50
	v_fmac_f32_e32 v50, v112, v112
	v_add_f32_e32 v48, v48, v50
	v_lshlrev_b32_e32 v112, 16, v51
	v_and_b32_e32 v51, 0xffff0000, v51
	v_mul_f32_e32 v51, v51, v51
	v_fmac_f32_e32 v51, v112, v112
	v_add_f32_e32 v48, v48, v51
	s_waitcnt vmcnt(6)
	v_lshlrev_b32_e32 v112, 16, v52
	v_and_b32_e32 v52, 0xffff0000, v52
	v_mul_f32_e32 v52, v52, v52
	v_fmac_f32_e32 v52, v112, v112
	v_lshlrev_b32_e32 v112, 16, v53
	v_and_b32_e32 v53, 0xffff0000, v53
	v_mul_f32_e32 v53, v53, v53
	v_fmac_f32_e32 v53, v112, v112
	v_add_f32_e32 v52, v52, v53
	v_lshlrev_b32_e32 v112, 16, v54
	v_and_b32_e32 v54, 0xffff0000, v54
	v_mul_f32_e32 v54, v54, v54
	v_fmac_f32_e32 v54, v112, v112
	v_add_f32_e32 v52, v52, v54
	v_lshlrev_b32_e32 v112, 16, v55
	v_and_b32_e32 v55, 0xffff0000, v55
	v_mul_f32_e32 v55, v55, v55
	v_fmac_f32_e32 v55, v112, v112
	v_add_f32_e32 v52, v52, v55
	s_waitcnt vmcnt(5)
	v_lshlrev_b32_e32 v112, 16, v56
	v_and_b32_e32 v56, 0xffff0000, v56
	v_mul_f32_e32 v56, v56, v56
	v_fmac_f32_e32 v56, v112, v112
	v_lshlrev_b32_e32 v112, 16, v57
	v_and_b32_e32 v57, 0xffff0000, v57
	v_mul_f32_e32 v57, v57, v57
	v_fmac_f32_e32 v57, v112, v112
	v_add_f32_e32 v56, v56, v57
	v_lshlrev_b32_e32 v112, 16, v58
	v_and_b32_e32 v58, 0xffff0000, v58
	v_mul_f32_e32 v58, v58, v58
	v_fmac_f32_e32 v58, v112, v112
	v_add_f32_e32 v56, v56, v58
	v_lshlrev_b32_e32 v112, 16, v59
	v_and_b32_e32 v59, 0xffff0000, v59
	v_mul_f32_e32 v59, v59, v59
	v_fmac_f32_e32 v59, v112, v112
	v_add_f32_e32 v56, v56, v59
	s_waitcnt vmcnt(4)
	v_lshlrev_b32_e32 v112, 16, v60
	v_and_b32_e32 v60, 0xffff0000, v60
	v_mul_f32_e32 v60, v60, v60
	v_fmac_f32_e32 v60, v112, v112
	v_lshlrev_b32_e32 v112, 16, v61
	v_and_b32_e32 v61, 0xffff0000, v61
	v_mul_f32_e32 v61, v61, v61
	v_fmac_f32_e32 v61, v112, v112
	v_add_f32_e32 v60, v60, v61
	v_lshlrev_b32_e32 v112, 16, v62
	v_and_b32_e32 v62, 0xffff0000, v62
	v_mul_f32_e32 v62, v62, v62
	v_fmac_f32_e32 v62, v112, v112
	v_add_f32_e32 v60, v60, v62
	v_lshlrev_b32_e32 v112, 16, v63
	v_and_b32_e32 v63, 0xffff0000, v63
	v_mul_f32_e32 v63, v63, v63
	v_fmac_f32_e32 v63, v112, v112
	v_add_f32_e32 v60, v60, v63
	s_waitcnt vmcnt(3)
	v_lshlrev_b32_e32 v112, 16, v64
	v_and_b32_e32 v64, 0xffff0000, v64
	v_mul_f32_e32 v64, v64, v64
	v_fmac_f32_e32 v64, v112, v112
	v_lshlrev_b32_e32 v112, 16, v65
	v_and_b32_e32 v65, 0xffff0000, v65
	v_mul_f32_e32 v65, v65, v65
	v_fmac_f32_e32 v65, v112, v112
	v_add_f32_e32 v64, v64, v65
	v_lshlrev_b32_e32 v112, 16, v66
	v_and_b32_e32 v66, 0xffff0000, v66
	v_mul_f32_e32 v66, v66, v66
	v_fmac_f32_e32 v66, v112, v112
	v_add_f32_e32 v64, v64, v66
	v_lshlrev_b32_e32 v112, 16, v67
	v_and_b32_e32 v67, 0xffff0000, v67
	v_mul_f32_e32 v67, v67, v67
	v_fmac_f32_e32 v67, v112, v112
	v_add_f32_e32 v64, v64, v67
	s_waitcnt vmcnt(2)
	v_lshlrev_b32_e32 v112, 16, v68
	v_and_b32_e32 v68, 0xffff0000, v68
	v_mul_f32_e32 v68, v68, v68
	v_fmac_f32_e32 v68, v112, v112
	v_lshlrev_b32_e32 v112, 16, v69
	v_and_b32_e32 v69, 0xffff0000, v69
	v_mul_f32_e32 v69, v69, v69
	v_fmac_f32_e32 v69, v112, v112
	v_add_f32_e32 v68, v68, v69
	v_lshlrev_b32_e32 v112, 16, v70
	v_and_b32_e32 v70, 0xffff0000, v70
	v_mul_f32_e32 v70, v70, v70
	v_fmac_f32_e32 v70, v112, v112
	v_add_f32_e32 v68, v68, v70
	v_lshlrev_b32_e32 v112, 16, v71
	v_and_b32_e32 v71, 0xffff0000, v71
	v_mul_f32_e32 v71, v71, v71
	v_fmac_f32_e32 v71, v112, v112
	v_add_f32_e32 v68, v68, v71
	s_waitcnt vmcnt(1)
	v_lshlrev_b32_e32 v112, 16, v72
	v_and_b32_e32 v72, 0xffff0000, v72
	v_mul_f32_e32 v72, v72, v72
	v_fmac_f32_e32 v72, v112, v112
	v_lshlrev_b32_e32 v112, 16, v73
	v_and_b32_e32 v73, 0xffff0000, v73
	v_mul_f32_e32 v73, v73, v73
	v_fmac_f32_e32 v73, v112, v112
	v_add_f32_e32 v72, v72, v73
	v_lshlrev_b32_e32 v112, 16, v74
	v_and_b32_e32 v74, 0xffff0000, v74
	v_mul_f32_e32 v74, v74, v74
	v_fmac_f32_e32 v74, v112, v112
	v_add_f32_e32 v72, v72, v74
	v_lshlrev_b32_e32 v112, 16, v75
	v_and_b32_e32 v75, 0xffff0000, v75
	v_mul_f32_e32 v75, v75, v75
	v_fmac_f32_e32 v75, v112, v112
	v_add_f32_e32 v72, v72, v75
	s_waitcnt vmcnt(0)
	v_lshlrev_b32_e32 v112, 16, v76
	v_and_b32_e32 v76, 0xffff0000, v76
	v_mul_f32_e32 v76, v76, v76
	v_fmac_f32_e32 v76, v112, v112
	v_lshlrev_b32_e32 v112, 16, v77
	v_and_b32_e32 v77, 0xffff0000, v77
	v_mul_f32_e32 v77, v77, v77
	v_fmac_f32_e32 v77, v112, v112
	v_add_f32_e32 v76, v76, v77
	v_lshlrev_b32_e32 v112, 16, v78
	v_and_b32_e32 v78, 0xffff0000, v78
	v_mul_f32_e32 v78, v78, v78
	v_fmac_f32_e32 v78, v112, v112
	v_add_f32_e32 v76, v76, v78
	v_lshlrev_b32_e32 v112, 16, v79
	v_and_b32_e32 v79, 0xffff0000, v79
	v_mul_f32_e32 v79, v79, v79
	v_fmac_f32_e32 v79, v112, v112
	v_add_f32_e32 v76, v76, v79
	s_nop 1
	v_permlane32_swap_b32_e32 v16, v48
	v_permlane32_swap_b32_e32 v20, v52
	v_permlane32_swap_b32_e32 v24, v56
	v_permlane32_swap_b32_e32 v28, v60
	v_permlane32_swap_b32_e32 v32, v64
	v_permlane32_swap_b32_e32 v36, v68
	v_permlane32_swap_b32_e32 v40, v72
	v_permlane32_swap_b32_e32 v44, v76
	s_nop 0
	v_add_f32_e32 v16, v16, v48
	v_add_f32_e32 v20, v20, v52
	v_add_f32_e32 v24, v24, v56
	v_add_f32_e32 v28, v28, v60
	v_add_f32_e32 v32, v32, v64
	v_add_f32_e32 v36, v36, v68
	v_add_f32_e32 v40, v40, v72
	v_add_f32_e32 v44, v44, v76
	s_nop 1
	v_permlane16_swap_b32_e32 v16, v32
	v_permlane16_swap_b32_e32 v20, v36
	v_permlane16_swap_b32_e32 v24, v40
	v_permlane16_swap_b32_e32 v28, v44
	s_nop 0
	v_add_f32_e32 v16, v16, v32
	v_add_f32_e32 v20, v20, v36
	v_add_f32_e32 v24, v24, v40
	v_add_f32_e32 v28, v28, v44
	s_nop 1
	v_add_f32_dpp v16, v16, v16 row_ror:8 row_mask:0xf bank_mask:0xf
	v_add_f32_dpp v20, v20, v20 row_ror:8 row_mask:0xf bank_mask:0xf
	v_add_f32_dpp v24, v24, v24 row_ror:8 row_mask:0xf bank_mask:0xf
	v_add_f32_dpp v28, v28, v28 row_ror:8 row_mask:0xf bank_mask:0xf
	s_nop 1
	v_add_f32_dpp v16, v16, v16 row_ror:4 row_mask:0xf bank_mask:0xf
	v_add_f32_dpp v20, v20, v20 row_ror:4 row_mask:0xf bank_mask:0xf
	v_add_f32_dpp v24, v24, v24 row_ror:4 row_mask:0xf bank_mask:0xf
	v_add_f32_dpp v28, v28, v28 row_ror:4 row_mask:0xf bank_mask:0xf
	s_nop 1
	v_add_f32_dpp v16, v16, v16 row_ror:2 row_mask:0xf bank_mask:0xf
	v_add_f32_dpp v20, v20, v20 row_ror:2 row_mask:0xf bank_mask:0xf
	v_add_f32_dpp v24, v24, v24 row_ror:2 row_mask:0xf bank_mask:0xf
	v_add_f32_dpp v28, v28, v28 row_ror:2 row_mask:0xf bank_mask:0xf
	s_nop 1
	v_add_f32_dpp v16, v16, v16 row_ror:1 row_mask:0xf bank_mask:0xf
	v_add_f32_dpp v20, v20, v20 row_ror:1 row_mask:0xf bank_mask:0xf
	v_add_f32_dpp v24, v24, v24 row_ror:1 row_mask:0xf bank_mask:0xf
	v_add_f32_dpp v28, v28, v28 row_ror:1 row_mask:0xf bank_mask:0xf
	v_fmamk_f32 v16, v16, 0x3b000000, v166
	v_fmamk_f32 v20, v20, 0x3b000000, v166
	v_fmamk_f32 v24, v24, 0x3b000000, v166
	v_fmamk_f32 v28, v28, 0x3b000000, v166
	v_mul_f32_e32 v112, 0x4b800000, v16
	v_cmp_gt_f32_e32 vcc, s58, v16
	s_nop 1
	v_cndmask_b32_e32 v16, v16, v112, vcc
	v_rsq_f32_e32 v16, v16
	s_nop 0
	v_mul_f32_e32 v112, 0x45800000, v16
	v_cndmask_b32_e32 v16, v16, v112, vcc
	v_mul_f32_e32 v16, 0x3dd53b94, v16
	v_mul_f32_e32 v112, 0x4b800000, v20
	v_cmp_gt_f32_e32 vcc, s58, v20
	s_nop 1
	v_cndmask_b32_e32 v20, v20, v112, vcc
	v_rsq_f32_e32 v20, v20
	s_nop 0
	v_mul_f32_e32 v112, 0x45800000, v20
	v_cndmask_b32_e32 v20, v20, v112, vcc
	v_mul_f32_e32 v20, 0x3dd53b94, v20
	v_mul_f32_e32 v112, 0x4b800000, v24
	v_cmp_gt_f32_e32 vcc, s58, v24
	s_nop 1
	v_cndmask_b32_e32 v24, v24, v112, vcc
	v_rsq_f32_e32 v24, v24
	s_nop 0
	v_mul_f32_e32 v112, 0x45800000, v24
	v_cndmask_b32_e32 v24, v24, v112, vcc
	v_mul_f32_e32 v24, 0x3dd53b94, v24
	v_mul_f32_e32 v112, 0x4b800000, v28
	v_cmp_gt_f32_e32 vcc, s58, v28
	s_nop 1
	v_cndmask_b32_e32 v28, v28, v112, vcc
	v_rsq_f32_e32 v28, v28
	s_nop 0
	v_mul_f32_e32 v112, 0x45800000, v28
	v_cndmask_b32_e32 v28, v28, v112, vcc
	v_mul_f32_e32 v28, 0x3dd53b94, v28
	v_mov_b32_e32 v112, v16
	v_mov_b32_e32 v113, v20
	v_mov_b32_e32 v114, v24
	v_mov_b32_e32 v115, v28
	v_cmp_eq_u32_e32 vcc, 0, v118
	s_and_saveexec_b64 s[0:1], vcc
	ds_write_b128 v117, v[112:115]
	s_or_b64 exec, exec, s[0:1]
	global_load_dwordx4 v[16:19], v116, s[24:25]
	s_add_u32 s24, s24, 0x1700
	s_addc_u32 s25, s25, 0
	global_load_dwordx4 v[20:23], v116, s[24:25]
	s_add_u32 s24, s24, 0x1700
	s_addc_u32 s25, s25, 0
	global_load_dwordx4 v[24:27], v116, s[24:25]
	s_add_u32 s24, s24, 0x1700
	s_addc_u32 s25, s25, 0
	global_load_dwordx4 v[28:31], v116, s[24:25]
	s_add_u32 s24, s24, 0x1700
	s_addc_u32 s25, s25, 0
	global_load_dwordx4 v[32:35], v116, s[24:25]
	s_add_u32 s24, s24, 0x1700
	s_addc_u32 s25, s25, 0
	global_load_dwordx4 v[36:39], v116, s[24:25]
	s_add_u32 s24, s24, 0x1700
	s_addc_u32 s25, s25, 0
	global_load_dwordx4 v[40:43], v116, s[24:25]
	s_add_u32 s24, s24, 0x1700
	s_addc_u32 s25, s25, 0
	global_load_dwordx4 v[44:47], v116, s[24:25]
	s_add_u32 s24, s24, 0x1700
	s_addc_u32 s25, s25, 0
	global_load_dwordx4 v[48:51], v116, s[24:25]
	s_add_u32 s24, s24, 0x1700
	s_addc_u32 s25, s25, 0
	global_load_dwordx4 v[52:55], v116, s[24:25]
	s_add_u32 s24, s24, 0x1700
	s_addc_u32 s25, s25, 0
	global_load_dwordx4 v[56:59], v116, s[24:25]
	s_add_u32 s24, s24, 0x1700
	s_addc_u32 s25, s25, 0
	global_load_dwordx4 v[60:63], v116, s[24:25]
	s_add_u32 s24, s24, 0x1700
	s_addc_u32 s25, s25, 0
	global_load_dwordx4 v[64:67], v116, s[24:25]
	s_add_u32 s24, s24, 0x1700
	s_addc_u32 s25, s25, 0
	global_load_dwordx4 v[68:71], v116, s[24:25]
	s_add_u32 s24, s24, 0x1700
	s_addc_u32 s25, s25, 0
	global_load_dwordx4 v[72:75], v116, s[24:25]
	s_add_u32 s24, s24, 0x1700
	s_addc_u32 s25, s25, 0
	global_load_dwordx4 v[76:79], v116, s[24:25]
	s_add_u32 s24, s24, 0x1700
	s_addc_u32 s25, s25, 0
	s_waitcnt vmcnt(15)
	v_lshlrev_b32_e32 v112, 16, v16
	v_and_b32_e32 v16, 0xffff0000, v16
	v_mul_f32_e32 v16, v16, v16
	v_fmac_f32_e32 v16, v112, v112
	v_lshlrev_b32_e32 v112, 16, v17
	v_and_b32_e32 v17, 0xffff0000, v17
	v_mul_f32_e32 v17, v17, v17
	v_fmac_f32_e32 v17, v112, v112
	v_add_f32_e32 v16, v16, v17
	v_lshlrev_b32_e32 v112, 16, v18
	v_and_b32_e32 v18, 0xffff0000, v18
	v_mul_f32_e32 v18, v18, v18
	v_fmac_f32_e32 v18, v112, v112
	v_add_f32_e32 v16, v16, v18
	v_lshlrev_b32_e32 v112, 16, v19
	v_and_b32_e32 v19, 0xffff0000, v19
	v_mul_f32_e32 v19, v19, v19
	v_fmac_f32_e32 v19, v112, v112
	v_add_f32_e32 v16, v16, v19
	s_waitcnt vmcnt(14)
	v_lshlrev_b32_e32 v112, 16, v20
	v_and_b32_e32 v20, 0xffff0000, v20
	v_mul_f32_e32 v20, v20, v20
	v_fmac_f32_e32 v20, v112, v112
	v_lshlrev_b32_e32 v112, 16, v21
	v_and_b32_e32 v21, 0xffff0000, v21
	v_mul_f32_e32 v21, v21, v21
	v_fmac_f32_e32 v21, v112, v112
	v_add_f32_e32 v20, v20, v21
	v_lshlrev_b32_e32 v112, 16, v22
	v_and_b32_e32 v22, 0xffff0000, v22
	v_mul_f32_e32 v22, v22, v22
	v_fmac_f32_e32 v22, v112, v112
	v_add_f32_e32 v20, v20, v22
	v_lshlrev_b32_e32 v112, 16, v23
	v_and_b32_e32 v23, 0xffff0000, v23
	v_mul_f32_e32 v23, v23, v23
	v_fmac_f32_e32 v23, v112, v112
	v_add_f32_e32 v20, v20, v23
	s_waitcnt vmcnt(13)
	v_lshlrev_b32_e32 v112, 16, v24
	v_and_b32_e32 v24, 0xffff0000, v24
	v_mul_f32_e32 v24, v24, v24
	v_fmac_f32_e32 v24, v112, v112
	v_lshlrev_b32_e32 v112, 16, v25
	v_and_b32_e32 v25, 0xffff0000, v25
	v_mul_f32_e32 v25, v25, v25
	v_fmac_f32_e32 v25, v112, v112
	v_add_f32_e32 v24, v24, v25
	v_lshlrev_b32_e32 v112, 16, v26
	v_and_b32_e32 v26, 0xffff0000, v26
	v_mul_f32_e32 v26, v26, v26
	v_fmac_f32_e32 v26, v112, v112
	v_add_f32_e32 v24, v24, v26
	v_lshlrev_b32_e32 v112, 16, v27
	v_and_b32_e32 v27, 0xffff0000, v27
	v_mul_f32_e32 v27, v27, v27
	v_fmac_f32_e32 v27, v112, v112
	v_add_f32_e32 v24, v24, v27
	s_waitcnt vmcnt(12)
	v_lshlrev_b32_e32 v112, 16, v28
	v_and_b32_e32 v28, 0xffff0000, v28
	v_mul_f32_e32 v28, v28, v28
	v_fmac_f32_e32 v28, v112, v112
	v_lshlrev_b32_e32 v112, 16, v29
	v_and_b32_e32 v29, 0xffff0000, v29
	v_mul_f32_e32 v29, v29, v29
	v_fmac_f32_e32 v29, v112, v112
	v_add_f32_e32 v28, v28, v29
	v_lshlrev_b32_e32 v112, 16, v30
	v_and_b32_e32 v30, 0xffff0000, v30
	v_mul_f32_e32 v30, v30, v30
	v_fmac_f32_e32 v30, v112, v112
	v_add_f32_e32 v28, v28, v30
	v_lshlrev_b32_e32 v112, 16, v31
	v_and_b32_e32 v31, 0xffff0000, v31
	v_mul_f32_e32 v31, v31, v31
	v_fmac_f32_e32 v31, v112, v112
	v_add_f32_e32 v28, v28, v31
	s_waitcnt vmcnt(11)
	v_lshlrev_b32_e32 v112, 16, v32
	v_and_b32_e32 v32, 0xffff0000, v32
	v_mul_f32_e32 v32, v32, v32
	v_fmac_f32_e32 v32, v112, v112
	v_lshlrev_b32_e32 v112, 16, v33
	v_and_b32_e32 v33, 0xffff0000, v33
	v_mul_f32_e32 v33, v33, v33
	v_fmac_f32_e32 v33, v112, v112
	v_add_f32_e32 v32, v32, v33
	v_lshlrev_b32_e32 v112, 16, v34
	v_and_b32_e32 v34, 0xffff0000, v34
	v_mul_f32_e32 v34, v34, v34
	v_fmac_f32_e32 v34, v112, v112
	v_add_f32_e32 v32, v32, v34
	v_lshlrev_b32_e32 v112, 16, v35
	v_and_b32_e32 v35, 0xffff0000, v35
	v_mul_f32_e32 v35, v35, v35
	v_fmac_f32_e32 v35, v112, v112
	v_add_f32_e32 v32, v32, v35
	s_waitcnt vmcnt(10)
	v_lshlrev_b32_e32 v112, 16, v36
	v_and_b32_e32 v36, 0xffff0000, v36
	v_mul_f32_e32 v36, v36, v36
	v_fmac_f32_e32 v36, v112, v112
	v_lshlrev_b32_e32 v112, 16, v37
	v_and_b32_e32 v37, 0xffff0000, v37
	v_mul_f32_e32 v37, v37, v37
	v_fmac_f32_e32 v37, v112, v112
	v_add_f32_e32 v36, v36, v37
	v_lshlrev_b32_e32 v112, 16, v38
	v_and_b32_e32 v38, 0xffff0000, v38
	v_mul_f32_e32 v38, v38, v38
	v_fmac_f32_e32 v38, v112, v112
	v_add_f32_e32 v36, v36, v38
	v_lshlrev_b32_e32 v112, 16, v39
	v_and_b32_e32 v39, 0xffff0000, v39
	v_mul_f32_e32 v39, v39, v39
	v_fmac_f32_e32 v39, v112, v112
	v_add_f32_e32 v36, v36, v39
	s_waitcnt vmcnt(9)
	v_lshlrev_b32_e32 v112, 16, v40
	v_and_b32_e32 v40, 0xffff0000, v40
	v_mul_f32_e32 v40, v40, v40
	v_fmac_f32_e32 v40, v112, v112
	v_lshlrev_b32_e32 v112, 16, v41
	v_and_b32_e32 v41, 0xffff0000, v41
	v_mul_f32_e32 v41, v41, v41
	v_fmac_f32_e32 v41, v112, v112
	v_add_f32_e32 v40, v40, v41
	v_lshlrev_b32_e32 v112, 16, v42
	v_and_b32_e32 v42, 0xffff0000, v42
	v_mul_f32_e32 v42, v42, v42
	v_fmac_f32_e32 v42, v112, v112
	v_add_f32_e32 v40, v40, v42
	v_lshlrev_b32_e32 v112, 16, v43
	v_and_b32_e32 v43, 0xffff0000, v43
	v_mul_f32_e32 v43, v43, v43
	v_fmac_f32_e32 v43, v112, v112
	v_add_f32_e32 v40, v40, v43
	s_waitcnt vmcnt(8)
	v_lshlrev_b32_e32 v112, 16, v44
	v_and_b32_e32 v44, 0xffff0000, v44
	v_mul_f32_e32 v44, v44, v44
	v_fmac_f32_e32 v44, v112, v112
	v_lshlrev_b32_e32 v112, 16, v45
	v_and_b32_e32 v45, 0xffff0000, v45
	v_mul_f32_e32 v45, v45, v45
	v_fmac_f32_e32 v45, v112, v112
	v_add_f32_e32 v44, v44, v45
	v_lshlrev_b32_e32 v112, 16, v46
	v_and_b32_e32 v46, 0xffff0000, v46
	v_mul_f32_e32 v46, v46, v46
	v_fmac_f32_e32 v46, v112, v112
	v_add_f32_e32 v44, v44, v46
	v_lshlrev_b32_e32 v112, 16, v47
	v_and_b32_e32 v47, 0xffff0000, v47
	v_mul_f32_e32 v47, v47, v47
	v_fmac_f32_e32 v47, v112, v112
	v_add_f32_e32 v44, v44, v47
	s_waitcnt vmcnt(7)
	v_lshlrev_b32_e32 v112, 16, v48
	v_and_b32_e32 v48, 0xffff0000, v48
	v_mul_f32_e32 v48, v48, v48
	v_fmac_f32_e32 v48, v112, v112
	v_lshlrev_b32_e32 v112, 16, v49
	v_and_b32_e32 v49, 0xffff0000, v49
	v_mul_f32_e32 v49, v49, v49
	v_fmac_f32_e32 v49, v112, v112
	v_add_f32_e32 v48, v48, v49
	v_lshlrev_b32_e32 v112, 16, v50
	v_and_b32_e32 v50, 0xffff0000, v50
	v_mul_f32_e32 v50, v50, v50
	v_fmac_f32_e32 v50, v112, v112
	v_add_f32_e32 v48, v48, v50
	v_lshlrev_b32_e32 v112, 16, v51
	v_and_b32_e32 v51, 0xffff0000, v51
	v_mul_f32_e32 v51, v51, v51
	v_fmac_f32_e32 v51, v112, v112
	v_add_f32_e32 v48, v48, v51
	s_waitcnt vmcnt(6)
	v_lshlrev_b32_e32 v112, 16, v52
	v_and_b32_e32 v52, 0xffff0000, v52
	v_mul_f32_e32 v52, v52, v52
	v_fmac_f32_e32 v52, v112, v112
	v_lshlrev_b32_e32 v112, 16, v53
	v_and_b32_e32 v53, 0xffff0000, v53
	v_mul_f32_e32 v53, v53, v53
	v_fmac_f32_e32 v53, v112, v112
	v_add_f32_e32 v52, v52, v53
	v_lshlrev_b32_e32 v112, 16, v54
	v_and_b32_e32 v54, 0xffff0000, v54
	v_mul_f32_e32 v54, v54, v54
	v_fmac_f32_e32 v54, v112, v112
	v_add_f32_e32 v52, v52, v54
	v_lshlrev_b32_e32 v112, 16, v55
	v_and_b32_e32 v55, 0xffff0000, v55
	v_mul_f32_e32 v55, v55, v55
	v_fmac_f32_e32 v55, v112, v112
	v_add_f32_e32 v52, v52, v55
	s_waitcnt vmcnt(5)
	v_lshlrev_b32_e32 v112, 16, v56
	v_and_b32_e32 v56, 0xffff0000, v56
	v_mul_f32_e32 v56, v56, v56
	v_fmac_f32_e32 v56, v112, v112
	v_lshlrev_b32_e32 v112, 16, v57
	v_and_b32_e32 v57, 0xffff0000, v57
	v_mul_f32_e32 v57, v57, v57
	v_fmac_f32_e32 v57, v112, v112
	v_add_f32_e32 v56, v56, v57
	v_lshlrev_b32_e32 v112, 16, v58
	v_and_b32_e32 v58, 0xffff0000, v58
	v_mul_f32_e32 v58, v58, v58
	v_fmac_f32_e32 v58, v112, v112
	v_add_f32_e32 v56, v56, v58
	v_lshlrev_b32_e32 v112, 16, v59
	v_and_b32_e32 v59, 0xffff0000, v59
	v_mul_f32_e32 v59, v59, v59
	v_fmac_f32_e32 v59, v112, v112
	v_add_f32_e32 v56, v56, v59
	s_waitcnt vmcnt(4)
	v_lshlrev_b32_e32 v112, 16, v60
	v_and_b32_e32 v60, 0xffff0000, v60
	v_mul_f32_e32 v60, v60, v60
	v_fmac_f32_e32 v60, v112, v112
	v_lshlrev_b32_e32 v112, 16, v61
	v_and_b32_e32 v61, 0xffff0000, v61
	v_mul_f32_e32 v61, v61, v61
	v_fmac_f32_e32 v61, v112, v112
	v_add_f32_e32 v60, v60, v61
	v_lshlrev_b32_e32 v112, 16, v62
	v_and_b32_e32 v62, 0xffff0000, v62
	v_mul_f32_e32 v62, v62, v62
	v_fmac_f32_e32 v62, v112, v112
	v_add_f32_e32 v60, v60, v62
	v_lshlrev_b32_e32 v112, 16, v63
	v_and_b32_e32 v63, 0xffff0000, v63
	v_mul_f32_e32 v63, v63, v63
	v_fmac_f32_e32 v63, v112, v112
	v_add_f32_e32 v60, v60, v63
	s_waitcnt vmcnt(3)
	v_lshlrev_b32_e32 v112, 16, v64
	v_and_b32_e32 v64, 0xffff0000, v64
	v_mul_f32_e32 v64, v64, v64
	v_fmac_f32_e32 v64, v112, v112
	v_lshlrev_b32_e32 v112, 16, v65
	v_and_b32_e32 v65, 0xffff0000, v65
	v_mul_f32_e32 v65, v65, v65
	v_fmac_f32_e32 v65, v112, v112
	v_add_f32_e32 v64, v64, v65
	v_lshlrev_b32_e32 v112, 16, v66
	v_and_b32_e32 v66, 0xffff0000, v66
	v_mul_f32_e32 v66, v66, v66
	v_fmac_f32_e32 v66, v112, v112
	v_add_f32_e32 v64, v64, v66
	v_lshlrev_b32_e32 v112, 16, v67
	v_and_b32_e32 v67, 0xffff0000, v67
	v_mul_f32_e32 v67, v67, v67
	v_fmac_f32_e32 v67, v112, v112
	v_add_f32_e32 v64, v64, v67
	s_waitcnt vmcnt(2)
	v_lshlrev_b32_e32 v112, 16, v68
	v_and_b32_e32 v68, 0xffff0000, v68
	v_mul_f32_e32 v68, v68, v68
	v_fmac_f32_e32 v68, v112, v112
	v_lshlrev_b32_e32 v112, 16, v69
	v_and_b32_e32 v69, 0xffff0000, v69
	v_mul_f32_e32 v69, v69, v69
	v_fmac_f32_e32 v69, v112, v112
	v_add_f32_e32 v68, v68, v69
	v_lshlrev_b32_e32 v112, 16, v70
	v_and_b32_e32 v70, 0xffff0000, v70
	v_mul_f32_e32 v70, v70, v70
	v_fmac_f32_e32 v70, v112, v112
	v_add_f32_e32 v68, v68, v70
	v_lshlrev_b32_e32 v112, 16, v71
	v_and_b32_e32 v71, 0xffff0000, v71
	v_mul_f32_e32 v71, v71, v71
	v_fmac_f32_e32 v71, v112, v112
	v_add_f32_e32 v68, v68, v71
	s_waitcnt vmcnt(1)
	v_lshlrev_b32_e32 v112, 16, v72
	v_and_b32_e32 v72, 0xffff0000, v72
	v_mul_f32_e32 v72, v72, v72
	v_fmac_f32_e32 v72, v112, v112
	v_lshlrev_b32_e32 v112, 16, v73
	v_and_b32_e32 v73, 0xffff0000, v73
	v_mul_f32_e32 v73, v73, v73
	v_fmac_f32_e32 v73, v112, v112
	v_add_f32_e32 v72, v72, v73
	v_lshlrev_b32_e32 v112, 16, v74
	v_and_b32_e32 v74, 0xffff0000, v74
	v_mul_f32_e32 v74, v74, v74
	v_fmac_f32_e32 v74, v112, v112
	v_add_f32_e32 v72, v72, v74
	v_lshlrev_b32_e32 v112, 16, v75
	v_and_b32_e32 v75, 0xffff0000, v75
	v_mul_f32_e32 v75, v75, v75
	v_fmac_f32_e32 v75, v112, v112
	v_add_f32_e32 v72, v72, v75
	s_waitcnt vmcnt(0)
	v_lshlrev_b32_e32 v112, 16, v76
	v_and_b32_e32 v76, 0xffff0000, v76
	v_mul_f32_e32 v76, v76, v76
	v_fmac_f32_e32 v76, v112, v112
	v_lshlrev_b32_e32 v112, 16, v77
	v_and_b32_e32 v77, 0xffff0000, v77
	v_mul_f32_e32 v77, v77, v77
	v_fmac_f32_e32 v77, v112, v112
	v_add_f32_e32 v76, v76, v77
	v_lshlrev_b32_e32 v112, 16, v78
	v_and_b32_e32 v78, 0xffff0000, v78
	v_mul_f32_e32 v78, v78, v78
	v_fmac_f32_e32 v78, v112, v112
	v_add_f32_e32 v76, v76, v78
	v_lshlrev_b32_e32 v112, 16, v79
	v_and_b32_e32 v79, 0xffff0000, v79
	v_mul_f32_e32 v79, v79, v79
	v_fmac_f32_e32 v79, v112, v112
	v_add_f32_e32 v76, v76, v79
	s_nop 1
	v_permlane32_swap_b32_e32 v16, v48
	v_permlane32_swap_b32_e32 v20, v52
	v_permlane32_swap_b32_e32 v24, v56
	v_permlane32_swap_b32_e32 v28, v60
	v_permlane32_swap_b32_e32 v32, v64
	v_permlane32_swap_b32_e32 v36, v68
	v_permlane32_swap_b32_e32 v40, v72
	v_permlane32_swap_b32_e32 v44, v76
	s_nop 0
	v_add_f32_e32 v16, v16, v48
	v_add_f32_e32 v20, v20, v52
	v_add_f32_e32 v24, v24, v56
	v_add_f32_e32 v28, v28, v60
	v_add_f32_e32 v32, v32, v64
	v_add_f32_e32 v36, v36, v68
	v_add_f32_e32 v40, v40, v72
	v_add_f32_e32 v44, v44, v76
	s_nop 1
	v_permlane16_swap_b32_e32 v16, v32
	v_permlane16_swap_b32_e32 v20, v36
	v_permlane16_swap_b32_e32 v24, v40
	v_permlane16_swap_b32_e32 v28, v44
	s_nop 0
	v_add_f32_e32 v16, v16, v32
	v_add_f32_e32 v20, v20, v36
	v_add_f32_e32 v24, v24, v40
	v_add_f32_e32 v28, v28, v44
	s_nop 1
	v_add_f32_dpp v16, v16, v16 row_ror:8 row_mask:0xf bank_mask:0xf
	v_add_f32_dpp v20, v20, v20 row_ror:8 row_mask:0xf bank_mask:0xf
	v_add_f32_dpp v24, v24, v24 row_ror:8 row_mask:0xf bank_mask:0xf
	v_add_f32_dpp v28, v28, v28 row_ror:8 row_mask:0xf bank_mask:0xf
	s_nop 1
	v_add_f32_dpp v16, v16, v16 row_ror:4 row_mask:0xf bank_mask:0xf
	v_add_f32_dpp v20, v20, v20 row_ror:4 row_mask:0xf bank_mask:0xf
	v_add_f32_dpp v24, v24, v24 row_ror:4 row_mask:0xf bank_mask:0xf
	v_add_f32_dpp v28, v28, v28 row_ror:4 row_mask:0xf bank_mask:0xf
	s_nop 1
	v_add_f32_dpp v16, v16, v16 row_ror:2 row_mask:0xf bank_mask:0xf
	v_add_f32_dpp v20, v20, v20 row_ror:2 row_mask:0xf bank_mask:0xf
	v_add_f32_dpp v24, v24, v24 row_ror:2 row_mask:0xf bank_mask:0xf
	v_add_f32_dpp v28, v28, v28 row_ror:2 row_mask:0xf bank_mask:0xf
	s_nop 1
	v_add_f32_dpp v16, v16, v16 row_ror:1 row_mask:0xf bank_mask:0xf
	v_add_f32_dpp v20, v20, v20 row_ror:1 row_mask:0xf bank_mask:0xf
	v_add_f32_dpp v24, v24, v24 row_ror:1 row_mask:0xf bank_mask:0xf
	v_add_f32_dpp v28, v28, v28 row_ror:1 row_mask:0xf bank_mask:0xf
	v_fmamk_f32 v16, v16, 0x3b000000, v166
	v_fmamk_f32 v20, v20, 0x3b000000, v166
	v_fmamk_f32 v24, v24, 0x3b000000, v166
	v_fmamk_f32 v28, v28, 0x3b000000, v166
	v_mul_f32_e32 v112, 0x4b800000, v16
	v_cmp_gt_f32_e32 vcc, s58, v16
	s_nop 1
	v_cndmask_b32_e32 v16, v16, v112, vcc
	v_rsq_f32_e32 v16, v16
	s_nop 0
	v_mul_f32_e32 v112, 0x45800000, v16
	v_cndmask_b32_e32 v16, v16, v112, vcc
	v_mul_f32_e32 v16, 0x3dd53b94, v16
	v_mul_f32_e32 v112, 0x4b800000, v20
	v_cmp_gt_f32_e32 vcc, s58, v20
	s_nop 1
	v_cndmask_b32_e32 v20, v20, v112, vcc
	v_rsq_f32_e32 v20, v20
	s_nop 0
	v_mul_f32_e32 v112, 0x45800000, v20
	v_cndmask_b32_e32 v20, v20, v112, vcc
	v_mul_f32_e32 v20, 0x3dd53b94, v20
	v_mul_f32_e32 v112, 0x4b800000, v24
	v_cmp_gt_f32_e32 vcc, s58, v24
	s_nop 1
	v_cndmask_b32_e32 v24, v24, v112, vcc
	v_rsq_f32_e32 v24, v24
	s_nop 0
	v_mul_f32_e32 v112, 0x45800000, v24
	v_cndmask_b32_e32 v24, v24, v112, vcc
	v_mul_f32_e32 v24, 0x3dd53b94, v24
	v_mul_f32_e32 v112, 0x4b800000, v28
	v_cmp_gt_f32_e32 vcc, s58, v28
	s_nop 1
	v_cndmask_b32_e32 v28, v28, v112, vcc
	v_rsq_f32_e32 v28, v28
	s_nop 0
	v_mul_f32_e32 v112, 0x45800000, v28
	v_cndmask_b32_e32 v28, v28, v112, vcc
	v_mul_f32_e32 v28, 0x3dd53b94, v28
	v_mov_b32_e32 v112, v16
	v_mov_b32_e32 v113, v20
	v_mov_b32_e32 v114, v24
	v_mov_b32_e32 v115, v28
	v_cmp_eq_u32_e32 vcc, 0, v118
	s_and_saveexec_b64 s[0:1], vcc
	ds_write_b128 v117, v[112:115] offset:64
	s_or_b64 exec, exec, s[0:1]
.LBB0_839:
	s_mul_i32 s0, s9, 6
	v_mov_b32_e32 v22, v167
	s_sub_i32 s1, s16, s0
	s_waitcnt lgkmcnt(0)
	s_barrier
	s_mul_i32 s16, s9, 0xb8000
	s_and_b32 s0, s1, 0xffff
	v_lshlrev_b32_e32 v1, 4, v22
	v_and_b32_e32 v0, 32, v22
	s_lshl_b64 s[2:3], s[16:17], 1
	v_bitop3_b32 v0, v1, v0, 48 bitop3:0x6c
	s_add_u32 s24, s22, s2
	v_lshrrev_b32_e32 v2, 1, v22
	v_lshrrev_b32_e32 v0, 1, v0
	s_addc_u32 s25, s23, s3
	s_lshl_b32 s1, s1, 18
	v_and_b32_e32 v16, 0xfffffc00, v1
	v_lshrrev_b32_e32 v3, 2, v22
	v_and_or_b32 v5, v2, 32, v0
	v_ashrrev_i32_e32 v0, 3, v22
	v_add_u32_e32 v4, 0x2000, v1
	v_add_u32_e32 v7, 0x4000, v1
	v_add_u32_e32 v1, 0x6000, v1
	s_add_u32 s26, s12, s1
	v_bfi_b32 v2, 15, v3, v0
	s_movk_i32 s1, 0xb80
	v_ashrrev_i32_e32 v4, 7, v4
	v_ashrrev_i32_e32 v7, 7, v7
	v_ashrrev_i32_e32 v1, 7, v1
	v_mul_lo_u32 v0, v2, s1
	v_bfi_b32 v6, -16, v4, v3
	v_bfi_b32 v7, -16, v7, v3
	v_bfi_b32 v1, -16, v1, v3
	v_or_b32_e32 v0, v0, v5
	v_mul_lo_u32 v4, v6, s1
	v_mul_lo_u32 v8, v7, s1
	v_mul_lo_u32 v3, v1, s1
	v_add_u32_e32 v17, 0, v16
	v_lshl_or_b32 v2, v2, 9, v5
	v_or_b32_e32 v4, v4, v5
	v_lshl_or_b32 v6, v6, 9, v5
	v_or_b32_e32 v8, v8, v5
	v_lshl_or_b32 v10, v7, 9, v5
	v_or_b32_e32 v12, v3, v5
	v_lshl_or_b32 v14, v1, 9, v5
	v_add_u32_e32 v5, 0x8000, v17
	v_ashrrev_i32_e32 v1, 31, v0
	v_readfirstlane_b32 s2, v17
	s_addc_u32 s27, s13, 0
	v_lshl_add_u64 v[0:1], v[0:1], 1, s[24:25]
	s_mov_b32 m0, s2
	v_ashrrev_i32_e32 v3, 31, v2
	v_readfirstlane_b32 s1, v5
	v_add_u32_e32 v32, 0x2000, v17
	v_lshl_add_u64 v[2:3], v[2:3], 1, s[26:27]
	s_mov_b32 m0, s1
	v_ashrrev_i32_e32 v5, 31, v4
	v_readfirstlane_b32 s3, v32
	v_add_u32_e32 v33, 0xa000, v17
	v_lshl_add_u64 v[4:5], v[4:5], 1, s[24:25]
	s_mov_b32 m0, s3
	v_ashrrev_i32_e32 v7, 31, v6
	v_readfirstlane_b32 s9, v33
	v_add_u32_e32 v34, 0x4000, v17
	v_lshl_add_u64 v[6:7], v[6:7], 1, s[26:27]
	s_mov_b32 m0, s9
	v_ashrrev_i32_e32 v9, 31, v8
	v_readfirstlane_b32 s10, v34
	v_add_u32_e32 v35, 0xc000, v17
	v_lshl_add_u64 v[8:9], v[8:9], 1, s[24:25]
	s_mov_b32 m0, s10
	v_ashrrev_i32_e32 v11, 31, v10
	v_readfirstlane_b32 s11, v35
	v_add_u32_e32 v36, 0x6000, v17
	v_add_u32_e32 v37, 0xe000, v17
	v_and_b32_e32 v17, 15, v22
	v_lshlrev_b32_e32 v19, 2, v22
	v_lshl_add_u64 v[10:11], v[10:11], 1, s[26:27]
	s_mov_b32 m0, s11
	v_ashrrev_i32_e32 v13, 31, v12
	v_readfirstlane_b32 s16, v36
	v_and_b32_e32 v18, 48, v22
	v_lshlrev_b32_e32 v17, 6, v17
	v_and_b32_e32 v19, 32, v19
	v_lshl_add_u64 v[12:13], v[12:13], 1, s[24:25]
	s_mov_b32 m0, s16
	v_ashrrev_i32_e32 v15, 31, v14
	v_readfirstlane_b32 s24, v37
	v_bitop3_b32 v25, v17, v19, v18 bitop3:0x36
	v_lshlrev_b32_e32 v17, 6, v22
	v_add_u32_e32 v39, s90, v16
	v_readlane_b32 s41, v254, 11
	v_lshl_add_u64 v[14:15], v[14:15], 1, s[26:27]
	s_mov_b32 m0, s24
	v_and_b32_e32 v30, 0xffffc000, v17
	v_and_b32_e32 v17, 0x3c0, v17
	v_add_u32_e32 v38, s41, v16
	v_readfirstlane_b32 s34, v39
	v_bitop3_b32 v127, v17, v19, v18 bitop3:0x36
	v_lshl_add_u64 v[16:17], v[0:1], 0, s[96:97]
	s_mov_b32 m0, s34
	v_readfirstlane_b32 s25, v38
	v_add_u32_e32 v40, 0x2000, v39
	s_waitcnt vmcnt(0)
	s_waitcnt vmcnt(0) lgkmcnt(0)
	s_barrier
	global_load_lds_dwordx4 v[16:17], off
	v_lshl_add_u64 v[16:17], v[2:3], 0, s[96:97]
	s_mov_b32 m0, s25
	v_readfirstlane_b32 s26, v40
	v_add_u32_e32 v41, 0x2000, v38
	global_load_lds_dwordx4 v[16:17], off
	v_lshl_add_u64 v[16:17], v[4:5], 0, s[96:97]
	s_mov_b32 m0, s26
	v_readfirstlane_b32 s27, v41
	v_add_u32_e32 v42, 0x4000, v39
	global_load_lds_dwordx4 v[16:17], off
	v_lshl_add_u64 v[16:17], v[6:7], 0, s[96:97]
	s_mov_b32 m0, s27
	v_readfirstlane_b32 s35, v42
	v_add_u32_e32 v43, 0x4000, v38
	global_load_lds_dwordx4 v[16:17], off
	v_lshl_add_u64 v[16:17], v[8:9], 0, s[96:97]
	s_mov_b32 m0, s35
	v_readfirstlane_b32 s36, v43
	v_add_u32_e32 v44, 0x6000, v39
	global_load_lds_dwordx4 v[16:17], off
	v_lshl_add_u64 v[16:17], v[10:11], 0, s[96:97]
	s_mov_b32 m0, s36
	v_readfirstlane_b32 s37, v44
	v_add_u32_e32 v45, 0x6000, v38
	global_load_lds_dwordx4 v[16:17], off
	v_lshl_add_u64 v[16:17], v[12:13], 0, s[96:97]
	s_mov_b32 m0, s37
	v_readfirstlane_b32 s40, v45
	global_load_lds_dwordx4 v[16:17], off
	v_lshl_add_u64 v[16:17], v[14:15], 0, s[96:97]
	s_mov_b32 m0, s40
	v_or_b32_e32 v126, 0x800, v30
	global_load_lds_dwordx4 v[16:17], off
	v_add_u32_e32 v16, 0, v25
	v_add_u32_e32 v24, v16, v30
	ds_read_b128 v[18:21], v24
	v_lshlrev_b32_e32 v17, 7, v22
	v_and_b32_e32 v162, 0x6000, v17
	v_add_u32_e32 v17, 0, v127
	v_add_u32_e32 v23, v16, v162
	v_add_u32_e32 v16, v17, v126
	ds_read_b128 v[26:29], v23 offset:32768
	ds_read_b128 v[46:49], v16
	ds_read_b128 v[50:53], v23 offset:34816
	ds_read_b128 v[62:65], v23 offset:36864
	ds_read_b128 v[66:69], v23 offset:38912
	v_or_b32_e32 v163, 0x1000, v30
	v_or_b32_e32 v164, 0x1800, v30
	v_or_b32_e32 v180, 0x2000, v30
	v_or_b32_e32 v182, 0x2800, v30
	v_or_b32_e32 v183, 0x3000, v30
	v_or_b32_e32 v193, 0x3800, v30
	s_waitcnt lgkmcnt(0)
	v_mfma_f32_16x16x32_bf16 v[54:57], v[26:29], v[18:21], 0
	v_add_u32_e32 v22, v17, v163
	ds_read_b128 v[90:93], v22
	v_mfma_f32_16x16x32_bf16 v[58:61], v[50:53], v[18:21], 0
	v_mfma_f32_16x16x32_bf16 v[70:73], v[62:65], v[18:21], 0
	v_mfma_f32_16x16x32_bf16 v[74:77], v[66:69], v[18:21], 0
	v_add_u32_e32 v19, v17, v164
	v_add_u32_e32 v21, v17, v180
	v_add_u32_e32 v18, v17, v182
	v_add_u32_e32 v20, v17, v183
	v_add_u32_e32 v17, v17, v193
	ds_read_b128 v[94:97], v19
	ds_read_b128 v[158:161], v20
	ds_read_b128 v[122:125], v21
	ds_read_b128 v[130:133], v18
	ds_read_b128 v[168:171], v17
	v_mfma_f32_16x16x32_bf16 v[78:81], v[26:29], v[46:49], 0
	v_mfma_f32_16x16x32_bf16 v[82:85], v[50:53], v[46:49], 0
	v_mfma_f32_16x16x32_bf16 v[86:89], v[62:65], v[46:49], 0
	v_mfma_f32_16x16x32_bf16 v[46:49], v[66:69], v[46:49], 0
	s_waitcnt lgkmcnt(0)
	v_mfma_f32_16x16x32_bf16 v[98:101], v[26:29], v[90:93], 0
	v_mfma_f32_16x16x32_bf16 v[102:105], v[50:53], v[90:93], 0
	v_mfma_f32_16x16x32_bf16 v[106:109], v[62:65], v[90:93], 0
	v_mfma_f32_16x16x32_bf16 v[90:93], v[66:69], v[90:93], 0
	v_mfma_f32_16x16x32_bf16 v[110:113], v[26:29], v[94:97], 0
	v_mfma_f32_16x16x32_bf16 v[114:117], v[50:53], v[94:97], 0
	v_mfma_f32_16x16x32_bf16 v[118:121], v[62:65], v[94:97], 0
	v_mfma_f32_16x16x32_bf16 v[94:97], v[66:69], v[94:97], 0
	v_mfma_f32_16x16x32_bf16 v[134:137], v[26:29], v[122:125], 0
	v_mfma_f32_16x16x32_bf16 v[138:141], v[50:53], v[122:125], 0
	v_mfma_f32_16x16x32_bf16 v[142:145], v[62:65], v[122:125], 0
	v_mfma_f32_16x16x32_bf16 v[122:125], v[66:69], v[122:125], 0
	v_mfma_f32_16x16x32_bf16 v[146:149], v[26:29], v[130:133], 0
	v_mfma_f32_16x16x32_bf16 v[150:153], v[50:53], v[130:133], 0
	v_mfma_f32_16x16x32_bf16 v[154:157], v[62:65], v[130:133], 0
	v_mfma_f32_16x16x32_bf16 v[130:133], v[66:69], v[130:133], 0
	v_mfma_f32_16x16x32_bf16 v[172:175], v[26:29], v[158:161], 0
	v_mfma_f32_16x16x32_bf16 v[176:179], v[50:53], v[158:161], 0
	v_mfma_f32_16x16x32_bf16 v[194:197], v[62:65], v[158:161], 0
	v_mfma_f32_16x16x32_bf16 v[158:161], v[66:69], v[158:161], 0
	v_mfma_f32_16x16x32_bf16 v[26:29], v[26:29], v[168:171], 0
	v_mfma_f32_16x16x32_bf16 v[50:53], v[50:53], v[168:171], 0
	v_mfma_f32_16x16x32_bf16 v[62:65], v[62:65], v[168:171], 0
	v_mfma_f32_16x16x32_bf16 v[66:69], v[66:69], v[168:171], 0
	ds_read_b128 v[168:171], v24 offset:1024
	ds_read_b128 v[198:201], v23 offset:33792
	ds_read_b128 v[202:205], v23 offset:35840
	ds_read_b128 v[206:209], v23 offset:37888
	ds_read_b128 v[210:213], v23 offset:39936
	s_waitcnt lgkmcnt(0)
	v_mfma_f32_16x16x32_bf16 v[54:57], v[198:201], v[168:171], v[54:57]
	v_mfma_f32_16x16x32_bf16 v[58:61], v[202:205], v[168:171], v[58:61]
	v_mfma_f32_16x16x32_bf16 v[70:73], v[206:209], v[168:171], v[70:73]
	v_mfma_f32_16x16x32_bf16 v[74:77], v[210:213], v[168:171], v[74:77]
	ds_read_b128 v[168:171], v16 offset:1024
	s_waitcnt lgkmcnt(0)
	v_mfma_f32_16x16x32_bf16 v[78:81], v[198:201], v[168:171], v[78:81]
	v_mfma_f32_16x16x32_bf16 v[82:85], v[202:205], v[168:171], v[82:85]
	v_mfma_f32_16x16x32_bf16 v[86:89], v[206:209], v[168:171], v[86:89]
	v_mfma_f32_16x16x32_bf16 v[46:49], v[210:213], v[168:171], v[46:49]
	ds_read_b128 v[168:171], v22 offset:1024
	s_waitcnt lgkmcnt(0)
	v_mfma_f32_16x16x32_bf16 v[98:101], v[198:201], v[168:171], v[98:101]
	v_mfma_f32_16x16x32_bf16 v[102:105], v[202:205], v[168:171], v[102:105]
	v_mfma_f32_16x16x32_bf16 v[106:109], v[206:209], v[168:171], v[106:109]
	v_mfma_f32_16x16x32_bf16 v[90:93], v[210:213], v[168:171], v[90:93]
	ds_read_b128 v[168:171], v19 offset:1024
	s_waitcnt lgkmcnt(0)
	v_mfma_f32_16x16x32_bf16 v[110:113], v[198:201], v[168:171], v[110:113]
	v_mfma_f32_16x16x32_bf16 v[114:117], v[202:205], v[168:171], v[114:117]
	v_mfma_f32_16x16x32_bf16 v[118:121], v[206:209], v[168:171], v[118:121]
	v_mfma_f32_16x16x32_bf16 v[94:97], v[210:213], v[168:171], v[94:97]
	ds_read_b128 v[168:171], v21 offset:1024
	s_waitcnt lgkmcnt(0)
	v_mfma_f32_16x16x32_bf16 v[134:137], v[198:201], v[168:171], v[134:137]
	v_mfma_f32_16x16x32_bf16 v[138:141], v[202:205], v[168:171], v[138:141]
	v_mfma_f32_16x16x32_bf16 v[142:145], v[206:209], v[168:171], v[142:145]
	v_mfma_f32_16x16x32_bf16 v[122:125], v[210:213], v[168:171], v[122:125]
	ds_read_b128 v[168:171], v18 offset:1024
	s_waitcnt lgkmcnt(0)
	v_mfma_f32_16x16x32_bf16 v[146:149], v[198:201], v[168:171], v[146:149]
	v_mfma_f32_16x16x32_bf16 v[150:153], v[202:205], v[168:171], v[150:153]
	v_mfma_f32_16x16x32_bf16 v[154:157], v[206:209], v[168:171], v[154:157]
	v_mfma_f32_16x16x32_bf16 v[168:171], v[210:213], v[168:171], v[130:133]
	s_nop 2
	ds_read_b128 v[130:133], v20 offset:1024
	s_waitcnt lgkmcnt(0)
	v_mfma_f32_16x16x32_bf16 v[172:175], v[198:201], v[130:133], v[172:175]
	v_mfma_f32_16x16x32_bf16 v[176:179], v[202:205], v[130:133], v[176:179]
	v_mfma_f32_16x16x32_bf16 v[194:197], v[206:209], v[130:133], v[194:197]
	v_mfma_f32_16x16x32_bf16 v[158:161], v[210:213], v[130:133], v[158:161]
	ds_read_b128 v[130:133], v17 offset:1024
	s_waitcnt lgkmcnt(0)
	v_mfma_f32_16x16x32_bf16 v[50:53], v[202:205], v[130:133], v[50:53]
	v_mfma_f32_16x16x32_bf16 v[62:65], v[206:209], v[130:133], v[62:65]
	v_mfma_f32_16x16x32_bf16 v[66:69], v[210:213], v[130:133], v[66:69]
	v_mfma_f32_16x16x32_bf16 v[198:201], v[198:201], v[130:133], v[26:29]
	s_mov_b32 m0, s2
	s_nop 1
	v_lshl_add_u64 v[26:27], v[0:1], 0, s[62:63]
	s_waitcnt vmcnt(0)
	s_waitcnt vmcnt(0)
	s_barrier
	global_load_lds_dwordx4 v[26:27], off
	v_lshl_add_u64 v[26:27], v[2:3], 0, s[62:63]
	s_mov_b32 m0, s1
	v_add_u32_e32 v127, s90, v127
	global_load_lds_dwordx4 v[26:27], off
	v_lshl_add_u64 v[26:27], v[4:5], 0, s[62:63]
	s_mov_b32 m0, s3
	s_nop 0
	global_load_lds_dwordx4 v[26:27], off
	v_lshl_add_u64 v[26:27], v[6:7], 0, s[62:63]
	s_mov_b32 m0, s9
	s_nop 0
	global_load_lds_dwordx4 v[26:27], off
	v_lshl_add_u64 v[26:27], v[8:9], 0, s[62:63]
	s_mov_b32 m0, s10
	s_nop 0
	global_load_lds_dwordx4 v[26:27], off
	v_lshl_add_u64 v[26:27], v[10:11], 0, s[62:63]
	s_mov_b32 m0, s11
	s_nop 0
	global_load_lds_dwordx4 v[26:27], off
	v_lshl_add_u64 v[26:27], v[12:13], 0, s[62:63]
	s_mov_b32 m0, s16
	s_nop 0
	global_load_lds_dwordx4 v[26:27], off
	v_lshl_add_u64 v[26:27], v[14:15], 0, s[62:63]
	s_mov_b32 m0, s24
	s_nop 0
	global_load_lds_dwordx4 v[26:27], off
	v_add3_u32 v26, s90, v25, v30
	ds_read_b128 v[28:31], v26
	v_add_u32_e32 v27, v127, v126
	ds_read_b128 v[130:133], v27
	v_add3_u32 v25, s41, v25, v162
	ds_read_b128 v[202:205], v25
	ds_read_b128 v[206:209], v25 offset:2048
	ds_read_b128 v[210:213], v25 offset:4096
	ds_read_b128 v[214:217], v25 offset:6144
	s_waitcnt lgkmcnt(0)
	v_mfma_f32_16x16x32_bf16 v[54:57], v[202:205], v[28:31], v[54:57]
	v_mfma_f32_16x16x32_bf16 v[58:61], v[206:209], v[28:31], v[58:61]
	v_mfma_f32_16x16x32_bf16 v[70:73], v[210:213], v[28:31], v[70:73]
	v_mfma_f32_16x16x32_bf16 v[74:77], v[214:217], v[28:31], v[74:77]
	v_add_u32_e32 v28, v127, v163
	v_add_u32_e32 v29, v127, v164
	v_add_u32_e32 v31, v127, v182
	v_mfma_f32_16x16x32_bf16 v[78:81], v[202:205], v[130:133], v[78:81]
	ds_read_b128 v[218:221], v31
	v_add_u32_e32 v30, v127, v180
	v_mfma_f32_16x16x32_bf16 v[82:85], v[206:209], v[130:133], v[82:85]
	v_mfma_f32_16x16x32_bf16 v[86:89], v[210:213], v[130:133], v[86:89]
	v_mfma_f32_16x16x32_bf16 v[46:49], v[214:217], v[130:133], v[46:49]
	ds_read_b128 v[130:133], v28
	s_waitcnt lgkmcnt(0)
	v_mfma_f32_16x16x32_bf16 v[98:101], v[202:205], v[130:133], v[98:101]
	v_mfma_f32_16x16x32_bf16 v[102:105], v[206:209], v[130:133], v[102:105]
	v_mfma_f32_16x16x32_bf16 v[106:109], v[210:213], v[130:133], v[106:109]
	v_mfma_f32_16x16x32_bf16 v[90:93], v[214:217], v[130:133], v[90:93]
	ds_read_b128 v[130:133], v29
	s_waitcnt lgkmcnt(0)
	v_mfma_f32_16x16x32_bf16 v[110:113], v[202:205], v[130:133], v[110:113]
	v_mfma_f32_16x16x32_bf16 v[114:117], v[206:209], v[130:133], v[114:117]
	v_mfma_f32_16x16x32_bf16 v[118:121], v[210:213], v[130:133], v[118:121]
	v_mfma_f32_16x16x32_bf16 v[94:97], v[214:217], v[130:133], v[94:97]
	ds_read_b128 v[130:133], v30
	s_waitcnt lgkmcnt(0)
	v_mfma_f32_16x16x32_bf16 v[134:137], v[202:205], v[130:133], v[134:137]
	v_mfma_f32_16x16x32_bf16 v[138:141], v[206:209], v[130:133], v[138:141]
	v_mfma_f32_16x16x32_bf16 v[142:145], v[210:213], v[130:133], v[142:145]
	v_mfma_f32_16x16x32_bf16 v[122:125], v[214:217], v[130:133], v[122:125]
	v_add_u32_e32 v130, v127, v183
	v_add_u32_e32 v131, v127, v193
	v_mfma_f32_16x16x32_bf16 v[146:149], v[202:205], v[218:221], v[146:149]
	v_mfma_f32_16x16x32_bf16 v[150:153], v[206:209], v[218:221], v[150:153]
	v_mfma_f32_16x16x32_bf16 v[154:157], v[210:213], v[218:221], v[154:157]
	v_mfma_f32_16x16x32_bf16 v[168:171], v[214:217], v[218:221], v[168:171]
	ds_read_b128 v[218:221], v130
	s_waitcnt lgkmcnt(0)
	v_mfma_f32_16x16x32_bf16 v[172:175], v[202:205], v[218:221], v[172:175]
	v_mfma_f32_16x16x32_bf16 v[176:179], v[206:209], v[218:221], v[176:179]
	v_mfma_f32_16x16x32_bf16 v[194:197], v[210:213], v[218:221], v[194:197]
	v_mfma_f32_16x16x32_bf16 v[158:161], v[214:217], v[218:221], v[158:161]
	ds_read_b128 v[218:221], v131
	s_waitcnt lgkmcnt(0)
	v_mfma_f32_16x16x32_bf16 v[50:53], v[206:209], v[218:221], v[50:53]
	v_mfma_f32_16x16x32_bf16 v[62:65], v[210:213], v[218:221], v[62:65]
	v_mfma_f32_16x16x32_bf16 v[66:69], v[214:217], v[218:221], v[66:69]
	v_mfma_f32_16x16x32_bf16 v[198:201], v[202:205], v[218:221], v[198:201]
	ds_read_b128 v[202:205], v26 offset:1024
	ds_read_b128 v[206:209], v25 offset:1024
	ds_read_b128 v[210:213], v25 offset:3072
	ds_read_b128 v[214:217], v25 offset:5120
	ds_read_b128 v[218:221], v25 offset:7168
	s_waitcnt lgkmcnt(0)
	v_mfma_f32_16x16x32_bf16 v[54:57], v[206:209], v[202:205], v[54:57]
	v_mfma_f32_16x16x32_bf16 v[58:61], v[210:213], v[202:205], v[58:61]
	v_mfma_f32_16x16x32_bf16 v[70:73], v[214:217], v[202:205], v[70:73]
	v_mfma_f32_16x16x32_bf16 v[74:77], v[218:221], v[202:205], v[74:77]
	ds_read_b128 v[202:205], v27 offset:1024
	s_waitcnt lgkmcnt(0)
	v_mfma_f32_16x16x32_bf16 v[78:81], v[206:209], v[202:205], v[78:81]
	v_mfma_f32_16x16x32_bf16 v[82:85], v[210:213], v[202:205], v[82:85]
	v_mfma_f32_16x16x32_bf16 v[86:89], v[214:217], v[202:205], v[86:89]
	v_mfma_f32_16x16x32_bf16 v[46:49], v[218:221], v[202:205], v[46:49]
	ds_read_b128 v[202:205], v28 offset:1024
	s_waitcnt lgkmcnt(0)
	v_mfma_f32_16x16x32_bf16 v[98:101], v[206:209], v[202:205], v[98:101]
	v_mfma_f32_16x16x32_bf16 v[102:105], v[210:213], v[202:205], v[102:105]
	v_mfma_f32_16x16x32_bf16 v[106:109], v[214:217], v[202:205], v[106:109]
	v_mfma_f32_16x16x32_bf16 v[90:93], v[218:221], v[202:205], v[90:93]
	ds_read_b128 v[202:205], v29 offset:1024
	s_waitcnt lgkmcnt(0)
	v_mfma_f32_16x16x32_bf16 v[110:113], v[206:209], v[202:205], v[110:113]
	v_mfma_f32_16x16x32_bf16 v[114:117], v[210:213], v[202:205], v[114:117]
	v_mfma_f32_16x16x32_bf16 v[118:121], v[214:217], v[202:205], v[118:121]
	v_mfma_f32_16x16x32_bf16 v[94:97], v[218:221], v[202:205], v[94:97]
	ds_read_b128 v[202:205], v30 offset:1024
	s_waitcnt lgkmcnt(0)
	v_mfma_f32_16x16x32_bf16 v[132:135], v[206:209], v[202:205], v[134:137]
	v_mfma_f32_16x16x32_bf16 v[136:139], v[210:213], v[202:205], v[138:141]
	v_mfma_f32_16x16x32_bf16 v[140:143], v[214:217], v[202:205], v[142:145]
	v_mfma_f32_16x16x32_bf16 v[122:125], v[218:221], v[202:205], v[122:125]
	ds_read_b128 v[202:205], v31 offset:1024
	s_waitcnt lgkmcnt(0)
	v_mfma_f32_16x16x32_bf16 v[144:147], v[206:209], v[202:205], v[146:149]
	v_mfma_f32_16x16x32_bf16 v[148:151], v[210:213], v[202:205], v[150:153]
	v_mfma_f32_16x16x32_bf16 v[152:155], v[214:217], v[202:205], v[154:157]
	v_mfma_f32_16x16x32_bf16 v[168:171], v[218:221], v[202:205], v[168:171]
	ds_read_b128 v[202:205], v130 offset:1024
	s_waitcnt lgkmcnt(0)
	v_mfma_f32_16x16x32_bf16 v[156:159], v[218:221], v[202:205], v[158:161]
	s_nop 2
	ds_read_b128 v[160:163], v131 offset:1024
	s_waitcnt lgkmcnt(0)
	v_mfma_f32_16x16x32_bf16 v[50:53], v[210:213], v[160:163], v[50:53]
	v_mfma_f32_16x16x32_bf16 v[62:65], v[214:217], v[160:163], v[62:65]
	v_mfma_f32_16x16x32_bf16 v[66:69], v[218:221], v[160:163], v[66:69]
	v_mfma_f32_16x16x32_bf16 v[172:175], v[206:209], v[202:205], v[172:175]
	v_mfma_f32_16x16x32_bf16 v[176:179], v[210:213], v[202:205], v[176:179]
	v_mfma_f32_16x16x32_bf16 v[194:197], v[214:217], v[202:205], v[194:197]
	v_mfma_f32_16x16x32_bf16 v[198:201], v[206:209], v[160:163], v[198:201]
	s_mov_b32 m0, s34
	v_lshl_add_u64 v[126:127], v[0:1], 0, s[6:7]
	s_waitcnt vmcnt(0)
	s_waitcnt vmcnt(0)
	s_barrier
	global_load_lds_dwordx4 v[126:127], off
	v_lshl_add_u64 v[126:127], v[2:3], 0, s[6:7]
	s_mov_b32 m0, s25
	s_nop 0
	global_load_lds_dwordx4 v[126:127], off
	v_lshl_add_u64 v[126:127], v[4:5], 0, s[6:7]
	s_mov_b32 m0, s26
	s_nop 0
	global_load_lds_dwordx4 v[126:127], off
	v_lshl_add_u64 v[126:127], v[6:7], 0, s[6:7]
	s_mov_b32 m0, s27
	s_nop 0
	global_load_lds_dwordx4 v[126:127], off
	v_lshl_add_u64 v[126:127], v[8:9], 0, s[6:7]
	s_mov_b32 m0, s35
	s_nop 0
	global_load_lds_dwordx4 v[126:127], off
	v_lshl_add_u64 v[126:127], v[10:11], 0, s[6:7]
	s_mov_b32 m0, s36
	s_nop 0
	global_load_lds_dwordx4 v[126:127], off
	v_lshl_add_u64 v[126:127], v[12:13], 0, s[6:7]
	s_mov_b32 m0, s37
	s_nop 0
	global_load_lds_dwordx4 v[126:127], off
	v_lshl_add_u64 v[126:127], v[14:15], 0, s[6:7]
	s_mov_b32 m0, s40
	s_nop 0
	global_load_lds_dwordx4 v[126:127], off
	ds_read_b128 v[160:163], v24
	ds_read_b128 v[202:205], v23 offset:32768
	ds_read_b128 v[206:209], v23 offset:34816
	ds_read_b128 v[210:213], v23 offset:36864
	ds_read_b128 v[214:217], v23 offset:38912
	s_waitcnt lgkmcnt(0)
	v_mfma_f32_16x16x32_bf16 v[54:57], v[202:205], v[160:163], v[54:57]
	v_mfma_f32_16x16x32_bf16 v[58:61], v[206:209], v[160:163], v[58:61]
	v_mfma_f32_16x16x32_bf16 v[70:73], v[210:213], v[160:163], v[70:73]
	v_mfma_f32_16x16x32_bf16 v[74:77], v[214:217], v[160:163], v[74:77]
	ds_read_b128 v[160:163], v16
	s_waitcnt lgkmcnt(0)
	v_mfma_f32_16x16x32_bf16 v[78:81], v[202:205], v[160:163], v[78:81]
	v_mfma_f32_16x16x32_bf16 v[82:85], v[206:209], v[160:163], v[82:85]
	v_mfma_f32_16x16x32_bf16 v[86:89], v[210:213], v[160:163], v[86:89]
	v_mfma_f32_16x16x32_bf16 v[46:49], v[214:217], v[160:163], v[46:49]
	ds_read_b128 v[160:163], v22
	s_waitcnt lgkmcnt(0)
	v_mfma_f32_16x16x32_bf16 v[98:101], v[202:205], v[160:163], v[98:101]
	v_mfma_f32_16x16x32_bf16 v[102:105], v[206:209], v[160:163], v[102:105]
	v_mfma_f32_16x16x32_bf16 v[106:109], v[210:213], v[160:163], v[106:109]
	v_mfma_f32_16x16x32_bf16 v[90:93], v[214:217], v[160:163], v[90:93]
	ds_read_b128 v[160:163], v19
	s_waitcnt lgkmcnt(0)
	v_mfma_f32_16x16x32_bf16 v[110:113], v[202:205], v[160:163], v[110:113]
	v_mfma_f32_16x16x32_bf16 v[114:117], v[206:209], v[160:163], v[114:117]
	v_mfma_f32_16x16x32_bf16 v[118:121], v[210:213], v[160:163], v[118:121]
	v_mfma_f32_16x16x32_bf16 v[94:97], v[214:217], v[160:163], v[94:97]
	ds_read_b128 v[160:163], v21
	s_waitcnt lgkmcnt(0)
	v_mfma_f32_16x16x32_bf16 v[132:135], v[202:205], v[160:163], v[132:135]
	v_mfma_f32_16x16x32_bf16 v[136:139], v[206:209], v[160:163], v[136:139]
	v_mfma_f32_16x16x32_bf16 v[140:143], v[210:213], v[160:163], v[140:143]
	v_mfma_f32_16x16x32_bf16 v[122:125], v[214:217], v[160:163], v[122:125]
	ds_read_b128 v[160:163], v18
	s_waitcnt lgkmcnt(0)
	v_mfma_f32_16x16x32_bf16 v[144:147], v[202:205], v[160:163], v[144:147]
	v_mfma_f32_16x16x32_bf16 v[148:151], v[206:209], v[160:163], v[148:151]
	v_mfma_f32_16x16x32_bf16 v[152:155], v[210:213], v[160:163], v[152:155]
	v_mfma_f32_16x16x32_bf16 v[160:163], v[214:217], v[160:163], v[168:171]
	s_nop 2
	ds_read_b128 v[168:171], v20
	s_waitcnt lgkmcnt(0)
	v_mfma_f32_16x16x32_bf16 v[172:175], v[202:205], v[168:171], v[172:175]
	v_mfma_f32_16x16x32_bf16 v[176:179], v[206:209], v[168:171], v[176:179]
	v_mfma_f32_16x16x32_bf16 v[194:197], v[210:213], v[168:171], v[194:197]
	v_mfma_f32_16x16x32_bf16 v[156:159], v[214:217], v[168:171], v[156:159]
	ds_read_b128 v[168:171], v17
	s_waitcnt lgkmcnt(0)
	v_mfma_f32_16x16x32_bf16 v[50:53], v[206:209], v[168:171], v[50:53]
	v_mfma_f32_16x16x32_bf16 v[62:65], v[210:213], v[168:171], v[62:65]
	v_mfma_f32_16x16x32_bf16 v[66:69], v[214:217], v[168:171], v[66:69]
	v_mfma_f32_16x16x32_bf16 v[198:201], v[202:205], v[168:171], v[198:201]
	ds_read_b128 v[168:171], v24 offset:1024
	ds_read_b128 v[202:205], v23 offset:33792
	ds_read_b128 v[206:209], v23 offset:35840
	ds_read_b128 v[210:213], v23 offset:37888
	ds_read_b128 v[214:217], v23 offset:39936
	s_waitcnt lgkmcnt(0)
	v_mfma_f32_16x16x32_bf16 v[54:57], v[202:205], v[168:171], v[54:57]
	v_mfma_f32_16x16x32_bf16 v[58:61], v[206:209], v[168:171], v[58:61]
	v_mfma_f32_16x16x32_bf16 v[70:73], v[210:213], v[168:171], v[70:73]
	v_mfma_f32_16x16x32_bf16 v[74:77], v[214:217], v[168:171], v[74:77]
	ds_read_b128 v[168:171], v16 offset:1024
	s_waitcnt lgkmcnt(0)
	v_mfma_f32_16x16x32_bf16 v[78:81], v[202:205], v[168:171], v[78:81]
	v_mfma_f32_16x16x32_bf16 v[82:85], v[206:209], v[168:171], v[82:85]
	v_mfma_f32_16x16x32_bf16 v[86:89], v[210:213], v[168:171], v[86:89]
	v_mfma_f32_16x16x32_bf16 v[46:49], v[214:217], v[168:171], v[46:49]
	ds_read_b128 v[168:171], v22 offset:1024
	s_waitcnt lgkmcnt(0)
	v_mfma_f32_16x16x32_bf16 v[98:101], v[202:205], v[168:171], v[98:101]
	v_mfma_f32_16x16x32_bf16 v[102:105], v[206:209], v[168:171], v[102:105]
	v_mfma_f32_16x16x32_bf16 v[106:109], v[210:213], v[168:171], v[106:109]
	v_mfma_f32_16x16x32_bf16 v[90:93], v[214:217], v[168:171], v[90:93]
	ds_read_b128 v[168:171], v19 offset:1024
	s_waitcnt lgkmcnt(0)
	v_mfma_f32_16x16x32_bf16 v[110:113], v[202:205], v[168:171], v[110:113]
	v_mfma_f32_16x16x32_bf16 v[114:117], v[206:209], v[168:171], v[114:117]
	v_mfma_f32_16x16x32_bf16 v[118:121], v[210:213], v[168:171], v[118:121]
	v_mfma_f32_16x16x32_bf16 v[94:97], v[214:217], v[168:171], v[94:97]
	ds_read_b128 v[168:171], v21 offset:1024
	s_waitcnt lgkmcnt(0)
	v_mfma_f32_16x16x32_bf16 v[132:135], v[202:205], v[168:171], v[132:135]
	v_mfma_f32_16x16x32_bf16 v[136:139], v[206:209], v[168:171], v[136:139]
	v_mfma_f32_16x16x32_bf16 v[140:143], v[210:213], v[168:171], v[140:143]
	v_mfma_f32_16x16x32_bf16 v[122:125], v[214:217], v[168:171], v[122:125]
	ds_read_b128 v[168:171], v18 offset:1024
	s_waitcnt lgkmcnt(0)
	v_mfma_f32_16x16x32_bf16 v[144:147], v[202:205], v[168:171], v[144:147]
	v_mfma_f32_16x16x32_bf16 v[148:151], v[206:209], v[168:171], v[148:151]
	v_mfma_f32_16x16x32_bf16 v[152:155], v[210:213], v[168:171], v[152:155]
	v_mfma_f32_16x16x32_bf16 v[160:163], v[214:217], v[168:171], v[160:163]
	ds_read_b128 v[168:171], v20 offset:1024
	s_waitcnt lgkmcnt(0)
	v_mfma_f32_16x16x32_bf16 v[172:175], v[202:205], v[168:171], v[172:175]
	v_mfma_f32_16x16x32_bf16 v[176:179], v[206:209], v[168:171], v[176:179]
	v_mfma_f32_16x16x32_bf16 v[194:197], v[210:213], v[168:171], v[194:197]
	v_mfma_f32_16x16x32_bf16 v[156:159], v[214:217], v[168:171], v[156:159]
	ds_read_b128 v[168:171], v17 offset:1024
	s_waitcnt lgkmcnt(0)
	v_mfma_f32_16x16x32_bf16 v[50:53], v[206:209], v[168:171], v[50:53]
	v_mfma_f32_16x16x32_bf16 v[62:65], v[210:213], v[168:171], v[62:65]
	v_mfma_f32_16x16x32_bf16 v[66:69], v[214:217], v[168:171], v[66:69]
	v_mfma_f32_16x16x32_bf16 v[198:201], v[202:205], v[168:171], v[198:201]
	s_mov_b64 s[26:27], 0x200
	s_mov_b32 m0, s2
	v_lshl_add_u64 v[126:127], v[0:1], 0, s[26:27]
	s_waitcnt vmcnt(0)
	s_waitcnt vmcnt(0)
	s_barrier
	global_load_lds_dwordx4 v[126:127], off
	v_lshl_add_u64 v[126:127], v[2:3], 0, s[26:27]
	s_mov_b32 m0, s1
	s_nop 0
	global_load_lds_dwordx4 v[126:127], off
	v_lshl_add_u64 v[126:127], v[4:5], 0, s[26:27]
	s_mov_b32 m0, s3
	s_nop 0
	global_load_lds_dwordx4 v[126:127], off
	v_lshl_add_u64 v[126:127], v[6:7], 0, s[26:27]
	s_mov_b32 m0, s9
	s_nop 0
	global_load_lds_dwordx4 v[126:127], off
	v_lshl_add_u64 v[126:127], v[8:9], 0, s[26:27]
	s_mov_b32 m0, s10
	s_nop 0
	global_load_lds_dwordx4 v[126:127], off
	v_lshl_add_u64 v[126:127], v[10:11], 0, s[26:27]
	s_mov_b32 m0, s11
	s_nop 0
	global_load_lds_dwordx4 v[126:127], off
	v_lshl_add_u64 v[126:127], v[12:13], 0, s[26:27]
	s_mov_b32 m0, s16
	s_nop 0
	global_load_lds_dwordx4 v[126:127], off
	v_lshl_add_u64 v[126:127], v[14:15], 0, s[26:27]
	s_mov_b32 m0, s24
	s_nop 0
	global_load_lds_dwordx4 v[126:127], off
	ds_read_b128 v[168:171], v26
	ds_read_b128 v[202:205], v25
	ds_read_b128 v[206:209], v25 offset:2048
	ds_read_b128 v[210:213], v25 offset:4096
	ds_read_b128 v[214:217], v25 offset:6144
	s_waitcnt lgkmcnt(0)
	v_mfma_f32_16x16x32_bf16 v[54:57], v[202:205], v[168:171], v[54:57]
	v_mfma_f32_16x16x32_bf16 v[58:61], v[206:209], v[168:171], v[58:61]
	v_mfma_f32_16x16x32_bf16 v[70:73], v[210:213], v[168:171], v[70:73]
	v_mfma_f32_16x16x32_bf16 v[74:77], v[214:217], v[168:171], v[74:77]
	ds_read_b128 v[168:171], v27
	s_waitcnt lgkmcnt(0)
	v_mfma_f32_16x16x32_bf16 v[78:81], v[202:205], v[168:171], v[78:81]
	v_mfma_f32_16x16x32_bf16 v[82:85], v[206:209], v[168:171], v[82:85]
	v_mfma_f32_16x16x32_bf16 v[86:89], v[210:213], v[168:171], v[86:89]
	v_mfma_f32_16x16x32_bf16 v[46:49], v[214:217], v[168:171], v[46:49]
	ds_read_b128 v[168:171], v28
	s_waitcnt lgkmcnt(0)
	v_mfma_f32_16x16x32_bf16 v[98:101], v[202:205], v[168:171], v[98:101]
	v_mfma_f32_16x16x32_bf16 v[102:105], v[206:209], v[168:171], v[102:105]
	v_mfma_f32_16x16x32_bf16 v[106:109], v[210:213], v[168:171], v[106:109]
	v_mfma_f32_16x16x32_bf16 v[90:93], v[214:217], v[168:171], v[90:93]
	ds_read_b128 v[168:171], v29
	s_waitcnt lgkmcnt(0)
	v_mfma_f32_16x16x32_bf16 v[110:113], v[202:205], v[168:171], v[110:113]
	v_mfma_f32_16x16x32_bf16 v[114:117], v[206:209], v[168:171], v[114:117]
	v_mfma_f32_16x16x32_bf16 v[118:121], v[210:213], v[168:171], v[118:121]
	v_mfma_f32_16x16x32_bf16 v[94:97], v[214:217], v[168:171], v[94:97]
	ds_read_b128 v[168:171], v30
	s_waitcnt lgkmcnt(0)
	v_mfma_f32_16x16x32_bf16 v[132:135], v[202:205], v[168:171], v[132:135]
	v_mfma_f32_16x16x32_bf16 v[136:139], v[206:209], v[168:171], v[136:139]
	v_mfma_f32_16x16x32_bf16 v[140:143], v[210:213], v[168:171], v[140:143]
	v_mfma_f32_16x16x32_bf16 v[122:125], v[214:217], v[168:171], v[122:125]
	ds_read_b128 v[168:171], v31
	s_waitcnt lgkmcnt(0)
	v_mfma_f32_16x16x32_bf16 v[144:147], v[202:205], v[168:171], v[144:147]
	v_mfma_f32_16x16x32_bf16 v[148:151], v[206:209], v[168:171], v[148:151]
	v_mfma_f32_16x16x32_bf16 v[152:155], v[210:213], v[168:171], v[152:155]
	v_mfma_f32_16x16x32_bf16 v[160:163], v[214:217], v[168:171], v[160:163]
	ds_read_b128 v[168:171], v130
	s_waitcnt lgkmcnt(0)
	v_mfma_f32_16x16x32_bf16 v[172:175], v[202:205], v[168:171], v[172:175]
	v_mfma_f32_16x16x32_bf16 v[176:179], v[206:209], v[168:171], v[176:179]
	v_mfma_f32_16x16x32_bf16 v[194:197], v[210:213], v[168:171], v[194:197]
	v_mfma_f32_16x16x32_bf16 v[156:159], v[214:217], v[168:171], v[156:159]
	ds_read_b128 v[168:171], v131
	s_waitcnt lgkmcnt(0)
	v_mfma_f32_16x16x32_bf16 v[50:53], v[206:209], v[168:171], v[50:53]
	v_mfma_f32_16x16x32_bf16 v[62:65], v[210:213], v[168:171], v[62:65]
	v_mfma_f32_16x16x32_bf16 v[66:69], v[214:217], v[168:171], v[66:69]
	v_mfma_f32_16x16x32_bf16 v[198:201], v[202:205], v[168:171], v[198:201]
	ds_read_b128 v[168:171], v26 offset:1024
	ds_read_b128 v[202:205], v25 offset:1024
	ds_read_b128 v[206:209], v25 offset:3072
	ds_read_b128 v[210:213], v25 offset:5120
	ds_read_b128 v[214:217], v25 offset:7168
	s_waitcnt lgkmcnt(0)
	v_mfma_f32_16x16x32_bf16 v[54:57], v[202:205], v[168:171], v[54:57]
	v_mfma_f32_16x16x32_bf16 v[58:61], v[206:209], v[168:171], v[58:61]
	v_mfma_f32_16x16x32_bf16 v[70:73], v[210:213], v[168:171], v[70:73]
	v_mfma_f32_16x16x32_bf16 v[74:77], v[214:217], v[168:171], v[74:77]
	ds_read_b128 v[168:171], v27 offset:1024
	s_waitcnt lgkmcnt(0)
	v_mfma_f32_16x16x32_bf16 v[78:81], v[202:205], v[168:171], v[78:81]
	v_mfma_f32_16x16x32_bf16 v[82:85], v[206:209], v[168:171], v[82:85]
	v_mfma_f32_16x16x32_bf16 v[86:89], v[210:213], v[168:171], v[86:89]
	v_mfma_f32_16x16x32_bf16 v[46:49], v[214:217], v[168:171], v[46:49]
	ds_read_b128 v[168:171], v28 offset:1024
	s_waitcnt lgkmcnt(0)
	v_mfma_f32_16x16x32_bf16 v[98:101], v[202:205], v[168:171], v[98:101]
	v_mfma_f32_16x16x32_bf16 v[102:105], v[206:209], v[168:171], v[102:105]
	v_mfma_f32_16x16x32_bf16 v[106:109], v[210:213], v[168:171], v[106:109]
	v_mfma_f32_16x16x32_bf16 v[90:93], v[214:217], v[168:171], v[90:93]
	ds_read_b128 v[168:171], v29 offset:1024
	s_waitcnt lgkmcnt(0)
	v_mfma_f32_16x16x32_bf16 v[110:113], v[202:205], v[168:171], v[110:113]
	v_mfma_f32_16x16x32_bf16 v[114:117], v[206:209], v[168:171], v[114:117]
	v_mfma_f32_16x16x32_bf16 v[118:121], v[210:213], v[168:171], v[118:121]
	v_mfma_f32_16x16x32_bf16 v[94:97], v[214:217], v[168:171], v[94:97]
	ds_read_b128 v[168:171], v30 offset:1024
	s_waitcnt lgkmcnt(0)
	v_mfma_f32_16x16x32_bf16 v[132:135], v[202:205], v[168:171], v[132:135]
	v_mfma_f32_16x16x32_bf16 v[136:139], v[206:209], v[168:171], v[136:139]
	v_mfma_f32_16x16x32_bf16 v[140:143], v[210:213], v[168:171], v[140:143]
	v_mfma_f32_16x16x32_bf16 v[122:125], v[214:217], v[168:171], v[122:125]
	ds_read_b128 v[168:171], v31 offset:1024
	s_waitcnt lgkmcnt(0)
	v_mfma_f32_16x16x32_bf16 v[144:147], v[202:205], v[168:171], v[144:147]
	v_mfma_f32_16x16x32_bf16 v[148:151], v[206:209], v[168:171], v[148:151]
	v_mfma_f32_16x16x32_bf16 v[152:155], v[210:213], v[168:171], v[152:155]
	v_mfma_f32_16x16x32_bf16 v[160:163], v[214:217], v[168:171], v[160:163]
	ds_read_b128 v[168:171], v130 offset:1024
	s_waitcnt lgkmcnt(0)
	v_mfma_f32_16x16x32_bf16 v[172:175], v[202:205], v[168:171], v[172:175]
	v_mfma_f32_16x16x32_bf16 v[176:179], v[206:209], v[168:171], v[176:179]
	v_mfma_f32_16x16x32_bf16 v[194:197], v[210:213], v[168:171], v[194:197]
	v_mfma_f32_16x16x32_bf16 v[156:159], v[214:217], v[168:171], v[156:159]
	ds_read_b128 v[168:171], v131 offset:1024
	s_waitcnt lgkmcnt(0)
	v_mfma_f32_16x16x32_bf16 v[50:53], v[206:209], v[168:171], v[50:53]
	v_mfma_f32_16x16x32_bf16 v[62:65], v[210:213], v[168:171], v[62:65]
	v_mfma_f32_16x16x32_bf16 v[66:69], v[214:217], v[168:171], v[66:69]
	v_mfma_f32_16x16x32_bf16 v[198:201], v[202:205], v[168:171], v[198:201]
	s_mov_b64 s[26:27], 0x280
	v_readfirstlane_b32 s25, v39
	v_lshl_add_u64 v[126:127], v[0:1], 0, s[26:27]
	s_mov_b32 m0, s25
	v_readfirstlane_b32 s3, v38
	s_waitcnt vmcnt(0)
	s_waitcnt vmcnt(0)
	s_barrier
	global_load_lds_dwordx4 v[126:127], off
	v_lshl_add_u64 v[126:127], v[2:3], 0, s[26:27]
	s_mov_b32 m0, s3
	v_readfirstlane_b32 s9, v40
	global_load_lds_dwordx4 v[126:127], off
	v_lshl_add_u64 v[38:39], v[4:5], 0, s[26:27]
	s_mov_b32 m0, s9
	v_readfirstlane_b32 s10, v41
	global_load_lds_dwordx4 v[38:39], off
	v_lshl_add_u64 v[38:39], v[6:7], 0, s[26:27]
	s_mov_b32 m0, s10
	v_readfirstlane_b32 s11, v42
	global_load_lds_dwordx4 v[38:39], off
	v_lshl_add_u64 v[38:39], v[8:9], 0, s[26:27]
	s_mov_b32 m0, s11
	v_readfirstlane_b32 s16, v43
	global_load_lds_dwordx4 v[38:39], off
	v_lshl_add_u64 v[38:39], v[10:11], 0, s[26:27]
	s_mov_b32 m0, s16
	v_readfirstlane_b32 s24, v44
	global_load_lds_dwordx4 v[38:39], off
	v_lshl_add_u64 v[38:39], v[12:13], 0, s[26:27]
	s_mov_b32 m0, s24
	s_nop 0
	global_load_lds_dwordx4 v[38:39], off
	v_lshl_add_u64 v[38:39], v[14:15], 0, s[26:27]
	v_readfirstlane_b32 s26, v45
	s_mov_b32 m0, s26
	s_nop 0
	global_load_lds_dwordx4 v[38:39], off
	ds_read_b128 v[38:41], v24
	ds_read_b128 v[42:45], v23 offset:32768
	ds_read_b128 v[168:171], v23 offset:34816
	ds_read_b128 v[202:205], v23 offset:36864
	ds_read_b128 v[206:209], v23 offset:38912
	s_waitcnt lgkmcnt(0)
	v_mfma_f32_16x16x32_bf16 v[54:57], v[42:45], v[38:41], v[54:57]
	v_mfma_f32_16x16x32_bf16 v[58:61], v[168:171], v[38:41], v[58:61]
	v_mfma_f32_16x16x32_bf16 v[70:73], v[202:205], v[38:41], v[70:73]
	v_mfma_f32_16x16x32_bf16 v[38:41], v[206:209], v[38:41], v[74:77]
	s_nop 2
	ds_read_b128 v[74:77], v16
	s_waitcnt lgkmcnt(0)
	v_mfma_f32_16x16x32_bf16 v[78:81], v[42:45], v[74:77], v[78:81]
	v_mfma_f32_16x16x32_bf16 v[82:85], v[168:171], v[74:77], v[82:85]
	v_mfma_f32_16x16x32_bf16 v[86:89], v[202:205], v[74:77], v[86:89]
	v_mfma_f32_16x16x32_bf16 v[46:49], v[206:209], v[74:77], v[46:49]
	ds_read_b128 v[74:77], v22
	s_waitcnt lgkmcnt(0)
	v_mfma_f32_16x16x32_bf16 v[98:101], v[42:45], v[74:77], v[98:101]
	v_mfma_f32_16x16x32_bf16 v[102:105], v[168:171], v[74:77], v[102:105]
	v_mfma_f32_16x16x32_bf16 v[106:109], v[202:205], v[74:77], v[106:109]
	v_mfma_f32_16x16x32_bf16 v[74:77], v[206:209], v[74:77], v[90:93]
	s_nop 2
	ds_read_b128 v[90:93], v19
	s_waitcnt lgkmcnt(0)
	v_mfma_f32_16x16x32_bf16 v[110:113], v[42:45], v[90:93], v[110:113]
	v_mfma_f32_16x16x32_bf16 v[114:117], v[168:171], v[90:93], v[114:117]
	v_mfma_f32_16x16x32_bf16 v[118:121], v[202:205], v[90:93], v[118:121]
	v_mfma_f32_16x16x32_bf16 v[90:93], v[206:209], v[90:93], v[94:97]
	s_nop 2
	ds_read_b128 v[94:97], v21
	s_waitcnt lgkmcnt(0)
	v_mfma_f32_16x16x32_bf16 v[132:135], v[42:45], v[94:97], v[132:135]
	v_mfma_f32_16x16x32_bf16 v[136:139], v[168:171], v[94:97], v[136:139]
	v_mfma_f32_16x16x32_bf16 v[140:143], v[202:205], v[94:97], v[140:143]
	v_mfma_f32_16x16x32_bf16 v[94:97], v[206:209], v[94:97], v[122:125]
	s_nop 2
	ds_read_b128 v[122:125], v18
	s_waitcnt lgkmcnt(0)
	v_mfma_f32_16x16x32_bf16 v[144:147], v[42:45], v[122:125], v[144:147]
	v_mfma_f32_16x16x32_bf16 v[148:151], v[168:171], v[122:125], v[148:151]
	v_mfma_f32_16x16x32_bf16 v[152:155], v[202:205], v[122:125], v[152:155]
	v_mfma_f32_16x16x32_bf16 v[122:125], v[206:209], v[122:125], v[160:163]
	s_nop 2
	ds_read_b128 v[160:163], v20
	s_waitcnt lgkmcnt(0)
	v_mfma_f32_16x16x32_bf16 v[172:175], v[42:45], v[160:163], v[172:175]
	v_mfma_f32_16x16x32_bf16 v[176:179], v[168:171], v[160:163], v[176:179]
	v_mfma_f32_16x16x32_bf16 v[194:197], v[202:205], v[160:163], v[194:197]
	v_mfma_f32_16x16x32_bf16 v[156:159], v[206:209], v[160:163], v[156:159]
	ds_read_b128 v[160:163], v17
	s_waitcnt lgkmcnt(0)
	v_mfma_f32_16x16x32_bf16 v[42:45], v[42:45], v[160:163], v[198:201]
	v_mfma_f32_16x16x32_bf16 v[50:53], v[168:171], v[160:163], v[50:53]
	v_mfma_f32_16x16x32_bf16 v[62:65], v[202:205], v[160:163], v[62:65]
	v_mfma_f32_16x16x32_bf16 v[66:69], v[206:209], v[160:163], v[66:69]
	ds_read_b128 v[160:163], v24 offset:1024
	ds_read_b128 v[168:171], v23 offset:33792
	ds_read_b128 v[198:201], v23 offset:35840
	ds_read_b128 v[202:205], v23 offset:37888
	ds_read_b128 v[206:209], v23 offset:39936
	s_waitcnt lgkmcnt(0)
	v_mfma_f32_16x16x32_bf16 v[54:57], v[168:171], v[160:163], v[54:57]
	v_mfma_f32_16x16x32_bf16 v[58:61], v[198:201], v[160:163], v[58:61]
	v_mfma_f32_16x16x32_bf16 v[70:73], v[202:205], v[160:163], v[70:73]
	v_mfma_f32_16x16x32_bf16 v[38:41], v[206:209], v[160:163], v[38:41]
	ds_read_b128 v[160:163], v16 offset:1024
	s_waitcnt lgkmcnt(0)
	v_mfma_f32_16x16x32_bf16 v[78:81], v[168:171], v[160:163], v[78:81]
	v_mfma_f32_16x16x32_bf16 v[82:85], v[198:201], v[160:163], v[82:85]
	v_mfma_f32_16x16x32_bf16 v[86:89], v[202:205], v[160:163], v[86:89]
	v_mfma_f32_16x16x32_bf16 v[46:49], v[206:209], v[160:163], v[46:49]
	ds_read_b128 v[160:163], v22 offset:1024
	s_waitcnt lgkmcnt(0)
	v_mfma_f32_16x16x32_bf16 v[98:101], v[168:171], v[160:163], v[98:101]
	v_mfma_f32_16x16x32_bf16 v[102:105], v[198:201], v[160:163], v[102:105]
	v_mfma_f32_16x16x32_bf16 v[106:109], v[202:205], v[160:163], v[106:109]
	v_mfma_f32_16x16x32_bf16 v[74:77], v[206:209], v[160:163], v[74:77]
	ds_read_b128 v[160:163], v19 offset:1024
	s_waitcnt lgkmcnt(0)
	v_mfma_f32_16x16x32_bf16 v[110:113], v[168:171], v[160:163], v[110:113]
	v_mfma_f32_16x16x32_bf16 v[114:117], v[198:201], v[160:163], v[114:117]
	v_mfma_f32_16x16x32_bf16 v[118:121], v[202:205], v[160:163], v[118:121]
	v_mfma_f32_16x16x32_bf16 v[90:93], v[206:209], v[160:163], v[90:93]
	ds_read_b128 v[160:163], v21 offset:1024
	s_waitcnt lgkmcnt(0)
	v_mfma_f32_16x16x32_bf16 v[132:135], v[168:171], v[160:163], v[132:135]
	v_mfma_f32_16x16x32_bf16 v[136:139], v[198:201], v[160:163], v[136:139]
	v_mfma_f32_16x16x32_bf16 v[140:143], v[202:205], v[160:163], v[140:143]
	v_mfma_f32_16x16x32_bf16 v[94:97], v[206:209], v[160:163], v[94:97]
	ds_read_b128 v[160:163], v18 offset:1024
	s_waitcnt lgkmcnt(0)
	v_mfma_f32_16x16x32_bf16 v[144:147], v[168:171], v[160:163], v[144:147]
	v_mfma_f32_16x16x32_bf16 v[148:151], v[198:201], v[160:163], v[148:151]
	v_mfma_f32_16x16x32_bf16 v[152:155], v[202:205], v[160:163], v[152:155]
	v_mfma_f32_16x16x32_bf16 v[122:125], v[206:209], v[160:163], v[122:125]
	ds_read_b128 v[160:163], v20 offset:1024
	s_waitcnt lgkmcnt(0)
	v_mfma_f32_16x16x32_bf16 v[172:175], v[168:171], v[160:163], v[172:175]
	v_mfma_f32_16x16x32_bf16 v[176:179], v[198:201], v[160:163], v[176:179]
	v_mfma_f32_16x16x32_bf16 v[194:197], v[202:205], v[160:163], v[194:197]
	v_mfma_f32_16x16x32_bf16 v[156:159], v[206:209], v[160:163], v[156:159]
	ds_read_b128 v[160:163], v17 offset:1024
	s_waitcnt lgkmcnt(0)
	v_mfma_f32_16x16x32_bf16 v[42:45], v[168:171], v[160:163], v[42:45]
	v_mfma_f32_16x16x32_bf16 v[50:53], v[198:201], v[160:163], v[50:53]
	v_mfma_f32_16x16x32_bf16 v[62:65], v[202:205], v[160:163], v[62:65]
	v_mfma_f32_16x16x32_bf16 v[66:69], v[206:209], v[160:163], v[66:69]
	s_mov_b64 s[34:35], 0x300
	s_mov_b32 m0, s2
	v_lshl_add_u64 v[126:127], v[0:1], 0, s[34:35]
	s_waitcnt vmcnt(0)
	s_waitcnt vmcnt(0)
	s_barrier
	global_load_lds_dwordx4 v[126:127], off
	v_lshl_add_u64 v[126:127], v[2:3], 0, s[34:35]
	s_mov_b32 m0, s1
	v_readfirstlane_b32 s1, v32
	global_load_lds_dwordx4 v[126:127], off
	v_lshl_add_u64 v[126:127], v[4:5], 0, s[34:35]
	s_mov_b32 m0, s1
	v_readfirstlane_b32 s1, v33
	global_load_lds_dwordx4 v[126:127], off
	v_lshl_add_u64 v[126:127], v[6:7], 0, s[34:35]
	s_mov_b32 m0, s1
	v_readfirstlane_b32 s1, v34
	global_load_lds_dwordx4 v[126:127], off
	v_lshl_add_u64 v[32:33], v[8:9], 0, s[34:35]
	s_mov_b32 m0, s1
	v_readfirstlane_b32 s1, v35
	global_load_lds_dwordx4 v[32:33], off
	v_lshl_add_u64 v[32:33], v[10:11], 0, s[34:35]
	s_mov_b32 m0, s1
	v_readfirstlane_b32 s1, v36
	global_load_lds_dwordx4 v[32:33], off
	v_lshl_add_u64 v[32:33], v[12:13], 0, s[34:35]
	s_mov_b32 m0, s1
	v_readfirstlane_b32 s1, v37
	global_load_lds_dwordx4 v[32:33], off
	v_lshl_add_u64 v[32:33], v[14:15], 0, s[34:35]
	s_mov_b32 m0, s1
	s_nop 0
	global_load_lds_dwordx4 v[32:33], off
	ds_read_b128 v[32:35], v26
	ds_read_b128 v[160:163], v25
	ds_read_b128 v[168:171], v25 offset:2048
	ds_read_b128 v[198:201], v25 offset:4096
	ds_read_b128 v[202:205], v25 offset:6144
	s_waitcnt lgkmcnt(0)
	v_mfma_f32_16x16x32_bf16 v[54:57], v[160:163], v[32:35], v[54:57]
	v_mfma_f32_16x16x32_bf16 v[58:61], v[168:171], v[32:35], v[58:61]
	v_mfma_f32_16x16x32_bf16 v[70:73], v[198:201], v[32:35], v[70:73]
	v_mfma_f32_16x16x32_bf16 v[32:35], v[202:205], v[32:35], v[38:41]
	s_nop 2
	ds_read_b128 v[36:39], v27
	s_waitcnt lgkmcnt(0)
	v_mfma_f32_16x16x32_bf16 v[78:81], v[160:163], v[36:39], v[78:81]
	v_mfma_f32_16x16x32_bf16 v[82:85], v[168:171], v[36:39], v[82:85]
	v_mfma_f32_16x16x32_bf16 v[86:89], v[198:201], v[36:39], v[86:89]
	v_mfma_f32_16x16x32_bf16 v[36:39], v[202:205], v[36:39], v[46:49]
	s_nop 2
	ds_read_b128 v[46:49], v28
	s_waitcnt lgkmcnt(0)
	v_mfma_f32_16x16x32_bf16 v[98:101], v[160:163], v[46:49], v[98:101]
	v_mfma_f32_16x16x32_bf16 v[102:105], v[168:171], v[46:49], v[102:105]
	v_mfma_f32_16x16x32_bf16 v[106:109], v[198:201], v[46:49], v[106:109]
	v_mfma_f32_16x16x32_bf16 v[46:49], v[202:205], v[46:49], v[74:77]
	s_nop 2
	ds_read_b128 v[74:77], v29
	s_waitcnt lgkmcnt(0)
	v_mfma_f32_16x16x32_bf16 v[110:113], v[160:163], v[74:77], v[110:113]
	v_mfma_f32_16x16x32_bf16 v[114:117], v[168:171], v[74:77], v[114:117]
	v_mfma_f32_16x16x32_bf16 v[118:121], v[198:201], v[74:77], v[118:121]
	v_mfma_f32_16x16x32_bf16 v[74:77], v[202:205], v[74:77], v[90:93]
	s_nop 2
	ds_read_b128 v[90:93], v30
	s_waitcnt lgkmcnt(0)
	v_mfma_f32_16x16x32_bf16 v[132:135], v[160:163], v[90:93], v[132:135]
	v_mfma_f32_16x16x32_bf16 v[136:139], v[168:171], v[90:93], v[136:139]
	v_mfma_f32_16x16x32_bf16 v[140:143], v[198:201], v[90:93], v[140:143]
	v_mfma_f32_16x16x32_bf16 v[90:93], v[202:205], v[90:93], v[94:97]
	s_nop 2
	ds_read_b128 v[94:97], v31
	s_waitcnt lgkmcnt(0)
	v_mfma_f32_16x16x32_bf16 v[144:147], v[160:163], v[94:97], v[144:147]
	v_mfma_f32_16x16x32_bf16 v[148:151], v[168:171], v[94:97], v[148:151]
	v_mfma_f32_16x16x32_bf16 v[152:155], v[198:201], v[94:97], v[152:155]
	v_mfma_f32_16x16x32_bf16 v[94:97], v[202:205], v[94:97], v[122:125]
	s_nop 2
	ds_read_b128 v[122:125], v130
	s_waitcnt lgkmcnt(0)
	v_mfma_f32_16x16x32_bf16 v[172:175], v[160:163], v[122:125], v[172:175]
	v_mfma_f32_16x16x32_bf16 v[176:179], v[168:171], v[122:125], v[176:179]
	v_mfma_f32_16x16x32_bf16 v[194:197], v[198:201], v[122:125], v[194:197]
	v_mfma_f32_16x16x32_bf16 v[122:125], v[202:205], v[122:125], v[156:159]
	s_nop 2
	ds_read_b128 v[156:159], v131
	s_waitcnt lgkmcnt(0)
	v_mfma_f32_16x16x32_bf16 v[40:43], v[160:163], v[156:159], v[42:45]
	v_mfma_f32_16x16x32_bf16 v[50:53], v[168:171], v[156:159], v[50:53]
	v_mfma_f32_16x16x32_bf16 v[62:65], v[198:201], v[156:159], v[62:65]
	v_mfma_f32_16x16x32_bf16 v[66:69], v[202:205], v[156:159], v[66:69]
	ds_read_b128 v[156:159], v26 offset:1024
	ds_read_b128 v[160:163], v25 offset:1024
	ds_read_b128 v[168:171], v25 offset:3072
	ds_read_b128 v[198:201], v25 offset:5120
	ds_read_b128 v[202:205], v25 offset:7168
	s_waitcnt lgkmcnt(0)
	v_mfma_f32_16x16x32_bf16 v[54:57], v[160:163], v[156:159], v[54:57]
	v_mfma_f32_16x16x32_bf16 v[58:61], v[168:171], v[156:159], v[58:61]
	v_mfma_f32_16x16x32_bf16 v[70:73], v[198:201], v[156:159], v[70:73]
	v_mfma_f32_16x16x32_bf16 v[32:35], v[202:205], v[156:159], v[32:35]
	ds_read_b128 v[156:159], v27 offset:1024
	s_waitcnt lgkmcnt(0)
	v_mfma_f32_16x16x32_bf16 v[78:81], v[160:163], v[156:159], v[78:81]
	v_mfma_f32_16x16x32_bf16 v[82:85], v[168:171], v[156:159], v[82:85]
	v_mfma_f32_16x16x32_bf16 v[86:89], v[198:201], v[156:159], v[86:89]
	v_mfma_f32_16x16x32_bf16 v[36:39], v[202:205], v[156:159], v[36:39]
	ds_read_b128 v[156:159], v28 offset:1024
	s_waitcnt lgkmcnt(0)
	v_mfma_f32_16x16x32_bf16 v[98:101], v[160:163], v[156:159], v[98:101]
	v_mfma_f32_16x16x32_bf16 v[102:105], v[168:171], v[156:159], v[102:105]
	v_mfma_f32_16x16x32_bf16 v[106:109], v[198:201], v[156:159], v[106:109]
	v_mfma_f32_16x16x32_bf16 v[44:47], v[202:205], v[156:159], v[46:49]
	ds_read_b128 v[156:159], v29 offset:1024
	s_waitcnt lgkmcnt(0)
	v_mfma_f32_16x16x32_bf16 v[110:113], v[160:163], v[156:159], v[110:113]
	v_mfma_f32_16x16x32_bf16 v[114:117], v[168:171], v[156:159], v[114:117]
	v_mfma_f32_16x16x32_bf16 v[118:121], v[198:201], v[156:159], v[118:121]
	v_mfma_f32_16x16x32_bf16 v[74:77], v[202:205], v[156:159], v[74:77]
	ds_read_b128 v[156:159], v30 offset:1024
	s_waitcnt lgkmcnt(0)
	v_mfma_f32_16x16x32_bf16 v[132:135], v[160:163], v[156:159], v[132:135]
	v_mfma_f32_16x16x32_bf16 v[136:139], v[168:171], v[156:159], v[136:139]
	v_mfma_f32_16x16x32_bf16 v[140:143], v[198:201], v[156:159], v[140:143]
	v_mfma_f32_16x16x32_bf16 v[90:93], v[202:205], v[156:159], v[90:93]
	ds_read_b128 v[156:159], v31 offset:1024
	s_waitcnt lgkmcnt(0)
	v_mfma_f32_16x16x32_bf16 v[144:147], v[160:163], v[156:159], v[144:147]
	v_mfma_f32_16x16x32_bf16 v[148:151], v[168:171], v[156:159], v[148:151]
	v_mfma_f32_16x16x32_bf16 v[152:155], v[198:201], v[156:159], v[152:155]
	v_mfma_f32_16x16x32_bf16 v[94:97], v[202:205], v[156:159], v[94:97]
	ds_read_b128 v[156:159], v130 offset:1024
	s_waitcnt lgkmcnt(0)
	v_mfma_f32_16x16x32_bf16 v[172:175], v[160:163], v[156:159], v[172:175]
	v_mfma_f32_16x16x32_bf16 v[176:179], v[168:171], v[156:159], v[176:179]
	v_mfma_f32_16x16x32_bf16 v[194:197], v[198:201], v[156:159], v[194:197]
	v_mfma_f32_16x16x32_bf16 v[122:125], v[202:205], v[156:159], v[122:125]
	ds_read_b128 v[156:159], v131 offset:1024
	s_waitcnt lgkmcnt(0)
	v_mfma_f32_16x16x32_bf16 v[40:43], v[160:163], v[156:159], v[40:43]
	v_mfma_f32_16x16x32_bf16 v[48:51], v[168:171], v[156:159], v[50:53]
	v_mfma_f32_16x16x32_bf16 v[62:65], v[198:201], v[156:159], v[62:65]
	v_mfma_f32_16x16x32_bf16 v[66:69], v[202:205], v[156:159], v[66:69]
	s_mov_b64 s[34:35], 0x380
	s_mov_b32 m0, s25
	v_lshl_add_u64 v[0:1], v[0:1], 0, s[34:35]
	s_waitcnt vmcnt(0)
	s_waitcnt vmcnt(0)
	s_barrier
	global_load_lds_dwordx4 v[0:1], off
	v_lshl_add_u64 v[0:1], v[2:3], 0, s[34:35]
	s_mov_b32 m0, s3
	s_nop 0
	global_load_lds_dwordx4 v[0:1], off
	v_lshl_add_u64 v[0:1], v[4:5], 0, s[34:35]
	s_mov_b32 m0, s9
	s_nop 0
	global_load_lds_dwordx4 v[0:1], off
	v_lshl_add_u64 v[0:1], v[6:7], 0, s[34:35]
	s_mov_b32 m0, s10
	s_nop 0
	global_load_lds_dwordx4 v[0:1], off
	v_lshl_add_u64 v[0:1], v[8:9], 0, s[34:35]
	s_mov_b32 m0, s11
	s_nop 0
	global_load_lds_dwordx4 v[0:1], off
	v_lshl_add_u64 v[0:1], v[10:11], 0, s[34:35]
	s_mov_b32 m0, s16
	s_nop 0
	global_load_lds_dwordx4 v[0:1], off
	v_lshl_add_u64 v[0:1], v[12:13], 0, s[34:35]
	s_mov_b32 m0, s24
	s_nop 0
	global_load_lds_dwordx4 v[0:1], off
	v_lshl_add_u64 v[0:1], v[14:15], 0, s[34:35]
	s_mov_b32 m0, s26
	s_nop 0
	global_load_lds_dwordx4 v[0:1], off
	ds_read_b128 v[0:3], v24
	ds_read_b128 v[4:7], v23 offset:32768
	ds_read_b128 v[12:15], v23 offset:34816
	ds_read_b128 v[156:159], v23 offset:38912
	s_waitcnt lgkmcnt(0)
	v_mfma_f32_16x16x32_bf16 v[8:11], v[4:7], v[0:3], v[54:57]
	v_mfma_f32_16x16x32_bf16 v[52:55], v[12:15], v[0:3], v[58:61]
	s_nop 2
	ds_read_b128 v[56:59], v23 offset:36864
	s_waitcnt lgkmcnt(0)
	v_mfma_f32_16x16x32_bf16 v[70:73], v[56:59], v[0:3], v[70:73]
	v_mfma_f32_16x16x32_bf16 v[0:3], v[156:159], v[0:3], v[32:35]
	s_nop 2
	ds_read_b128 v[32:35], v16
	s_waitcnt lgkmcnt(0)
	v_mfma_f32_16x16x32_bf16 v[78:81], v[4:7], v[32:35], v[78:81]
	v_mfma_f32_16x16x32_bf16 v[82:85], v[12:15], v[32:35], v[82:85]
	v_mfma_f32_16x16x32_bf16 v[86:89], v[56:59], v[32:35], v[86:89]
	v_mfma_f32_16x16x32_bf16 v[32:35], v[156:159], v[32:35], v[36:39]
	s_nop 2
	ds_read_b128 v[36:39], v22
	s_waitcnt lgkmcnt(0)
	v_mfma_f32_16x16x32_bf16 v[98:101], v[4:7], v[36:39], v[98:101]
	v_mfma_f32_16x16x32_bf16 v[102:105], v[12:15], v[36:39], v[102:105]
	v_mfma_f32_16x16x32_bf16 v[106:109], v[56:59], v[36:39], v[106:109]
	v_mfma_f32_16x16x32_bf16 v[36:39], v[156:159], v[36:39], v[44:47]
	s_nop 2
	ds_read_b128 v[44:47], v19
	s_waitcnt lgkmcnt(0)
	v_mfma_f32_16x16x32_bf16 v[110:113], v[4:7], v[44:47], v[110:113]
	v_mfma_f32_16x16x32_bf16 v[114:117], v[12:15], v[44:47], v[114:117]
	v_mfma_f32_16x16x32_bf16 v[118:121], v[56:59], v[44:47], v[118:121]
	v_mfma_f32_16x16x32_bf16 v[44:47], v[156:159], v[44:47], v[74:77]
	s_nop 2
	ds_read_b128 v[74:77], v21
	s_waitcnt lgkmcnt(0)
	v_mfma_f32_16x16x32_bf16 v[132:135], v[4:7], v[74:77], v[132:135]
	v_mfma_f32_16x16x32_bf16 v[136:139], v[12:15], v[74:77], v[136:139]
	v_mfma_f32_16x16x32_bf16 v[140:143], v[56:59], v[74:77], v[140:143]
	v_mfma_f32_16x16x32_bf16 v[74:77], v[156:159], v[74:77], v[90:93]
	s_nop 2
	ds_read_b128 v[90:93], v18
	s_waitcnt lgkmcnt(0)
	v_mfma_f32_16x16x32_bf16 v[144:147], v[4:7], v[90:93], v[144:147]
	v_mfma_f32_16x16x32_bf16 v[148:151], v[12:15], v[90:93], v[148:151]
	v_mfma_f32_16x16x32_bf16 v[152:155], v[56:59], v[90:93], v[152:155]
	v_mfma_f32_16x16x32_bf16 v[90:93], v[156:159], v[90:93], v[94:97]
	s_nop 2
	ds_read_b128 v[94:97], v20
	s_waitcnt lgkmcnt(0)
	v_mfma_f32_16x16x32_bf16 v[160:163], v[4:7], v[94:97], v[172:175]
	v_mfma_f32_16x16x32_bf16 v[168:171], v[12:15], v[94:97], v[176:179]
	v_mfma_f32_16x16x32_bf16 v[172:175], v[56:59], v[94:97], v[194:197]
	v_mfma_f32_16x16x32_bf16 v[94:97], v[156:159], v[94:97], v[122:125]
	s_nop 2
	ds_read_b128 v[122:125], v17
	s_waitcnt lgkmcnt(0)
	v_mfma_f32_16x16x32_bf16 v[4:7], v[4:7], v[122:125], v[40:43]
	v_mfma_f32_16x16x32_bf16 v[12:15], v[12:15], v[122:125], v[48:51]
	v_mfma_f32_16x16x32_bf16 v[40:43], v[56:59], v[122:125], v[62:65]
	v_mfma_f32_16x16x32_bf16 v[48:51], v[156:159], v[122:125], v[66:69]
	ds_read_b128 v[56:59], v24 offset:1024
	s_nop 0
	ds_read_b128 v[60:63], v23 offset:33792
	ds_read_b128 v[64:67], v23 offset:35840
	ds_read_b128 v[122:125], v23 offset:37888
	ds_read_b128 v[156:159], v23 offset:39936
	s_waitcnt lgkmcnt(0)
	v_mfma_f32_16x16x32_bf16 v[8:11], v[60:63], v[56:59], v[8:11]
	v_mfma_f32_16x16x32_bf16 v[52:55], v[64:67], v[56:59], v[52:55]
	v_mfma_f32_16x16x32_bf16 v[68:71], v[122:125], v[56:59], v[70:73]
	v_mfma_f32_16x16x32_bf16 v[0:3], v[156:159], v[56:59], v[0:3]
	ds_read_b128 v[56:59], v16 offset:1024
	s_waitcnt lgkmcnt(0)
	v_mfma_f32_16x16x32_bf16 v[78:81], v[60:63], v[56:59], v[78:81]
	v_mfma_f32_16x16x32_bf16 v[82:85], v[64:67], v[56:59], v[82:85]
	v_mfma_f32_16x16x32_bf16 v[86:89], v[122:125], v[56:59], v[86:89]
	v_mfma_f32_16x16x32_bf16 v[32:35], v[156:159], v[56:59], v[32:35]
	ds_read_b128 v[56:59], v22 offset:1024
	s_waitcnt lgkmcnt(0)
	v_mfma_f32_16x16x32_bf16 v[98:101], v[60:63], v[56:59], v[98:101]
	v_mfma_f32_16x16x32_bf16 v[102:105], v[64:67], v[56:59], v[102:105]
	v_mfma_f32_16x16x32_bf16 v[106:109], v[122:125], v[56:59], v[106:109]
	v_mfma_f32_16x16x32_bf16 v[36:39], v[156:159], v[56:59], v[36:39]
	ds_read_b128 v[56:59], v19 offset:1024
	s_waitcnt lgkmcnt(0)
	v_mfma_f32_16x16x32_bf16 v[110:113], v[60:63], v[56:59], v[110:113]
	v_mfma_f32_16x16x32_bf16 v[114:117], v[64:67], v[56:59], v[114:117]
	v_mfma_f32_16x16x32_bf16 v[118:121], v[122:125], v[56:59], v[118:121]
	v_mfma_f32_16x16x32_bf16 v[44:47], v[156:159], v[56:59], v[44:47]
	ds_read_b128 v[56:59], v21 offset:1024
	s_waitcnt lgkmcnt(0)
	v_mfma_f32_16x16x32_bf16 v[132:135], v[60:63], v[56:59], v[132:135]
	v_mfma_f32_16x16x32_bf16 v[136:139], v[64:67], v[56:59], v[136:139]
	v_mfma_f32_16x16x32_bf16 v[140:143], v[122:125], v[56:59], v[140:143]
	v_mfma_f32_16x16x32_bf16 v[56:59], v[156:159], v[56:59], v[74:77]
	s_nop 2
	ds_read_b128 v[72:75], v18 offset:1024
	ds_read_b128 v[18:21], v20 offset:1024
	s_waitcnt lgkmcnt(0)
	v_mfma_f32_16x16x32_bf16 v[144:147], v[60:63], v[72:75], v[144:147]
	v_mfma_f32_16x16x32_bf16 v[148:151], v[64:67], v[72:75], v[148:151]
	v_mfma_f32_16x16x32_bf16 v[152:155], v[122:125], v[72:75], v[152:155]
	v_mfma_f32_16x16x32_bf16 v[72:75], v[156:159], v[72:75], v[90:93]
	v_mfma_f32_16x16x32_bf16 v[90:93], v[60:63], v[18:21], v[160:163]
	v_mfma_f32_16x16x32_bf16 v[160:163], v[64:67], v[18:21], v[168:171]
	v_mfma_f32_16x16x32_bf16 v[168:171], v[122:125], v[18:21], v[172:175]
	v_mfma_f32_16x16x32_bf16 v[18:21], v[156:159], v[18:21], v[94:97]
	s_nop 2
	ds_read_b128 v[94:97], v17 offset:1024
	s_waitcnt lgkmcnt(0)
	v_mfma_f32_16x16x32_bf16 v[4:7], v[60:63], v[94:97], v[4:7]
	v_mfma_f32_16x16x32_bf16 v[12:15], v[64:67], v[94:97], v[12:15]
	v_mfma_f32_16x16x32_bf16 v[40:43], v[122:125], v[94:97], v[40:43]
	v_mfma_f32_16x16x32_bf16 v[48:51], v[156:159], v[94:97], v[48:51]
	s_waitcnt vmcnt(0)
	s_waitcnt vmcnt(0)
	s_barrier
	ds_read_b128 v[60:63], v26
	ds_read_b128 v[64:67], v25
	ds_read_b128 v[94:97], v25 offset:2048
	ds_read_b128 v[122:125], v25 offset:4096
	ds_read_b128 v[156:159], v25 offset:6144
	s_waitcnt lgkmcnt(3)
	v_mfma_f32_16x16x32_bf16 v[8:11], v[64:67], v[60:63], v[8:11]
	s_waitcnt lgkmcnt(2)
	v_mfma_f32_16x16x32_bf16 v[52:55], v[94:97], v[60:63], v[52:55]
	s_waitcnt lgkmcnt(1)
	v_mfma_f32_16x16x32_bf16 v[68:71], v[122:125], v[60:63], v[68:71]
	s_waitcnt lgkmcnt(0)
	v_mfma_f32_16x16x32_bf16 v[0:3], v[156:159], v[60:63], v[0:3]
	ds_read_b128 v[60:63], v27
	s_waitcnt lgkmcnt(0)
	v_mfma_f32_16x16x32_bf16 v[76:79], v[64:67], v[60:63], v[78:81]
	v_mfma_f32_16x16x32_bf16 v[80:83], v[94:97], v[60:63], v[82:85]
	v_mfma_f32_16x16x32_bf16 v[84:87], v[122:125], v[60:63], v[86:89]
	v_mfma_f32_16x16x32_bf16 v[32:35], v[156:159], v[60:63], v[32:35]
	ds_read_b128 v[60:63], v28
	s_waitcnt lgkmcnt(0)
	v_mfma_f32_16x16x32_bf16 v[172:175], v[64:67], v[60:63], v[98:101]
	v_mfma_f32_16x16x32_bf16 v[176:179], v[94:97], v[60:63], v[102:105]
	v_mfma_f32_16x16x32_bf16 v[194:197], v[122:125], v[60:63], v[106:109]
	v_mfma_f32_16x16x32_bf16 v[36:39], v[156:159], v[60:63], v[36:39]
	ds_read_b128 v[60:63], v29
	s_waitcnt lgkmcnt(0)
	v_mfma_f32_16x16x32_bf16 v[198:201], v[64:67], v[60:63], v[110:113]
	v_mfma_f32_16x16x32_bf16 v[202:205], v[94:97], v[60:63], v[114:117]
	v_mfma_f32_16x16x32_bf16 v[206:209], v[122:125], v[60:63], v[118:121]
	v_mfma_f32_16x16x32_bf16 v[44:47], v[156:159], v[60:63], v[44:47]
	ds_read_b128 v[60:63], v30
	s_waitcnt lgkmcnt(0)
	v_mfma_f32_16x16x32_bf16 v[210:213], v[156:159], v[60:63], v[56:59]
	s_nop 2
	ds_read_b128 v[56:59], v31
	s_waitcnt lgkmcnt(0)
	v_mfma_f32_16x16x32_bf16 v[144:147], v[64:67], v[56:59], v[144:147]
	v_mfma_f32_16x16x32_bf16 v[148:151], v[94:97], v[56:59], v[148:151]
	v_mfma_f32_16x16x32_bf16 v[152:155], v[122:125], v[56:59], v[152:155]
	v_mfma_f32_16x16x32_bf16 v[214:217], v[156:159], v[56:59], v[72:75]
	ds_read_b128 v[56:59], v130
	s_waitcnt lgkmcnt(0)
	v_mfma_f32_16x16x32_bf16 v[20:23], v[156:159], v[56:59], v[18:21]
	s_nop 2
	ds_read_b128 v[16:19], v131
	v_mfma_f32_16x16x32_bf16 v[140:143], v[122:125], v[60:63], v[140:143]
	s_waitcnt lgkmcnt(0)
	v_mfma_f32_16x16x32_bf16 v[4:7], v[64:67], v[16:19], v[4:7]
	v_mfma_f32_16x16x32_bf16 v[132:135], v[64:67], v[60:63], v[132:135]
	v_mfma_f32_16x16x32_bf16 v[136:139], v[94:97], v[60:63], v[136:139]
	v_mfma_f32_16x16x32_bf16 v[218:221], v[64:67], v[56:59], v[90:93]
	v_mfma_f32_16x16x32_bf16 v[160:163], v[94:97], v[56:59], v[160:163]
	v_mfma_f32_16x16x32_bf16 v[168:171], v[122:125], v[56:59], v[168:171]
	v_mfma_f32_16x16x32_bf16 v[222:225], v[94:97], v[16:19], v[12:15]
	v_mfma_f32_16x16x32_bf16 v[226:229], v[122:125], v[16:19], v[40:43]
	v_mfma_f32_16x16x32_bf16 v[156:159], v[156:159], v[16:19], v[48:51]
	s_nop 0
	ds_read_b128 v[12:15], v26 offset:1024
	ds_read_b128 v[230:233], v25 offset:1024
	ds_read_b128 v[238:241], v25 offset:7168
	s_waitcnt lgkmcnt(0)
	v_mfma_f32_16x16x32_bf16 v[120:123], v[238:241], v[12:15], v[0:3]
	s_nop 2
	ds_read_b128 v[0:3], v27 offset:1024
	ds_read_b128 v[234:237], v25 offset:5120
	v_mfma_f32_16x16x32_bf16 v[112:115], v[230:233], v[12:15], v[8:11]
	s_nop 2
	ds_read_b128 v[8:11], v25 offset:3072
	s_waitcnt lgkmcnt(2)
	v_mfma_f32_16x16x32_bf16 v[108:111], v[230:233], v[0:3], v[76:79]
	s_waitcnt lgkmcnt(0)
	v_mfma_f32_16x16x32_bf16 v[96:99], v[8:11], v[0:3], v[80:83]
	v_mfma_f32_16x16x32_bf16 v[104:107], v[234:237], v[0:3], v[84:87]
	v_mfma_f32_16x16x32_bf16 v[100:103], v[238:241], v[0:3], v[32:35]
	ds_read_b128 v[0:3], v28 offset:1024
	s_waitcnt lgkmcnt(0)
	v_mfma_f32_16x16x32_bf16 v[92:95], v[230:233], v[0:3], v[172:175]
	v_mfma_f32_16x16x32_bf16 v[80:83], v[8:11], v[0:3], v[176:179]
	v_mfma_f32_16x16x32_bf16 v[88:91], v[234:237], v[0:3], v[194:197]
	v_mfma_f32_16x16x32_bf16 v[84:87], v[238:241], v[0:3], v[36:39]
	ds_read_b128 v[0:3], v29 offset:1024
	v_mfma_f32_16x16x32_bf16 v[124:127], v[234:237], v[12:15], v[68:71]
	s_waitcnt lgkmcnt(0)
	v_mfma_f32_16x16x32_bf16 v[76:79], v[230:233], v[0:3], v[198:201]
	v_mfma_f32_16x16x32_bf16 v[64:67], v[8:11], v[0:3], v[202:205]
	v_mfma_f32_16x16x32_bf16 v[72:75], v[234:237], v[0:3], v[206:209]
	v_mfma_f32_16x16x32_bf16 v[68:71], v[238:241], v[0:3], v[44:47]
	ds_read_b128 v[0:3], v30 offset:1024
	v_mfma_f32_16x16x32_bf16 v[116:119], v[8:11], v[12:15], v[52:55]
	s_waitcnt lgkmcnt(0)
	v_mfma_f32_16x16x32_bf16 v[60:63], v[230:233], v[0:3], v[132:135]
	v_mfma_f32_16x16x32_bf16 v[48:51], v[8:11], v[0:3], v[136:139]
	v_mfma_f32_16x16x32_bf16 v[56:59], v[234:237], v[0:3], v[140:143]
	v_mfma_f32_16x16x32_bf16 v[52:55], v[238:241], v[0:3], v[210:213]
	ds_read_b128 v[0:3], v31 offset:1024
	s_waitcnt lgkmcnt(0)
	v_mfma_f32_16x16x32_bf16 v[44:47], v[230:233], v[0:3], v[144:147]
	v_mfma_f32_16x16x32_bf16 v[32:35], v[8:11], v[0:3], v[148:151]
	v_mfma_f32_16x16x32_bf16 v[40:43], v[234:237], v[0:3], v[152:155]
	v_mfma_f32_16x16x32_bf16 v[36:39], v[238:241], v[0:3], v[214:217]
	ds_read_b128 v[0:3], v130 offset:1024
	ds_read_b128 v[130:133], v131 offset:1024
	s_waitcnt lgkmcnt(1)
	v_mfma_f32_16x16x32_bf16 v[28:31], v[230:233], v[0:3], v[218:221]
	v_mfma_f32_16x16x32_bf16 v[16:19], v[8:11], v[0:3], v[160:163]
	v_mfma_f32_16x16x32_bf16 v[24:27], v[234:237], v[0:3], v[168:171]
	v_mfma_f32_16x16x32_bf16 v[20:23], v[238:241], v[0:3], v[20:23]
	s_waitcnt lgkmcnt(0)
	v_mfma_f32_16x16x32_bf16 v[12:15], v[230:233], v[130:133], v[4:7]
	v_mfma_f32_16x16x32_bf16 v[0:3], v[8:11], v[130:133], v[222:225]
	v_mfma_f32_16x16x32_bf16 v[8:11], v[234:237], v[130:133], v[226:229]
	v_mfma_f32_16x16x32_bf16 v[4:7], v[238:241], v[130:133], v[156:159]
	s_waitcnt vmcnt(0)
	s_barrier
	s_add_i32 s0, s20, 0xfffffde0
	s_mul_i32 s1, s0, 0xaaab
	s_lshr_b32 s1, s1, 18
	s_mul_i32 s2, s1, 6
	s_sub_i32 s2, s0, s2
	v_readfirstlane_b32 s8, v167
	v_and_b32_e32 v128, 15, v167
	v_bfe_u32 v129, v167, 4, 2
	s_lshr_b32 s8, s8, 6
	s_and_b32 s9, s8, 3
	s_lshr_b32 s8, s8, 2
	s_lshl_b32 s3, s1, 8
	s_lshl_b32 s10, s8, 7
	s_add_u32 s3, s3, s10
	s_lshl_b32 s10, s2, 8
	s_lshl_b32 s11, s9, 6
	s_add_u32 s10, s10, s11
	v_readlane_b32 s24, v255, 28
	v_readlane_b32 s25, v255, 29
	s_mul_i32 s11, s3, 0xc00
	s_lshl_b32 s26, s10, 1
	s_add_u32 s11, s11, s26
	s_add_u32 s24, s24, s11
	s_addc_u32 s25, s25, 0
	v_mul_u32_u24_e32 v131, 0xc00, v128
	v_lshl_add_u32 v131, v129, 3, v131
	s_lshl_b32 s11, s8, 9
	v_lshl_add_u32 v130, v128, 2, s11
	v_add_u32_e32 v130, 0x20000, v130
	ds_read_b32 v134, v130
	ds_read_b32 v135, v130 offset:64
	ds_read_b32 v136, v130 offset:128
	ds_read_b32 v137, v130 offset:192
	ds_read_b32 v138, v130 offset:256
	ds_read_b32 v139, v130 offset:320
	ds_read_b32 v140, v130 offset:384
	ds_read_b32 v141, v130 offset:448
	s_lshl_b32 s11, s2, 2
	s_add_u32 s11, s11, s9
	s_mul_i32 s26, s11, 0xaaab
	s_lshr_b32 s26, s26, 17
	s_mul_i32 s26, s26, 3
	s_sub_u32 s11, s11, s26
	s_cmp_eq_u32 s11, 2
	s_cselect_b32 s11, 1, 0
	s_cmp_lt_u32 s1, 64
	s_cselect_b32 s11, s11, 0
	s_cmp_eq_u32 s11, 0
	s_cbranch_scc1 .Lq_norope
	s_and_b32 s26, s3, 0xfff
	s_lshr_b32 s26, s26, 6
	s_lshl_b32 s26, s26, 7
	v_lshlrev_b32_e32 v132, 5, v129
	v_lshl_add_u32 v133, v128, 7, v132
	v_add_u32_e32 v132, s26, v132
	global_load_dwordx4 v[194:197], v132, s[38:39]
	global_load_dwordx4 v[198:201], v132, s[38:39] offset:16
	global_load_dwordx4 v[210:213], v133, s[38:39]
	global_load_dwordx4 v[214:217], v133, s[38:39] offset:16
	global_load_dwordx4 v[202:205], v132, s[38:39]
	global_load_dwordx4 v[206:209], v132, s[38:39] offset:16
	global_load_dwordx4 v[218:221], v133, s[38:39] offset:2048
	global_load_dwordx4 v[222:225], v133, s[38:39] offset:2064
	s_waitcnt lgkmcnt(0)
	global_load_dwordx4 v[226:229], v132, s[38:39]
	global_load_dwordx4 v[230:233], v132, s[38:39] offset:16
	v_add_u32_e32 v160, 4096, v133
	global_load_dwordx4 v[142:145], v160, s[38:39]
	global_load_dwordx4 v[146:149], v160, s[38:39] offset:16
	global_load_dwordx4 v[234:237], v132, s[38:39]
	global_load_dwordx4 v[238:241], v132, s[38:39] offset:16
	v_add_u32_e32 v160, 6144, v133
	global_load_dwordx4 v[150:153], v160, s[38:39]
	global_load_dwordx4 v[154:157], v160, s[38:39] offset:16
	v_mul_f32_e32 v112, v112, v134
	v_mul_f32_e32 v113, v113, v134
	v_mul_f32_e32 v114, v114, v134
	v_mul_f32_e32 v115, v115, v134
	v_mul_f32_e32 v116, v116, v134
	v_mul_f32_e32 v117, v117, v134
	v_mul_f32_e32 v118, v118, v134
	v_mul_f32_e32 v119, v119, v134
	v_mul_f32_e32 v124, v124, v134
	v_mul_f32_e32 v125, v125, v134
	v_mul_f32_e32 v126, v126, v134
	v_mul_f32_e32 v127, v127, v134
	v_mul_f32_e32 v120, v120, v134
	v_mul_f32_e32 v121, v121, v134
	v_mul_f32_e32 v122, v122, v134
	v_mul_f32_e32 v123, v123, v134
	v_mul_f32_e32 v108, v108, v135
	v_mul_f32_e32 v109, v109, v135
	v_mul_f32_e32 v110, v110, v135
	v_mul_f32_e32 v111, v111, v135
	v_mul_f32_e32 v96, v96, v135
	v_mul_f32_e32 v97, v97, v135
	v_mul_f32_e32 v98, v98, v135
	v_mul_f32_e32 v99, v99, v135
	v_mul_f32_e32 v104, v104, v135
	v_mul_f32_e32 v105, v105, v135
	v_mul_f32_e32 v106, v106, v135
	v_mul_f32_e32 v107, v107, v135
	v_mul_f32_e32 v100, v100, v135
	v_mul_f32_e32 v101, v101, v135
	v_mul_f32_e32 v102, v102, v135
	v_mul_f32_e32 v103, v103, v135
	s_waitcnt vmcnt(8)
	v_mul_f32_e32 v160, v116, v195
	v_mul_f32_e32 v161, v112, v195
	v_fma_f32 v112, v112, v194, -v160
	v_fma_f32 v116, v116, v194, v161
	v_mul_f32_e32 v162, v117, v197
	v_mul_f32_e32 v163, v113, v197
	v_fma_f32 v113, v113, v196, -v162
	v_fma_f32 v117, v117, v196, v163
	v_mul_f32_e32 v160, v118, v199
	v_mul_f32_e32 v161, v114, v199
	v_fma_f32 v114, v114, v198, -v160
	v_fma_f32 v118, v118, v198, v161
	v_mul_f32_e32 v162, v119, v201
	v_mul_f32_e32 v163, v115, v201
	v_fma_f32 v115, v115, v200, -v162
	v_fma_f32 v119, v119, v200, v163
	v_mul_f32_e32 v160, v120, v211
	v_mul_f32_e32 v161, v124, v211
	v_fma_f32 v124, v124, v210, -v160
	v_fma_f32 v120, v120, v210, v161
	v_mul_f32_e32 v162, v121, v213
	v_mul_f32_e32 v163, v125, v213
	v_fma_f32 v125, v125, v212, -v162
	v_fma_f32 v121, v121, v212, v163
	v_mul_f32_e32 v160, v122, v215
	v_mul_f32_e32 v161, v126, v215
	v_fma_f32 v126, v126, v214, -v160
	v_fma_f32 v122, v122, v214, v161
	v_mul_f32_e32 v162, v123, v217
	v_mul_f32_e32 v163, v127, v217
	v_fma_f32 v127, v127, v216, -v162
	v_fma_f32 v123, v123, v216, v163
	v_mul_f32_e32 v160, v96, v203
	v_mul_f32_e32 v161, v108, v203
	v_fma_f32 v108, v108, v202, -v160
	v_fma_f32 v96, v96, v202, v161
	v_mul_f32_e32 v162, v97, v205
	v_mul_f32_e32 v163, v109, v205
	v_fma_f32 v109, v109, v204, -v162
	v_fma_f32 v97, v97, v204, v163
	v_mul_f32_e32 v160, v98, v207
	v_mul_f32_e32 v161, v110, v207
	v_fma_f32 v110, v110, v206, -v160
	v_fma_f32 v98, v98, v206, v161
	v_mul_f32_e32 v162, v99, v209
	v_mul_f32_e32 v163, v111, v209
	v_fma_f32 v111, v111, v208, -v162
	v_fma_f32 v99, v99, v208, v163
	v_mul_f32_e32 v160, v100, v219
	v_mul_f32_e32 v161, v104, v219
	v_fma_f32 v104, v104, v218, -v160
	v_fma_f32 v100, v100, v218, v161
	v_mul_f32_e32 v162, v101, v221
	v_mul_f32_e32 v163, v105, v221
	v_fma_f32 v105, v105, v220, -v162
	v_fma_f32 v101, v101, v220, v163
	v_mul_f32_e32 v160, v102, v223
	v_mul_f32_e32 v161, v106, v223
	v_fma_f32 v106, v106, v222, -v160
	v_fma_f32 v102, v102, v222, v161
	v_mul_f32_e32 v162, v103, v225
	v_mul_f32_e32 v163, v107, v225
	v_fma_f32 v107, v107, v224, -v162
	v_fma_f32 v103, v103, v224, v163
	v_mov_b32_e32 v158, v131
	v_cvt_pk_bf16_f32 v112, v112, v113
	v_cvt_pk_bf16_f32 v113, v114, v115
	v_cvt_pk_bf16_f32 v116, v116, v117
	v_cvt_pk_bf16_f32 v117, v118, v119
	v_cvt_pk_bf16_f32 v124, v124, v125
	v_cvt_pk_bf16_f32 v125, v126, v127
	v_cvt_pk_bf16_f32 v120, v120, v121
	v_cvt_pk_bf16_f32 v121, v122, v123
	global_store_dwordx2 v158, v[112:113], s[24:25]
	global_store_dwordx2 v158, v[116:117], s[24:25] offset:32
	global_store_dwordx2 v158, v[124:125], s[24:25] offset:64
	global_store_dwordx2 v158, v[120:121], s[24:25] offset:96
	v_add_u32_e32 v158, 49152, v131
	v_cvt_pk_bf16_f32 v108, v108, v109
	v_cvt_pk_bf16_f32 v109, v110, v111
	v_cvt_pk_bf16_f32 v96, v96, v97
	v_cvt_pk_bf16_f32 v97, v98, v99
	v_cvt_pk_bf16_f32 v104, v104, v105
	v_cvt_pk_bf16_f32 v105, v106, v107
	v_cvt_pk_bf16_f32 v100, v100, v101
	v_cvt_pk_bf16_f32 v101, v102, v103
	global_store_dwordx2 v158, v[108:109], s[24:25]
	global_store_dwordx2 v158, v[96:97], s[24:25] offset:32
	global_store_dwordx2 v158, v[104:105], s[24:25] offset:64
	global_store_dwordx2 v158, v[100:101], s[24:25] offset:96
	global_load_dwordx4 v[194:197], v132, s[38:39] offset:128
	global_load_dwordx4 v[198:201], v132, s[38:39] offset:144
	global_load_dwordx4 v[210:213], v133, s[38:39]
	global_load_dwordx4 v[214:217], v133, s[38:39] offset:16
	global_load_dwordx4 v[202:205], v132, s[38:39] offset:128
	global_load_dwordx4 v[206:209], v132, s[38:39] offset:144
	global_load_dwordx4 v[218:221], v133, s[38:39] offset:2048
	global_load_dwordx4 v[222:225], v133, s[38:39] offset:2064
	v_mul_f32_e32 v92, v92, v136
	v_mul_f32_e32 v93, v93, v136
	v_mul_f32_e32 v94, v94, v136
	v_mul_f32_e32 v95, v95, v136
	v_mul_f32_e32 v80, v80, v136
	v_mul_f32_e32 v81, v81, v136
	v_mul_f32_e32 v82, v82, v136
	v_mul_f32_e32 v83, v83, v136
	v_mul_f32_e32 v88, v88, v136
	v_mul_f32_e32 v89, v89, v136
	v_mul_f32_e32 v90, v90, v136
	v_mul_f32_e32 v91, v91, v136
	v_mul_f32_e32 v84, v84, v136
	v_mul_f32_e32 v85, v85, v136
	v_mul_f32_e32 v86, v86, v136
	v_mul_f32_e32 v87, v87, v136
	v_mul_f32_e32 v76, v76, v137
	v_mul_f32_e32 v77, v77, v137
	v_mul_f32_e32 v78, v78, v137
	v_mul_f32_e32 v79, v79, v137
	v_mul_f32_e32 v64, v64, v137
	v_mul_f32_e32 v65, v65, v137
	v_mul_f32_e32 v66, v66, v137
	v_mul_f32_e32 v67, v67, v137
	v_mul_f32_e32 v72, v72, v137
	v_mul_f32_e32 v73, v73, v137
	v_mul_f32_e32 v74, v74, v137
	v_mul_f32_e32 v75, v75, v137
	v_mul_f32_e32 v68, v68, v137
	v_mul_f32_e32 v69, v69, v137
	v_mul_f32_e32 v70, v70, v137
	v_mul_f32_e32 v71, v71, v137
	s_waitcnt vmcnt(16)
	v_mul_f32_e32 v160, v80, v227
	v_mul_f32_e32 v161, v92, v227
	v_fma_f32 v92, v92, v226, -v160
	v_fma_f32 v80, v80, v226, v161
	v_mul_f32_e32 v162, v81, v229
	v_mul_f32_e32 v163, v93, v229
	v_fma_f32 v93, v93, v228, -v162
	v_fma_f32 v81, v81, v228, v163
	v_mul_f32_e32 v160, v82, v231
	v_mul_f32_e32 v161, v94, v231
	v_fma_f32 v94, v94, v230, -v160
	v_fma_f32 v82, v82, v230, v161
	v_mul_f32_e32 v162, v83, v233
	v_mul_f32_e32 v163, v95, v233
	v_fma_f32 v95, v95, v232, -v162
	v_fma_f32 v83, v83, v232, v163
	v_mul_f32_e32 v160, v84, v143
	v_mul_f32_e32 v161, v88, v143
	v_fma_f32 v88, v88, v142, -v160
	v_fma_f32 v84, v84, v142, v161
	v_mul_f32_e32 v162, v85, v145
	v_mul_f32_e32 v163, v89, v145
	v_fma_f32 v89, v89, v144, -v162
	v_fma_f32 v85, v85, v144, v163
	v_mul_f32_e32 v160, v86, v147
	v_mul_f32_e32 v161, v90, v147
	v_fma_f32 v90, v90, v146, -v160
	v_fma_f32 v86, v86, v146, v161
	v_mul_f32_e32 v162, v87, v149
	v_mul_f32_e32 v163, v91, v149
	v_fma_f32 v91, v91, v148, -v162
	v_fma_f32 v87, v87, v148, v163
	v_mul_f32_e32 v160, v64, v235
	v_mul_f32_e32 v161, v76, v235
	v_fma_f32 v76, v76, v234, -v160
	v_fma_f32 v64, v64, v234, v161
	v_mul_f32_e32 v162, v65, v237
	v_mul_f32_e32 v163, v77, v237
	v_fma_f32 v77, v77, v236, -v162
	v_fma_f32 v65, v65, v236, v163
	v_mul_f32_e32 v160, v66, v239
	v_mul_f32_e32 v161, v78, v239
	v_fma_f32 v78, v78, v238, -v160
	v_fma_f32 v66, v66, v238, v161
	v_mul_f32_e32 v162, v67, v241
	v_mul_f32_e32 v163, v79, v241
	v_fma_f32 v79, v79, v240, -v162
	v_fma_f32 v67, v67, v240, v163
	v_mul_f32_e32 v160, v68, v151
	v_mul_f32_e32 v161, v72, v151
	v_fma_f32 v72, v72, v150, -v160
	v_fma_f32 v68, v68, v150, v161
	v_mul_f32_e32 v162, v69, v153
	v_mul_f32_e32 v163, v73, v153
	v_fma_f32 v73, v73, v152, -v162
	v_fma_f32 v69, v69, v152, v163
	v_mul_f32_e32 v160, v70, v155
	v_mul_f32_e32 v161, v74, v155
	v_fma_f32 v74, v74, v154, -v160
	v_fma_f32 v70, v70, v154, v161
	v_mul_f32_e32 v162, v71, v157
	v_mul_f32_e32 v163, v75, v157
	v_fma_f32 v75, v75, v156, -v162
	v_fma_f32 v71, v71, v156, v163
	v_add_u32_e32 v158, 98304, v131
	v_cvt_pk_bf16_f32 v92, v92, v93
	v_cvt_pk_bf16_f32 v93, v94, v95
	v_cvt_pk_bf16_f32 v80, v80, v81
	v_cvt_pk_bf16_f32 v81, v82, v83
	v_cvt_pk_bf16_f32 v88, v88, v89
	v_cvt_pk_bf16_f32 v89, v90, v91
	v_cvt_pk_bf16_f32 v84, v84, v85
	v_cvt_pk_bf16_f32 v85, v86, v87
	global_store_dwordx2 v158, v[92:93], s[24:25]
	global_store_dwordx2 v158, v[80:81], s[24:25] offset:32
	global_store_dwordx2 v158, v[88:89], s[24:25] offset:64
	global_store_dwordx2 v158, v[84:85], s[24:25] offset:96
	v_add_u32_e32 v158, 147456, v131
	v_cvt_pk_bf16_f32 v76, v76, v77
	v_cvt_pk_bf16_f32 v77, v78, v79
	v_cvt_pk_bf16_f32 v64, v64, v65
	v_cvt_pk_bf16_f32 v65, v66, v67
	v_cvt_pk_bf16_f32 v72, v72, v73
	v_cvt_pk_bf16_f32 v73, v74, v75
	v_cvt_pk_bf16_f32 v68, v68, v69
	v_cvt_pk_bf16_f32 v69, v70, v71
	global_store_dwordx2 v158, v[76:77], s[24:25]
	global_store_dwordx2 v158, v[64:65], s[24:25] offset:32
	global_store_dwordx2 v158, v[72:73], s[24:25] offset:64
	global_store_dwordx2 v158, v[68:69], s[24:25] offset:96
	global_load_dwordx4 v[226:229], v132, s[38:39] offset:128
	global_load_dwordx4 v[230:233], v132, s[38:39] offset:144
	v_add_u32_e32 v160, 4096, v133
	global_load_dwordx4 v[142:145], v160, s[38:39]
	global_load_dwordx4 v[146:149], v160, s[38:39] offset:16
	global_load_dwordx4 v[234:237], v132, s[38:39] offset:128
	global_load_dwordx4 v[238:241], v132, s[38:39] offset:144
	v_add_u32_e32 v160, 6144, v133
	global_load_dwordx4 v[150:153], v160, s[38:39]
	global_load_dwordx4 v[154:157], v160, s[38:39] offset:16
	v_mul_f32_e32 v60, v60, v138
	v_mul_f32_e32 v61, v61, v138
	v_mul_f32_e32 v62, v62, v138
	v_mul_f32_e32 v63, v63, v138
	v_mul_f32_e32 v48, v48, v138
	v_mul_f32_e32 v49, v49, v138
	v_mul_f32_e32 v50, v50, v138
	v_mul_f32_e32 v51, v51, v138
	v_mul_f32_e32 v56, v56, v138
	v_mul_f32_e32 v57, v57, v138
	v_mul_f32_e32 v58, v58, v138
	v_mul_f32_e32 v59, v59, v138
	v_mul_f32_e32 v52, v52, v138
	v_mul_f32_e32 v53, v53, v138
	v_mul_f32_e32 v54, v54, v138
	v_mul_f32_e32 v55, v55, v138
	v_mul_f32_e32 v44, v44, v139
	v_mul_f32_e32 v45, v45, v139
	v_mul_f32_e32 v46, v46, v139
	v_mul_f32_e32 v47, v47, v139
	v_mul_f32_e32 v32, v32, v139
	v_mul_f32_e32 v33, v33, v139
	v_mul_f32_e32 v34, v34, v139
	v_mul_f32_e32 v35, v35, v139
	v_mul_f32_e32 v40, v40, v139
	v_mul_f32_e32 v41, v41, v139
	v_mul_f32_e32 v42, v42, v139
	v_mul_f32_e32 v43, v43, v139
	v_mul_f32_e32 v36, v36, v139
	v_mul_f32_e32 v37, v37, v139
	v_mul_f32_e32 v38, v38, v139
	v_mul_f32_e32 v39, v39, v139
	s_waitcnt vmcnt(16)
	v_mul_f32_e32 v160, v48, v195
	v_mul_f32_e32 v161, v60, v195
	v_fma_f32 v60, v60, v194, -v160
	v_fma_f32 v48, v48, v194, v161
	v_mul_f32_e32 v162, v49, v197
	v_mul_f32_e32 v163, v61, v197
	v_fma_f32 v61, v61, v196, -v162
	v_fma_f32 v49, v49, v196, v163
	v_mul_f32_e32 v160, v50, v199
	v_mul_f32_e32 v161, v62, v199
	v_fma_f32 v62, v62, v198, -v160
	v_fma_f32 v50, v50, v198, v161
	v_mul_f32_e32 v162, v51, v201
	v_mul_f32_e32 v163, v63, v201
	v_fma_f32 v63, v63, v200, -v162
	v_fma_f32 v51, v51, v200, v163
	v_mul_f32_e32 v160, v52, v211
	v_mul_f32_e32 v161, v56, v211
	v_fma_f32 v56, v56, v210, -v160
	v_fma_f32 v52, v52, v210, v161
	v_mul_f32_e32 v162, v53, v213
	v_mul_f32_e32 v163, v57, v213
	v_fma_f32 v57, v57, v212, -v162
	v_fma_f32 v53, v53, v212, v163
	v_mul_f32_e32 v160, v54, v215
	v_mul_f32_e32 v161, v58, v215
	v_fma_f32 v58, v58, v214, -v160
	v_fma_f32 v54, v54, v214, v161
	v_mul_f32_e32 v162, v55, v217
	v_mul_f32_e32 v163, v59, v217
	v_fma_f32 v59, v59, v216, -v162
	v_fma_f32 v55, v55, v216, v163
	v_mul_f32_e32 v160, v32, v203
	v_mul_f32_e32 v161, v44, v203
	v_fma_f32 v44, v44, v202, -v160
	v_fma_f32 v32, v32, v202, v161
	v_mul_f32_e32 v162, v33, v205
	v_mul_f32_e32 v163, v45, v205
	v_fma_f32 v45, v45, v204, -v162
	v_fma_f32 v33, v33, v204, v163
	v_mul_f32_e32 v160, v34, v207
	v_mul_f32_e32 v161, v46, v207
	v_fma_f32 v46, v46, v206, -v160
	v_fma_f32 v34, v34, v206, v161
	v_mul_f32_e32 v162, v35, v209
	v_mul_f32_e32 v163, v47, v209
	v_fma_f32 v47, v47, v208, -v162
	v_fma_f32 v35, v35, v208, v163
	v_mul_f32_e32 v160, v36, v219
	v_mul_f32_e32 v161, v40, v219
	v_fma_f32 v40, v40, v218, -v160
	v_fma_f32 v36, v36, v218, v161
	v_mul_f32_e32 v162, v37, v221
	v_mul_f32_e32 v163, v41, v221
	v_fma_f32 v41, v41, v220, -v162
	v_fma_f32 v37, v37, v220, v163
	v_mul_f32_e32 v160, v38, v223
	v_mul_f32_e32 v161, v42, v223
	v_fma_f32 v42, v42, v222, -v160
	v_fma_f32 v38, v38, v222, v161
	v_mul_f32_e32 v162, v39, v225
	v_mul_f32_e32 v163, v43, v225
	v_fma_f32 v43, v43, v224, -v162
	v_fma_f32 v39, v39, v224, v163
	v_add_u32_e32 v158, 196608, v131
	v_cvt_pk_bf16_f32 v60, v60, v61
	v_cvt_pk_bf16_f32 v61, v62, v63
	v_cvt_pk_bf16_f32 v48, v48, v49
	v_cvt_pk_bf16_f32 v49, v50, v51
	v_cvt_pk_bf16_f32 v56, v56, v57
	v_cvt_pk_bf16_f32 v57, v58, v59
	v_cvt_pk_bf16_f32 v52, v52, v53
	v_cvt_pk_bf16_f32 v53, v54, v55
	global_store_dwordx2 v158, v[60:61], s[24:25]
	global_store_dwordx2 v158, v[48:49], s[24:25] offset:32
	global_store_dwordx2 v158, v[56:57], s[24:25] offset:64
	global_store_dwordx2 v158, v[52:53], s[24:25] offset:96
	v_add_u32_e32 v158, 245760, v131
	v_cvt_pk_bf16_f32 v44, v44, v45
	v_cvt_pk_bf16_f32 v45, v46, v47
	v_cvt_pk_bf16_f32 v32, v32, v33
	v_cvt_pk_bf16_f32 v33, v34, v35
	v_cvt_pk_bf16_f32 v40, v40, v41
	v_cvt_pk_bf16_f32 v41, v42, v43
	v_cvt_pk_bf16_f32 v36, v36, v37
	v_cvt_pk_bf16_f32 v37, v38, v39
	global_store_dwordx2 v158, v[44:45], s[24:25]
	global_store_dwordx2 v158, v[32:33], s[24:25] offset:32
	global_store_dwordx2 v158, v[40:41], s[24:25] offset:64
	global_store_dwordx2 v158, v[36:37], s[24:25] offset:96
	v_mul_f32_e32 v28, v28, v140
	v_mul_f32_e32 v29, v29, v140
	v_mul_f32_e32 v30, v30, v140
	v_mul_f32_e32 v31, v31, v140
	v_mul_f32_e32 v16, v16, v140
	v_mul_f32_e32 v17, v17, v140
	v_mul_f32_e32 v18, v18, v140
	v_mul_f32_e32 v19, v19, v140
	v_mul_f32_e32 v24, v24, v140
	v_mul_f32_e32 v25, v25, v140
	v_mul_f32_e32 v26, v26, v140
	v_mul_f32_e32 v27, v27, v140
	v_mul_f32_e32 v20, v20, v140
	v_mul_f32_e32 v21, v21, v140
	v_mul_f32_e32 v22, v22, v140
	v_mul_f32_e32 v23, v23, v140
	v_mul_f32_e32 v12, v12, v141
	v_mul_f32_e32 v13, v13, v141
	v_mul_f32_e32 v14, v14, v141
	v_mul_f32_e32 v15, v15, v141
	v_mul_f32_e32 v0, v0, v141
	v_mul_f32_e32 v1, v1, v141
	v_mul_f32_e32 v2, v2, v141
	v_mul_f32_e32 v3, v3, v141
	v_mul_f32_e32 v8, v8, v141
	v_mul_f32_e32 v9, v9, v141
	v_mul_f32_e32 v10, v10, v141
	v_mul_f32_e32 v11, v11, v141
	v_mul_f32_e32 v4, v4, v141
	v_mul_f32_e32 v5, v5, v141
	v_mul_f32_e32 v6, v6, v141
	v_mul_f32_e32 v7, v7, v141
	s_waitcnt vmcnt(8)
	v_mul_f32_e32 v160, v16, v227
	v_mul_f32_e32 v161, v28, v227
	v_fma_f32 v28, v28, v226, -v160
	v_fma_f32 v16, v16, v226, v161
	v_mul_f32_e32 v162, v17, v229
	v_mul_f32_e32 v163, v29, v229
	v_fma_f32 v29, v29, v228, -v162
	v_fma_f32 v17, v17, v228, v163
	v_mul_f32_e32 v160, v18, v231
	v_mul_f32_e32 v161, v30, v231
	v_fma_f32 v30, v30, v230, -v160
	v_fma_f32 v18, v18, v230, v161
	v_mul_f32_e32 v162, v19, v233
	v_mul_f32_e32 v163, v31, v233
	v_fma_f32 v31, v31, v232, -v162
	v_fma_f32 v19, v19, v232, v163
	v_mul_f32_e32 v160, v20, v143
	v_mul_f32_e32 v161, v24, v143
	v_fma_f32 v24, v24, v142, -v160
	v_fma_f32 v20, v20, v142, v161
	v_mul_f32_e32 v162, v21, v145
	v_mul_f32_e32 v163, v25, v145
	v_fma_f32 v25, v25, v144, -v162
	v_fma_f32 v21, v21, v144, v163
	v_mul_f32_e32 v160, v22, v147
	v_mul_f32_e32 v161, v26, v147
	v_fma_f32 v26, v26, v146, -v160
	v_fma_f32 v22, v22, v146, v161
	v_mul_f32_e32 v162, v23, v149
	v_mul_f32_e32 v163, v27, v149
	v_fma_f32 v27, v27, v148, -v162
	v_fma_f32 v23, v23, v148, v163
	v_mul_f32_e32 v160, v0, v235
	v_mul_f32_e32 v161, v12, v235
	v_fma_f32 v12, v12, v234, -v160
	v_fma_f32 v0, v0, v234, v161
	v_mul_f32_e32 v162, v1, v237
	v_mul_f32_e32 v163, v13, v237
	v_fma_f32 v13, v13, v236, -v162
	v_fma_f32 v1, v1, v236, v163
	v_mul_f32_e32 v160, v2, v239
	v_mul_f32_e32 v161, v14, v239
	v_fma_f32 v14, v14, v238, -v160
	v_fma_f32 v2, v2, v238, v161
	v_mul_f32_e32 v162, v3, v241
	v_mul_f32_e32 v163, v15, v241
	v_fma_f32 v15, v15, v240, -v162
	v_fma_f32 v3, v3, v240, v163
	v_mul_f32_e32 v160, v4, v151
	v_mul_f32_e32 v161, v8, v151
	v_fma_f32 v8, v8, v150, -v160
	v_fma_f32 v4, v4, v150, v161
	v_mul_f32_e32 v162, v5, v153
	v_mul_f32_e32 v163, v9, v153
	v_fma_f32 v9, v9, v152, -v162
	v_fma_f32 v5, v5, v152, v163
	v_mul_f32_e32 v160, v6, v155
	v_mul_f32_e32 v161, v10, v155
	v_fma_f32 v10, v10, v154, -v160
	v_fma_f32 v6, v6, v154, v161
	v_mul_f32_e32 v162, v7, v157
	v_mul_f32_e32 v163, v11, v157
	v_fma_f32 v11, v11, v156, -v162
	v_fma_f32 v7, v7, v156, v163
	v_add_u32_e32 v158, 294912, v131
	v_cvt_pk_bf16_f32 v28, v28, v29
	v_cvt_pk_bf16_f32 v29, v30, v31
	v_cvt_pk_bf16_f32 v16, v16, v17
	v_cvt_pk_bf16_f32 v17, v18, v19
	v_cvt_pk_bf16_f32 v24, v24, v25
	v_cvt_pk_bf16_f32 v25, v26, v27
	v_cvt_pk_bf16_f32 v20, v20, v21
	v_cvt_pk_bf16_f32 v21, v22, v23
	global_store_dwordx2 v158, v[28:29], s[24:25]
	global_store_dwordx2 v158, v[16:17], s[24:25] offset:32
	global_store_dwordx2 v158, v[24:25], s[24:25] offset:64
	global_store_dwordx2 v158, v[20:21], s[24:25] offset:96
	v_add_u32_e32 v158, 344064, v131
	v_cvt_pk_bf16_f32 v12, v12, v13
	v_cvt_pk_bf16_f32 v13, v14, v15
	v_cvt_pk_bf16_f32 v0, v0, v1
	v_cvt_pk_bf16_f32 v1, v2, v3
	v_cvt_pk_bf16_f32 v8, v8, v9
	v_cvt_pk_bf16_f32 v9, v10, v11
	v_cvt_pk_bf16_f32 v4, v4, v5
	v_cvt_pk_bf16_f32 v5, v6, v7
	global_store_dwordx2 v158, v[12:13], s[24:25]
	global_store_dwordx2 v158, v[0:1], s[24:25] offset:32
	global_store_dwordx2 v158, v[8:9], s[24:25] offset:64
	global_store_dwordx2 v158, v[4:5], s[24:25] offset:96
	s_branch .Lq_epi_done

.LBB0_906:
	s_and_b64 vcc, exec, s[0:1]
	s_cbranch_vccz .LBB0_803
	v_and_b32_e32 v2, 64, v192
	v_add_u32_e32 v2, 64, v2
	v_xor_b32_e32 v3, 32, v192
	v_cmp_lt_i32_e32 vcc, v3, v2
	v_mov_b32_e32 v128, v167
	s_ashr_i32 s8, s20, 3
	v_cndmask_b32_e32 v3, v192, v3, vcc
	v_lshlrev_b32_e32 v33, 2, v3
	v_xor_b32_e32 v3, 16, v192
	v_cmp_lt_i32_e32 vcc, v3, v2
	s_lshl_b32 s9, s8, 8
	v_and_b32_e32 v0, 63, v128
	v_cndmask_b32_e32 v3, v192, v3, vcc
	v_lshlrev_b32_e32 v34, 2, v3
	v_xor_b32_e32 v3, 8, v192
	v_cmp_lt_i32_e32 vcc, v3, v2
	v_ashrrev_i32_e32 v1, 6, v128
	v_readlane_b32 s1, v254, 47
	v_cndmask_b32_e32 v3, v192, v3, vcc
	v_lshlrev_b32_e32 v35, 2, v3
	v_xor_b32_e32 v3, 4, v192
	v_cmp_lt_i32_e32 vcc, v3, v2
	v_lshlrev_b32_e32 v164, 3, v0
	v_lshl_add_u32 v32, v1, 5, s9
	v_cndmask_b32_e32 v3, v192, v3, vcc
	v_lshlrev_b32_e32 v36, 2, v3
	v_xor_b32_e32 v3, 2, v192
	v_cmp_lt_i32_e32 vcc, v3, v2
	s_mov_b32 s0, 0
	v_cmp_eq_u32_e64 s[10:11], 0, v0
	v_cndmask_b32_e32 v3, v192, v3, vcc
	v_lshlrev_b32_e32 v37, 2, v3
	v_xor_b32_e32 v3, 1, v192
	v_cmp_lt_i32_e32 vcc, v3, v2
	v_lshl_add_u32 v39, v1, 7, s1
	v_lshl_add_u64 v[0:1], s[22:23], 0, v[164:165]
	v_cndmask_b32_e32 v2, v192, v3, vcc
	v_lshlrev_b32_e32 v38, 2, v2
	s_mov_b64 s[2:3], -1
	v_lshlrev_b32_e32 v80, 4, v167
	v_and_b32_e32 v81, 32, v167
	v_and_b32_e32 v82, 48, v80
	v_xor_b32_e32 v81, v81, v82
	v_lshrrev_b32_e32 v81, 1, v81
	v_lshrrev_b32_e32 v82, 1, v167
	v_and_b32_e32 v82, 32, v82
	v_or_b32_e32 v81, v81, v82
	v_and_b32_e32 v97, 0xfffffc00, v80
	v_lshrrev_b32_e32 v82, 2, v167
	v_and_b32_e32 v82, 15, v82
	v_lshrrev_b32_e32 v83, 3, v167
	v_and_b32_e32 v84, -16, v83
	v_or_b32_e32 v85, v84, v82
	v_add_u32_e32 v84, 64, v83
	v_and_b32_e32 v84, -16, v84
	v_or_b32_e32 v86, v84, v82
	v_add_u32_e32 v84, 128, v83
	v_and_b32_e32 v84, -16, v84
	v_or_b32_e32 v87, v84, v82
	v_add_u32_e32 v84, 192, v83
	v_and_b32_e32 v84, -16, v84
	v_or_b32_e32 v88, v84, v82
	v_mul_u32_u24_e32 v89, 0xb80, v85
	v_add_lshl_u32 v89, v89, v81, 1
	v_mul_u32_u24_e32 v90, 0xb80, v86
	v_add_lshl_u32 v90, v90, v81, 1
	v_mul_u32_u24_e32 v91, 0xb80, v87
	v_add_lshl_u32 v91, v91, v81, 1
	v_mul_u32_u24_e32 v92, 0xb80, v88
	v_add_lshl_u32 v92, v92, v81, 1
	v_lshl_or_b32 v93, v85, 8, v81
	v_lshlrev_b32_e32 v93, 1, v93
	v_lshl_or_b32 v94, v86, 8, v81
	v_lshlrev_b32_e32 v94, 1, v94
	v_lshl_or_b32 v95, v87, 8, v81
	v_lshlrev_b32_e32 v95, 1, v95
	v_lshl_or_b32 v96, v88, 8, v81
	v_lshlrev_b32_e32 v96, 1, v96
	s_nop 1
	v_readfirstlane_b32 s2, v97
	s_mul_i32 s0, s9, 0x1700
	s_mul_hi_i32 s1, s9, 0x1700
	s_add_u32 s0, s22, s0
	s_addc_u32 s1, s23, s1
	s_add_u32 s0, s0, 0x400
	s_addc_u32 s1, s1, 0
	s_mov_b32 m0, s2
	s_nop 0
	global_load_lds_dwordx4 v89, s[0:1]
	s_add_u32 s24, s2, 8192
	s_mov_b32 m0, s24
	s_nop 0
	global_load_lds_dwordx4 v90, s[0:1]
	s_add_u32 s24, s2, 16384
	s_mov_b32 m0, s24
	s_nop 0
	global_load_lds_dwordx4 v91, s[0:1]
	s_add_u32 s24, s2, 24576
	s_mov_b32 m0, s24
	s_nop 0
	global_load_lds_dwordx4 v92, s[0:1]
	s_and_b32 s0, s20, 7
	s_lshl_b32 s0, s0, 17
	s_add_u32 s0, s14, s0
	s_addc_u32 s1, s15, 0
	s_add_u32 s24, s2, 32768
	s_mov_b32 m0, s24
	s_nop 0
	global_load_lds_dwordx4 v93, s[0:1]
	s_add_u32 s24, s2, 40960
	s_mov_b32 m0, s24
	s_nop 0
	global_load_lds_dwordx4 v94, s[0:1]
	s_add_u32 s24, s2, 49152
	s_mov_b32 m0, s24
	s_nop 0
	global_load_lds_dwordx4 v95, s[0:1]
	s_add_u32 s24, s2, 57344
	s_mov_b32 m0, s24
	s_nop 0
	global_load_lds_dwordx4 v96, s[0:1]
	v_readfirstlane_b32 s0, v167
	v_and_b32_e32 v116, 63, v167
	v_and_b32_e32 v118, 15, v167
	s_lshr_b32 s0, s0, 6
	s_lshl_b32 s1, s0, 5
	s_add_u32 s2, s9, s1
	s_mul_i32 s2, s2, 0x1700
	s_add_u32 s2, s2, 0x400
	s_add_u32 s24, s22, s2
	s_addc_u32 s25, s23, 0
	v_lshlrev_b32_e32 v116, 3, v116
	v_and_b32_e32 v117, 48, v167
	s_lshl_b32 s1, s0, 7
	v_add_u32_e32 v117, s1, v117
	v_add_u32_e32 v117, 0x20000, v117
	global_load_dwordx2 v[16:17], v116, s[24:25]
	s_add_u32 s24, s24, 0x1700
	s_addc_u32 s25, s25, 0
	global_load_dwordx2 v[18:19], v116, s[24:25]
	s_add_u32 s24, s24, 0x1700
	s_addc_u32 s25, s25, 0
	global_load_dwordx2 v[20:21], v116, s[24:25]
	s_add_u32 s24, s24, 0x1700
	s_addc_u32 s25, s25, 0
	global_load_dwordx2 v[22:23], v116, s[24:25]
	s_add_u32 s24, s24, 0x1700
	s_addc_u32 s25, s25, 0
	global_load_dwordx2 v[24:25], v116, s[24:25]
	s_add_u32 s24, s24, 0x1700
	s_addc_u32 s25, s25, 0
	global_load_dwordx2 v[26:27], v116, s[24:25]
	s_add_u32 s24, s24, 0x1700
	s_addc_u32 s25, s25, 0
	global_load_dwordx2 v[28:29], v116, s[24:25]
	s_add_u32 s24, s24, 0x1700
	s_addc_u32 s25, s25, 0
	global_load_dwordx2 v[30:31], v116, s[24:25]
	s_add_u32 s24, s24, 0x1700
	s_addc_u32 s25, s25, 0
	global_load_dwordx2 v[32:33], v116, s[24:25]
	s_add_u32 s24, s24, 0x1700
	s_addc_u32 s25, s25, 0
	global_load_dwordx2 v[34:35], v116, s[24:25]
	s_add_u32 s24, s24, 0x1700
	s_addc_u32 s25, s25, 0
	global_load_dwordx2 v[36:37], v116, s[24:25]
	s_add_u32 s24, s24, 0x1700
	s_addc_u32 s25, s25, 0
	global_load_dwordx2 v[38:39], v116, s[24:25]
	s_add_u32 s24, s24, 0x1700
	s_addc_u32 s25, s25, 0
	global_load_dwordx2 v[40:41], v116, s[24:25]
	s_add_u32 s24, s24, 0x1700
	s_addc_u32 s25, s25, 0
	global_load_dwordx2 v[42:43], v116, s[24:25]
	s_add_u32 s24, s24, 0x1700
	s_addc_u32 s25, s25, 0
	global_load_dwordx2 v[44:45], v116, s[24:25]
	s_add_u32 s24, s24, 0x1700
	s_addc_u32 s25, s25, 0
	global_load_dwordx2 v[46:47], v116, s[24:25]
	s_add_u32 s24, s24, 0x1700
	s_addc_u32 s25, s25, 0
	s_waitcnt vmcnt(15)
	v_lshlrev_b32_e32 v112, 16, v16
	v_and_b32_e32 v16, 0xffff0000, v16
	v_mul_f32_e32 v16, v16, v16
	v_lshlrev_b32_e32 v113, 16, v17
	v_fmac_f32_e32 v16, v112, v112
	v_and_b32_e32 v17, 0xffff0000, v17
	v_fmac_f32_e32 v16, v113, v113
	v_fmac_f32_e32 v16, v17, v17
	s_waitcnt vmcnt(14)
	v_lshlrev_b32_e32 v112, 16, v18
	v_and_b32_e32 v18, 0xffff0000, v18
	v_mul_f32_e32 v18, v18, v18
	v_lshlrev_b32_e32 v113, 16, v19
	v_fmac_f32_e32 v18, v112, v112
	v_and_b32_e32 v19, 0xffff0000, v19
	v_fmac_f32_e32 v18, v113, v113
	v_fmac_f32_e32 v18, v19, v19
	s_waitcnt vmcnt(13)
	v_lshlrev_b32_e32 v112, 16, v20
	v_and_b32_e32 v20, 0xffff0000, v20
	v_mul_f32_e32 v20, v20, v20
	v_lshlrev_b32_e32 v113, 16, v21
	v_fmac_f32_e32 v20, v112, v112
	v_and_b32_e32 v21, 0xffff0000, v21
	v_fmac_f32_e32 v20, v113, v113
	v_fmac_f32_e32 v20, v21, v21
	s_waitcnt vmcnt(12)
	v_lshlrev_b32_e32 v112, 16, v22
	v_and_b32_e32 v22, 0xffff0000, v22
	v_mul_f32_e32 v22, v22, v22
	v_lshlrev_b32_e32 v113, 16, v23
	v_fmac_f32_e32 v22, v112, v112
	v_and_b32_e32 v23, 0xffff0000, v23
	v_fmac_f32_e32 v22, v113, v113
	v_fmac_f32_e32 v22, v23, v23
	s_waitcnt vmcnt(11)
	v_lshlrev_b32_e32 v112, 16, v24
	v_and_b32_e32 v24, 0xffff0000, v24
	v_mul_f32_e32 v24, v24, v24
	v_lshlrev_b32_e32 v113, 16, v25
	v_fmac_f32_e32 v24, v112, v112
	v_and_b32_e32 v25, 0xffff0000, v25
	v_fmac_f32_e32 v24, v113, v113
	v_fmac_f32_e32 v24, v25, v25
	s_waitcnt vmcnt(10)
	v_lshlrev_b32_e32 v112, 16, v26
	v_and_b32_e32 v26, 0xffff0000, v26
	v_mul_f32_e32 v26, v26, v26
	v_lshlrev_b32_e32 v113, 16, v27
	v_fmac_f32_e32 v26, v112, v112
	v_and_b32_e32 v27, 0xffff0000, v27
	v_fmac_f32_e32 v26, v113, v113
	v_fmac_f32_e32 v26, v27, v27
	s_waitcnt vmcnt(9)
	v_lshlrev_b32_e32 v112, 16, v28
	v_and_b32_e32 v28, 0xffff0000, v28
	v_mul_f32_e32 v28, v28, v28
	v_lshlrev_b32_e32 v113, 16, v29
	v_fmac_f32_e32 v28, v112, v112
	v_and_b32_e32 v29, 0xffff0000, v29
	v_fmac_f32_e32 v28, v113, v113
	v_fmac_f32_e32 v28, v29, v29
	s_waitcnt vmcnt(8)
	v_lshlrev_b32_e32 v112, 16, v30
	v_and_b32_e32 v30, 0xffff0000, v30
	v_mul_f32_e32 v30, v30, v30
	v_lshlrev_b32_e32 v113, 16, v31
	v_fmac_f32_e32 v30, v112, v112
	v_and_b32_e32 v31, 0xffff0000, v31
	v_fmac_f32_e32 v30, v113, v113
	v_fmac_f32_e32 v30, v31, v31
	s_waitcnt vmcnt(7)
	v_lshlrev_b32_e32 v112, 16, v32
	v_and_b32_e32 v32, 0xffff0000, v32
	v_mul_f32_e32 v32, v32, v32
	v_lshlrev_b32_e32 v113, 16, v33
	v_fmac_f32_e32 v32, v112, v112
	v_and_b32_e32 v33, 0xffff0000, v33
	v_fmac_f32_e32 v32, v113, v113
	v_fmac_f32_e32 v32, v33, v33
	s_waitcnt vmcnt(6)
	v_lshlrev_b32_e32 v112, 16, v34
	v_and_b32_e32 v34, 0xffff0000, v34
	v_mul_f32_e32 v34, v34, v34
	v_lshlrev_b32_e32 v113, 16, v35
	v_fmac_f32_e32 v34, v112, v112
	v_and_b32_e32 v35, 0xffff0000, v35
	v_fmac_f32_e32 v34, v113, v113
	v_fmac_f32_e32 v34, v35, v35
	s_waitcnt vmcnt(5)
	v_lshlrev_b32_e32 v112, 16, v36
	v_and_b32_e32 v36, 0xffff0000, v36
	v_mul_f32_e32 v36, v36, v36
	v_lshlrev_b32_e32 v113, 16, v37
	v_fmac_f32_e32 v36, v112, v112
	v_and_b32_e32 v37, 0xffff0000, v37
	v_fmac_f32_e32 v36, v113, v113
	v_fmac_f32_e32 v36, v37, v37
	s_waitcnt vmcnt(4)
	v_lshlrev_b32_e32 v112, 16, v38
	v_and_b32_e32 v38, 0xffff0000, v38
	v_mul_f32_e32 v38, v38, v38
	v_lshlrev_b32_e32 v113, 16, v39
	v_fmac_f32_e32 v38, v112, v112
	v_and_b32_e32 v39, 0xffff0000, v39
	v_fmac_f32_e32 v38, v113, v113
	v_fmac_f32_e32 v38, v39, v39
	s_waitcnt vmcnt(3)
	v_lshlrev_b32_e32 v112, 16, v40
	v_and_b32_e32 v40, 0xffff0000, v40
	v_mul_f32_e32 v40, v40, v40
	v_lshlrev_b32_e32 v113, 16, v41
	v_fmac_f32_e32 v40, v112, v112
	v_and_b32_e32 v41, 0xffff0000, v41
	v_fmac_f32_e32 v40, v113, v113
	v_fmac_f32_e32 v40, v41, v41
	s_waitcnt vmcnt(2)
	v_lshlrev_b32_e32 v112, 16, v42
	v_and_b32_e32 v42, 0xffff0000, v42
	v_mul_f32_e32 v42, v42, v42
	v_lshlrev_b32_e32 v113, 16, v43
	v_fmac_f32_e32 v42, v112, v112
	v_and_b32_e32 v43, 0xffff0000, v43
	v_fmac_f32_e32 v42, v113, v113
	v_fmac_f32_e32 v42, v43, v43
	s_waitcnt vmcnt(1)
	v_lshlrev_b32_e32 v112, 16, v44
	v_and_b32_e32 v44, 0xffff0000, v44
	v_mul_f32_e32 v44, v44, v44
	v_lshlrev_b32_e32 v113, 16, v45
	v_fmac_f32_e32 v44, v112, v112
	v_and_b32_e32 v45, 0xffff0000, v45
	v_fmac_f32_e32 v44, v113, v113
	v_fmac_f32_e32 v44, v45, v45
	s_waitcnt vmcnt(0)
	v_lshlrev_b32_e32 v112, 16, v46
	v_and_b32_e32 v46, 0xffff0000, v46
	v_mul_f32_e32 v46, v46, v46
	v_lshlrev_b32_e32 v113, 16, v47
	v_fmac_f32_e32 v46, v112, v112
	v_and_b32_e32 v47, 0xffff0000, v47
	v_fmac_f32_e32 v46, v113, v113
	v_fmac_f32_e32 v46, v47, v47
	s_nop 1
	v_permlane32_swap_b32_e32 v16, v32
	v_permlane32_swap_b32_e32 v18, v34
	v_permlane32_swap_b32_e32 v20, v36
	v_permlane32_swap_b32_e32 v22, v38
	v_permlane32_swap_b32_e32 v24, v40
	v_permlane32_swap_b32_e32 v26, v42
	v_permlane32_swap_b32_e32 v28, v44
	v_permlane32_swap_b32_e32 v30, v46
	s_nop 0
	v_add_f32_e32 v16, v16, v32
	v_add_f32_e32 v18, v18, v34
	v_add_f32_e32 v20, v20, v36
	v_add_f32_e32 v22, v22, v38
	v_add_f32_e32 v24, v24, v40
	v_add_f32_e32 v26, v26, v42
	v_add_f32_e32 v28, v28, v44
	v_add_f32_e32 v30, v30, v46
	s_nop 1
	v_permlane16_swap_b32_e32 v16, v24
	v_permlane16_swap_b32_e32 v18, v26
	v_permlane16_swap_b32_e32 v20, v28
	v_permlane16_swap_b32_e32 v22, v30
	s_nop 0
	v_add_f32_e32 v16, v16, v24
	v_add_f32_e32 v18, v18, v26
	v_add_f32_e32 v20, v20, v28
	v_add_f32_e32 v22, v22, v30
	s_nop 1
	v_add_f32_dpp v16, v16, v16 row_ror:8 row_mask:0xf bank_mask:0xf
	v_add_f32_dpp v18, v18, v18 row_ror:8 row_mask:0xf bank_mask:0xf
	v_add_f32_dpp v20, v20, v20 row_ror:8 row_mask:0xf bank_mask:0xf
	v_add_f32_dpp v22, v22, v22 row_ror:8 row_mask:0xf bank_mask:0xf
	s_nop 1
	v_add_f32_dpp v16, v16, v16 row_ror:4 row_mask:0xf bank_mask:0xf
	v_add_f32_dpp v18, v18, v18 row_ror:4 row_mask:0xf bank_mask:0xf
	v_add_f32_dpp v20, v20, v20 row_ror:4 row_mask:0xf bank_mask:0xf
	v_add_f32_dpp v22, v22, v22 row_ror:4 row_mask:0xf bank_mask:0xf
	s_nop 1
	v_add_f32_dpp v16, v16, v16 row_ror:2 row_mask:0xf bank_mask:0xf
	v_add_f32_dpp v18, v18, v18 row_ror:2 row_mask:0xf bank_mask:0xf
	v_add_f32_dpp v20, v20, v20 row_ror:2 row_mask:0xf bank_mask:0xf
	v_add_f32_dpp v22, v22, v22 row_ror:2 row_mask:0xf bank_mask:0xf
	s_nop 1
	v_add_f32_dpp v16, v16, v16 row_ror:1 row_mask:0xf bank_mask:0xf
	v_add_f32_dpp v18, v18, v18 row_ror:1 row_mask:0xf bank_mask:0xf
	v_add_f32_dpp v20, v20, v20 row_ror:1 row_mask:0xf bank_mask:0xf
	v_add_f32_dpp v22, v22, v22 row_ror:1 row_mask:0xf bank_mask:0xf
	v_fmamk_f32 v16, v16, 0x3b800000, v166
	v_fmamk_f32 v18, v18, 0x3b800000, v166
	v_fmamk_f32 v20, v20, 0x3b800000, v166
	v_fmamk_f32 v22, v22, 0x3b800000, v166
	v_mul_f32_e32 v112, 0x4b800000, v16
	v_cmp_gt_f32_e32 vcc, s58, v16
	s_nop 1
	v_cndmask_b32_e32 v16, v16, v112, vcc
	v_rsq_f32_e32 v16, v16
	s_nop 0
	v_mul_f32_e32 v112, 0x45800000, v16
	v_cndmask_b32_e32 v16, v16, v112, vcc
	v_mul_f32_e32 v112, 0x4b800000, v18
	v_cmp_gt_f32_e32 vcc, s58, v18
	s_nop 1
	v_cndmask_b32_e32 v18, v18, v112, vcc
	v_rsq_f32_e32 v18, v18
	s_nop 0
	v_mul_f32_e32 v112, 0x45800000, v18
	v_cndmask_b32_e32 v18, v18, v112, vcc
	v_mul_f32_e32 v112, 0x4b800000, v20
	v_cmp_gt_f32_e32 vcc, s58, v20
	s_nop 1
	v_cndmask_b32_e32 v20, v20, v112, vcc
	v_rsq_f32_e32 v20, v20
	s_nop 0
	v_mul_f32_e32 v112, 0x45800000, v20
	v_cndmask_b32_e32 v20, v20, v112, vcc
	v_mul_f32_e32 v112, 0x4b800000, v22
	v_cmp_gt_f32_e32 vcc, s58, v22
	s_nop 1
	v_cndmask_b32_e32 v22, v22, v112, vcc
	v_rsq_f32_e32 v22, v22
	s_nop 0
	v_mul_f32_e32 v112, 0x45800000, v22
	v_cndmask_b32_e32 v22, v22, v112, vcc
	v_mov_b32_e32 v112, v16
	v_mov_b32_e32 v113, v18
	v_mov_b32_e32 v114, v20
	v_mov_b32_e32 v115, v22
	v_cmp_eq_u32_e32 vcc, 0, v118
	s_and_saveexec_b64 s[0:1], vcc
	ds_write_b128 v117, v[112:115]
	s_or_b64 exec, exec, s[0:1]
	global_load_dwordx2 v[16:17], v116, s[24:25]
	s_add_u32 s24, s24, 0x1700
	s_addc_u32 s25, s25, 0
	global_load_dwordx2 v[18:19], v116, s[24:25]
	s_add_u32 s24, s24, 0x1700
	s_addc_u32 s25, s25, 0
	global_load_dwordx2 v[20:21], v116, s[24:25]
	s_add_u32 s24, s24, 0x1700
	s_addc_u32 s25, s25, 0
	global_load_dwordx2 v[22:23], v116, s[24:25]
	s_add_u32 s24, s24, 0x1700
	s_addc_u32 s25, s25, 0
	global_load_dwordx2 v[24:25], v116, s[24:25]
	s_add_u32 s24, s24, 0x1700
	s_addc_u32 s25, s25, 0
	global_load_dwordx2 v[26:27], v116, s[24:25]
	s_add_u32 s24, s24, 0x1700
	s_addc_u32 s25, s25, 0
	global_load_dwordx2 v[28:29], v116, s[24:25]
	s_add_u32 s24, s24, 0x1700
	s_addc_u32 s25, s25, 0
	global_load_dwordx2 v[30:31], v116, s[24:25]
	s_add_u32 s24, s24, 0x1700
	s_addc_u32 s25, s25, 0
	global_load_dwordx2 v[32:33], v116, s[24:25]
	s_add_u32 s24, s24, 0x1700
	s_addc_u32 s25, s25, 0
	global_load_dwordx2 v[34:35], v116, s[24:25]
	s_add_u32 s24, s24, 0x1700
	s_addc_u32 s25, s25, 0
	global_load_dwordx2 v[36:37], v116, s[24:25]
	s_add_u32 s24, s24, 0x1700
	s_addc_u32 s25, s25, 0
	global_load_dwordx2 v[38:39], v116, s[24:25]
	s_add_u32 s24, s24, 0x1700
	s_addc_u32 s25, s25, 0
	global_load_dwordx2 v[40:41], v116, s[24:25]
	s_add_u32 s24, s24, 0x1700
	s_addc_u32 s25, s25, 0
	global_load_dwordx2 v[42:43], v116, s[24:25]
	s_add_u32 s24, s24, 0x1700
	s_addc_u32 s25, s25, 0
	global_load_dwordx2 v[44:45], v116, s[24:25]
	s_add_u32 s24, s24, 0x1700
	s_addc_u32 s25, s25, 0
	global_load_dwordx2 v[46:47], v116, s[24:25]
	s_add_u32 s24, s24, 0x1700
	s_addc_u32 s25, s25, 0
	s_waitcnt vmcnt(15)
	v_lshlrev_b32_e32 v112, 16, v16
	v_and_b32_e32 v16, 0xffff0000, v16
	v_mul_f32_e32 v16, v16, v16
	v_lshlrev_b32_e32 v113, 16, v17
	v_fmac_f32_e32 v16, v112, v112
	v_and_b32_e32 v17, 0xffff0000, v17
	v_fmac_f32_e32 v16, v113, v113
	v_fmac_f32_e32 v16, v17, v17
	s_waitcnt vmcnt(14)
	v_lshlrev_b32_e32 v112, 16, v18
	v_and_b32_e32 v18, 0xffff0000, v18
	v_mul_f32_e32 v18, v18, v18
	v_lshlrev_b32_e32 v113, 16, v19
	v_fmac_f32_e32 v18, v112, v112
	v_and_b32_e32 v19, 0xffff0000, v19
	v_fmac_f32_e32 v18, v113, v113
	v_fmac_f32_e32 v18, v19, v19
	s_waitcnt vmcnt(13)
	v_lshlrev_b32_e32 v112, 16, v20
	v_and_b32_e32 v20, 0xffff0000, v20
	v_mul_f32_e32 v20, v20, v20
	v_lshlrev_b32_e32 v113, 16, v21
	v_fmac_f32_e32 v20, v112, v112
	v_and_b32_e32 v21, 0xffff0000, v21
	v_fmac_f32_e32 v20, v113, v113
	v_fmac_f32_e32 v20, v21, v21
	s_waitcnt vmcnt(12)
	v_lshlrev_b32_e32 v112, 16, v22
	v_and_b32_e32 v22, 0xffff0000, v22
	v_mul_f32_e32 v22, v22, v22
	v_lshlrev_b32_e32 v113, 16, v23
	v_fmac_f32_e32 v22, v112, v112
	v_and_b32_e32 v23, 0xffff0000, v23
	v_fmac_f32_e32 v22, v113, v113
	v_fmac_f32_e32 v22, v23, v23
	s_waitcnt vmcnt(11)
	v_lshlrev_b32_e32 v112, 16, v24
	v_and_b32_e32 v24, 0xffff0000, v24
	v_mul_f32_e32 v24, v24, v24
	v_lshlrev_b32_e32 v113, 16, v25
	v_fmac_f32_e32 v24, v112, v112
	v_and_b32_e32 v25, 0xffff0000, v25
	v_fmac_f32_e32 v24, v113, v113
	v_fmac_f32_e32 v24, v25, v25
	s_waitcnt vmcnt(10)
	v_lshlrev_b32_e32 v112, 16, v26
	v_and_b32_e32 v26, 0xffff0000, v26
	v_mul_f32_e32 v26, v26, v26
	v_lshlrev_b32_e32 v113, 16, v27
	v_fmac_f32_e32 v26, v112, v112
	v_and_b32_e32 v27, 0xffff0000, v27
	v_fmac_f32_e32 v26, v113, v113
	v_fmac_f32_e32 v26, v27, v27
	s_waitcnt vmcnt(9)
	v_lshlrev_b32_e32 v112, 16, v28
	v_and_b32_e32 v28, 0xffff0000, v28
	v_mul_f32_e32 v28, v28, v28
	v_lshlrev_b32_e32 v113, 16, v29
	v_fmac_f32_e32 v28, v112, v112
	v_and_b32_e32 v29, 0xffff0000, v29
	v_fmac_f32_e32 v28, v113, v113
	v_fmac_f32_e32 v28, v29, v29
	s_waitcnt vmcnt(8)
	v_lshlrev_b32_e32 v112, 16, v30
	v_and_b32_e32 v30, 0xffff0000, v30
	v_mul_f32_e32 v30, v30, v30
	v_lshlrev_b32_e32 v113, 16, v31
	v_fmac_f32_e32 v30, v112, v112
	v_and_b32_e32 v31, 0xffff0000, v31
	v_fmac_f32_e32 v30, v113, v113
	v_fmac_f32_e32 v30, v31, v31
	s_waitcnt vmcnt(7)
	v_lshlrev_b32_e32 v112, 16, v32
	v_and_b32_e32 v32, 0xffff0000, v32
	v_mul_f32_e32 v32, v32, v32
	v_lshlrev_b32_e32 v113, 16, v33
	v_fmac_f32_e32 v32, v112, v112
	v_and_b32_e32 v33, 0xffff0000, v33
	v_fmac_f32_e32 v32, v113, v113
	v_fmac_f32_e32 v32, v33, v33
	s_waitcnt vmcnt(6)
	v_lshlrev_b32_e32 v112, 16, v34
	v_and_b32_e32 v34, 0xffff0000, v34
	v_mul_f32_e32 v34, v34, v34
	v_lshlrev_b32_e32 v113, 16, v35
	v_fmac_f32_e32 v34, v112, v112
	v_and_b32_e32 v35, 0xffff0000, v35
	v_fmac_f32_e32 v34, v113, v113
	v_fmac_f32_e32 v34, v35, v35
	s_waitcnt vmcnt(5)
	v_lshlrev_b32_e32 v112, 16, v36
	v_and_b32_e32 v36, 0xffff0000, v36
	v_mul_f32_e32 v36, v36, v36
	v_lshlrev_b32_e32 v113, 16, v37
	v_fmac_f32_e32 v36, v112, v112
	v_and_b32_e32 v37, 0xffff0000, v37
	v_fmac_f32_e32 v36, v113, v113
	v_fmac_f32_e32 v36, v37, v37
	s_waitcnt vmcnt(4)
	v_lshlrev_b32_e32 v112, 16, v38
	v_and_b32_e32 v38, 0xffff0000, v38
	v_mul_f32_e32 v38, v38, v38
	v_lshlrev_b32_e32 v113, 16, v39
	v_fmac_f32_e32 v38, v112, v112
	v_and_b32_e32 v39, 0xffff0000, v39
	v_fmac_f32_e32 v38, v113, v113
	v_fmac_f32_e32 v38, v39, v39
	s_waitcnt vmcnt(3)
	v_lshlrev_b32_e32 v112, 16, v40
	v_and_b32_e32 v40, 0xffff0000, v40
	v_mul_f32_e32 v40, v40, v40
	v_lshlrev_b32_e32 v113, 16, v41
	v_fmac_f32_e32 v40, v112, v112
	v_and_b32_e32 v41, 0xffff0000, v41
	v_fmac_f32_e32 v40, v113, v113
	v_fmac_f32_e32 v40, v41, v41
	s_waitcnt vmcnt(2)
	v_lshlrev_b32_e32 v112, 16, v42
	v_and_b32_e32 v42, 0xffff0000, v42
	v_mul_f32_e32 v42, v42, v42
	v_lshlrev_b32_e32 v113, 16, v43
	v_fmac_f32_e32 v42, v112, v112
	v_and_b32_e32 v43, 0xffff0000, v43
	v_fmac_f32_e32 v42, v113, v113
	v_fmac_f32_e32 v42, v43, v43
	s_waitcnt vmcnt(1)
	v_lshlrev_b32_e32 v112, 16, v44
	v_and_b32_e32 v44, 0xffff0000, v44
	v_mul_f32_e32 v44, v44, v44
	v_lshlrev_b32_e32 v113, 16, v45
	v_fmac_f32_e32 v44, v112, v112
	v_and_b32_e32 v45, 0xffff0000, v45
	v_fmac_f32_e32 v44, v113, v113
	v_fmac_f32_e32 v44, v45, v45
	s_waitcnt vmcnt(0)
	v_lshlrev_b32_e32 v112, 16, v46
	v_and_b32_e32 v46, 0xffff0000, v46
	v_mul_f32_e32 v46, v46, v46
	v_lshlrev_b32_e32 v113, 16, v47
	v_fmac_f32_e32 v46, v112, v112
	v_and_b32_e32 v47, 0xffff0000, v47
	v_fmac_f32_e32 v46, v113, v113
	v_fmac_f32_e32 v46, v47, v47
	s_nop 1
	v_permlane32_swap_b32_e32 v16, v32
	v_permlane32_swap_b32_e32 v18, v34
	v_permlane32_swap_b32_e32 v20, v36
	v_permlane32_swap_b32_e32 v22, v38
	v_permlane32_swap_b32_e32 v24, v40
	v_permlane32_swap_b32_e32 v26, v42
	v_permlane32_swap_b32_e32 v28, v44
	v_permlane32_swap_b32_e32 v30, v46
	s_nop 0
	v_add_f32_e32 v16, v16, v32
	v_add_f32_e32 v18, v18, v34
	v_add_f32_e32 v20, v20, v36
	v_add_f32_e32 v22, v22, v38
	v_add_f32_e32 v24, v24, v40
	v_add_f32_e32 v26, v26, v42
	v_add_f32_e32 v28, v28, v44
	v_add_f32_e32 v30, v30, v46
	s_nop 1
	v_permlane16_swap_b32_e32 v16, v24
	v_permlane16_swap_b32_e32 v18, v26
	v_permlane16_swap_b32_e32 v20, v28
	v_permlane16_swap_b32_e32 v22, v30
	s_nop 0
	v_add_f32_e32 v16, v16, v24
	v_add_f32_e32 v18, v18, v26
	v_add_f32_e32 v20, v20, v28
	v_add_f32_e32 v22, v22, v30
	s_nop 1
	v_add_f32_dpp v16, v16, v16 row_ror:8 row_mask:0xf bank_mask:0xf
	v_add_f32_dpp v18, v18, v18 row_ror:8 row_mask:0xf bank_mask:0xf
	v_add_f32_dpp v20, v20, v20 row_ror:8 row_mask:0xf bank_mask:0xf
	v_add_f32_dpp v22, v22, v22 row_ror:8 row_mask:0xf bank_mask:0xf
	s_nop 1
	v_add_f32_dpp v16, v16, v16 row_ror:4 row_mask:0xf bank_mask:0xf
	v_add_f32_dpp v18, v18, v18 row_ror:4 row_mask:0xf bank_mask:0xf
	v_add_f32_dpp v20, v20, v20 row_ror:4 row_mask:0xf bank_mask:0xf
	v_add_f32_dpp v22, v22, v22 row_ror:4 row_mask:0xf bank_mask:0xf
	s_nop 1
	v_add_f32_dpp v16, v16, v16 row_ror:2 row_mask:0xf bank_mask:0xf
	v_add_f32_dpp v18, v18, v18 row_ror:2 row_mask:0xf bank_mask:0xf
	v_add_f32_dpp v20, v20, v20 row_ror:2 row_mask:0xf bank_mask:0xf
	v_add_f32_dpp v22, v22, v22 row_ror:2 row_mask:0xf bank_mask:0xf
	s_nop 1
	v_add_f32_dpp v16, v16, v16 row_ror:1 row_mask:0xf bank_mask:0xf
	v_add_f32_dpp v18, v18, v18 row_ror:1 row_mask:0xf bank_mask:0xf
	v_add_f32_dpp v20, v20, v20 row_ror:1 row_mask:0xf bank_mask:0xf
	v_add_f32_dpp v22, v22, v22 row_ror:1 row_mask:0xf bank_mask:0xf
	v_fmamk_f32 v16, v16, 0x3b800000, v166
	v_fmamk_f32 v18, v18, 0x3b800000, v166
	v_fmamk_f32 v20, v20, 0x3b800000, v166
	v_fmamk_f32 v22, v22, 0x3b800000, v166
	v_mul_f32_e32 v112, 0x4b800000, v16
	v_cmp_gt_f32_e32 vcc, s58, v16
	s_nop 1
	v_cndmask_b32_e32 v16, v16, v112, vcc
	v_rsq_f32_e32 v16, v16
	s_nop 0
	v_mul_f32_e32 v112, 0x45800000, v16
	v_cndmask_b32_e32 v16, v16, v112, vcc
	v_mul_f32_e32 v112, 0x4b800000, v18
	v_cmp_gt_f32_e32 vcc, s58, v18
	s_nop 1
	v_cndmask_b32_e32 v18, v18, v112, vcc
	v_rsq_f32_e32 v18, v18
	s_nop 0
	v_mul_f32_e32 v112, 0x45800000, v18
	v_cndmask_b32_e32 v18, v18, v112, vcc
	v_mul_f32_e32 v112, 0x4b800000, v20
	v_cmp_gt_f32_e32 vcc, s58, v20
	s_nop 1
	v_cndmask_b32_e32 v20, v20, v112, vcc
	v_rsq_f32_e32 v20, v20
	s_nop 0
	v_mul_f32_e32 v112, 0x45800000, v20
	v_cndmask_b32_e32 v20, v20, v112, vcc
	v_mul_f32_e32 v112, 0x4b800000, v22
	v_cmp_gt_f32_e32 vcc, s58, v22
	s_nop 1
	v_cndmask_b32_e32 v22, v22, v112, vcc
	v_rsq_f32_e32 v22, v22
	s_nop 0
	v_mul_f32_e32 v112, 0x45800000, v22
	v_cndmask_b32_e32 v22, v22, v112, vcc
	v_mov_b32_e32 v112, v16
	v_mov_b32_e32 v113, v18
	v_mov_b32_e32 v114, v20
	v_mov_b32_e32 v115, v22
	v_cmp_eq_u32_e32 vcc, 0, v118
	s_and_saveexec_b64 s[0:1], vcc
	ds_write_b128 v117, v[112:115] offset:64
	s_or_b64 exec, exec, s[0:1]
.LBB0_941:
	v_mov_b32_e32 v22, v167
	s_waitcnt lgkmcnt(0)
	s_barrier
	s_movk_i32 s11, 0xb80
	v_lshlrev_b32_e32 v1, 4, v22
	v_and_b32_e32 v0, 32, v22
	v_bitop3_b32 v0, v1, v0, 48 bitop3:0x6c
	v_lshrrev_b32_e32 v2, 1, v22
	v_lshrrev_b32_e32 v0, 1, v0
	v_lshrrev_b32_e32 v3, 2, v22
	v_and_or_b32 v5, v2, 32, v0
	v_ashrrev_i32_e32 v0, 3, v22
	v_and_b32_e32 v18, 0xfffffc00, v1
	v_bfi_b32 v2, 15, v3, v0
	v_add_u32_e32 v4, 0x2000, v1
	v_add_u32_e32 v7, 0x4000, v1
	v_add_u32_e32 v1, 0x6000, v1
	s_and_b32 s10, s20, 7
	s_mul_i32 s0, s9, 0x1700
	v_mul_lo_u32 v0, v2, s11
	v_ashrrev_i32_e32 v4, 7, v4
	v_ashrrev_i32_e32 v7, 7, v7
	v_ashrrev_i32_e32 v1, 7, v1
	s_mul_hi_i32 s1, s9, 0x1700
	s_add_u32 s0, s22, s0
	v_or_b32_e32 v0, v0, v5
	v_bfi_b32 v6, -16, v4, v3
	v_bfi_b32 v7, -16, v7, v3
	v_bfi_b32 v1, -16, v1, v3
	s_addc_u32 s1, s23, s1
	s_lshl_b32 s2, s10, 17
	v_mul_lo_u32 v4, v6, s11
	v_mul_lo_u32 v8, v7, s11
	v_mul_lo_u32 v3, v1, s11
	v_lshl_or_b32 v14, v1, 8, v5
	v_add_u32_e32 v19, 0, v18
	v_ashrrev_i32_e32 v1, 31, v0
	s_add_u32 s2, s14, s2
	v_lshl_or_b32 v2, v2, 8, v5
	v_or_b32_e32 v4, v4, v5
	v_lshl_or_b32 v6, v6, 8, v5
	v_or_b32_e32 v8, v8, v5
	v_lshl_or_b32 v10, v7, 8, v5
	v_or_b32_e32 v12, v3, v5
	v_add_u32_e32 v5, 0x8000, v19
	v_lshl_add_u64 v[0:1], v[0:1], 1, s[0:1]
	s_mov_b64 s[40:41], 0x400
	v_readfirstlane_b32 s26, v19
	s_addc_u32 s3, s15, 0
	v_lshl_add_u64 v[16:17], v[0:1], 0, s[40:41]
	s_mov_b32 m0, s26
	v_ashrrev_i32_e32 v3, 31, v2
	v_readfirstlane_b32 s25, v5
	v_ashrrev_i32_e32 v5, 31, v4
	v_add_u32_e32 v7, 0x2000, v19
	v_lshl_add_u64 v[2:3], v[2:3], 1, s[2:3]
	s_mov_b32 m0, s25
	v_lshl_add_u64 v[4:5], v[4:5], 1, s[0:1]
	v_readfirstlane_b32 s27, v7
	v_add_u32_e32 v9, 0xa000, v19
	v_lshl_add_u64 v[16:17], v[4:5], 0, s[40:41]
	s_mov_b32 m0, s27
	v_ashrrev_i32_e32 v7, 31, v6
	v_readfirstlane_b32 s34, v9
	v_ashrrev_i32_e32 v9, 31, v8
	v_add_u32_e32 v11, 0x4000, v19
	v_lshl_add_u64 v[6:7], v[6:7], 1, s[2:3]
	s_mov_b32 m0, s34
	v_lshl_add_u64 v[8:9], v[8:9], 1, s[0:1]
	v_readfirstlane_b32 s35, v11
	v_add_u32_e32 v13, 0xc000, v19
	v_lshl_add_u64 v[16:17], v[8:9], 0, s[40:41]
	s_mov_b32 m0, s35
	v_ashrrev_i32_e32 v11, 31, v10
	v_readfirstlane_b32 s36, v13
	v_ashrrev_i32_e32 v13, 31, v12
	v_add_u32_e32 v15, 0x6000, v19
	v_lshl_add_u64 v[10:11], v[10:11], 1, s[2:3]
	s_mov_b32 m0, s36
	v_lshl_add_u64 v[12:13], v[12:13], 1, s[0:1]
	v_readfirstlane_b32 s37, v15
	v_lshl_add_u64 v[16:17], v[12:13], 0, s[40:41]
	s_mov_b32 m0, s37
	v_ashrrev_i32_e32 v15, 31, v14
	v_add_u32_e32 v16, 0xe000, v19
	v_lshlrev_b32_e32 v19, 2, v22
	v_readfirstlane_b32 s40, v16
	v_and_b32_e32 v16, 15, v22
	v_and_b32_e32 v17, 48, v22
	v_lshlrev_b32_e32 v16, 6, v16
	v_and_b32_e32 v19, 32, v19
	v_bitop3_b32 v25, v16, v19, v17 bitop3:0x36
	v_lshlrev_b32_e32 v16, 6, v22
	v_and_b32_e32 v126, 0xffffc000, v16
	v_and_b32_e32 v16, 0x3c0, v16
	v_bitop3_b32 v129, v16, v19, v17 bitop3:0x36
	v_add_u32_e32 v19, s90, v18
	v_readlane_b32 s41, v254, 11
	v_lshl_add_u64 v[14:15], v[14:15], 1, s[2:3]
	s_mov_b32 m0, s40
	v_add_u32_e32 v18, s41, v18
	s_mov_b64 s[42:43], 0x480
	v_readfirstlane_b32 s3, v19
	v_lshl_add_u64 v[16:17], v[0:1], 0, s[42:43]
	s_mov_b32 m0, s3
	v_readfirstlane_b32 s0, v18
	v_add_u32_e32 v20, 0x2000, v19
	s_waitcnt vmcnt(0)
	s_waitcnt vmcnt(0) lgkmcnt(0)
	s_barrier
	global_load_lds_dwordx4 v[16:17], off
	v_lshl_add_u64 v[16:17], v[2:3], 0, s[96:97]
	s_mov_b32 m0, s0
	v_readfirstlane_b32 s1, v20
	v_add_u32_e32 v20, 0x2000, v18
	global_load_lds_dwordx4 v[16:17], off
	v_lshl_add_u64 v[16:17], v[4:5], 0, s[42:43]
	s_mov_b32 m0, s1
	v_readfirstlane_b32 s2, v20
	v_add_u32_e32 v20, 0x4000, v19
	global_load_lds_dwordx4 v[16:17], off
	v_lshl_add_u64 v[16:17], v[6:7], 0, s[96:97]
	s_mov_b32 m0, s2
	v_readfirstlane_b32 s11, v20
	v_add_u32_e32 v20, 0x4000, v18
	global_load_lds_dwordx4 v[16:17], off
	v_lshl_add_u64 v[16:17], v[8:9], 0, s[42:43]
	s_mov_b32 m0, s11
	v_readfirstlane_b32 s16, v20
	v_add_u32_e32 v19, 0x6000, v19
	global_load_lds_dwordx4 v[16:17], off
	v_lshl_add_u64 v[16:17], v[10:11], 0, s[96:97]
	s_mov_b32 m0, s16
	v_readfirstlane_b32 s21, v19
	v_add_u32_e32 v18, 0x6000, v18
	global_load_lds_dwordx4 v[16:17], off
	v_lshl_add_u64 v[16:17], v[12:13], 0, s[42:43]
	s_mov_b32 m0, s21
	v_readfirstlane_b32 s24, v18
	global_load_lds_dwordx4 v[16:17], off
	v_lshl_add_u64 v[16:17], v[14:15], 0, s[96:97]
	s_mov_b32 m0, s24
	v_or_b32_e32 v127, 0x800, v126
	global_load_lds_dwordx4 v[16:17], off
	v_add_u32_e32 v16, 0, v25
	v_add_u32_e32 v24, v16, v126
	ds_read_b128 v[18:21], v24
	v_lshlrev_b32_e32 v17, 7, v22
	v_and_b32_e32 v162, 0x6000, v17
	v_add_u32_e32 v17, 0, v129
	v_add_u32_e32 v23, v16, v162
	v_add_u32_e32 v16, v17, v127
	ds_read_b128 v[26:29], v23 offset:32768
	ds_read_b128 v[30:33], v16
	ds_read_b128 v[34:37], v23 offset:34816
	ds_read_b128 v[46:49], v23 offset:36864
	ds_read_b128 v[50:53], v23 offset:38912
	v_or_b32_e32 v163, 0x1000, v126
	v_or_b32_e32 v164, 0x1800, v126
	v_or_b32_e32 v180, 0x2000, v126
	v_or_b32_e32 v182, 0x2800, v126
	v_or_b32_e32 v183, 0x3000, v126
	v_or_b32_e32 v193, 0x3800, v126
	s_waitcnt lgkmcnt(0)
	v_mfma_f32_16x16x32_bf16 v[38:41], v[18:21], v[26:29], 0
	v_add_u32_e32 v22, v17, v163
	ds_read_b128 v[74:77], v22
	v_mfma_f32_16x16x32_bf16 v[42:45], v[18:21], v[34:37], 0
	v_mfma_f32_16x16x32_bf16 v[54:57], v[18:21], v[46:49], 0
	v_mfma_f32_16x16x32_bf16 v[58:61], v[18:21], v[50:53], 0
	v_add_u32_e32 v19, v17, v164
	v_add_u32_e32 v21, v17, v180
	v_add_u32_e32 v18, v17, v182
	v_add_u32_e32 v20, v17, v183
	v_add_u32_e32 v17, v17, v193
	ds_read_b128 v[78:81], v19
	ds_read_b128 v[142:145], v20
	ds_read_b128 v[106:109], v21
	ds_read_b128 v[110:113], v18
	ds_read_b128 v[146:149], v17
	v_mfma_f32_16x16x32_bf16 v[62:65], v[30:33], v[26:29], 0
	v_mfma_f32_16x16x32_bf16 v[66:69], v[30:33], v[34:37], 0
	v_mfma_f32_16x16x32_bf16 v[70:73], v[30:33], v[46:49], 0
	v_mfma_f32_16x16x32_bf16 v[30:33], v[30:33], v[50:53], 0
	s_waitcnt lgkmcnt(0)
	v_mfma_f32_16x16x32_bf16 v[82:85], v[74:77], v[26:29], 0
	v_mfma_f32_16x16x32_bf16 v[86:89], v[74:77], v[34:37], 0
	v_mfma_f32_16x16x32_bf16 v[90:93], v[74:77], v[46:49], 0
	v_mfma_f32_16x16x32_bf16 v[74:77], v[74:77], v[50:53], 0
	v_mfma_f32_16x16x32_bf16 v[94:97], v[78:81], v[26:29], 0
	v_mfma_f32_16x16x32_bf16 v[98:101], v[78:81], v[34:37], 0
	v_mfma_f32_16x16x32_bf16 v[102:105], v[78:81], v[46:49], 0
	v_mfma_f32_16x16x32_bf16 v[78:81], v[78:81], v[50:53], 0
	v_mfma_f32_16x16x32_bf16 v[114:117], v[106:109], v[26:29], 0
	v_mfma_f32_16x16x32_bf16 v[118:121], v[106:109], v[34:37], 0
	v_mfma_f32_16x16x32_bf16 v[122:125], v[106:109], v[46:49], 0
	v_mfma_f32_16x16x32_bf16 v[106:109], v[106:109], v[50:53], 0
	v_mfma_f32_16x16x32_bf16 v[130:133], v[110:113], v[26:29], 0
	v_mfma_f32_16x16x32_bf16 v[134:137], v[110:113], v[34:37], 0
	v_mfma_f32_16x16x32_bf16 v[138:141], v[110:113], v[46:49], 0
	v_mfma_f32_16x16x32_bf16 v[110:113], v[110:113], v[50:53], 0
	v_mfma_f32_16x16x32_bf16 v[150:153], v[142:145], v[26:29], 0
	v_mfma_f32_16x16x32_bf16 v[154:157], v[142:145], v[34:37], 0
	v_mfma_f32_16x16x32_bf16 v[158:161], v[142:145], v[46:49], 0
	v_mfma_f32_16x16x32_bf16 v[142:145], v[142:145], v[50:53], 0
	v_mfma_f32_16x16x32_bf16 v[26:29], v[146:149], v[26:29], 0
	v_mfma_f32_16x16x32_bf16 v[34:37], v[146:149], v[34:37], 0
	v_mfma_f32_16x16x32_bf16 v[46:49], v[146:149], v[46:49], 0
	v_mfma_f32_16x16x32_bf16 v[50:53], v[146:149], v[50:53], 0
	ds_read_b128 v[146:149], v24 offset:1024
	ds_read_b128 v[168:171], v23 offset:33792
	ds_read_b128 v[172:175], v23 offset:35840
	ds_read_b128 v[176:179], v23 offset:37888
	ds_read_b128 v[194:197], v23 offset:39936
	s_waitcnt lgkmcnt(0)
	v_mfma_f32_16x16x32_bf16 v[38:41], v[146:149], v[168:171], v[38:41]
	v_mfma_f32_16x16x32_bf16 v[42:45], v[146:149], v[172:175], v[42:45]
	v_mfma_f32_16x16x32_bf16 v[54:57], v[146:149], v[176:179], v[54:57]
	v_mfma_f32_16x16x32_bf16 v[58:61], v[146:149], v[194:197], v[58:61]
	ds_read_b128 v[146:149], v16 offset:1024
	s_waitcnt lgkmcnt(0)
	v_mfma_f32_16x16x32_bf16 v[62:65], v[146:149], v[168:171], v[62:65]
	v_mfma_f32_16x16x32_bf16 v[66:69], v[146:149], v[172:175], v[66:69]
	v_mfma_f32_16x16x32_bf16 v[70:73], v[146:149], v[176:179], v[70:73]
	v_mfma_f32_16x16x32_bf16 v[30:33], v[146:149], v[194:197], v[30:33]
	ds_read_b128 v[146:149], v22 offset:1024
	s_waitcnt lgkmcnt(0)
	v_mfma_f32_16x16x32_bf16 v[82:85], v[146:149], v[168:171], v[82:85]
	v_mfma_f32_16x16x32_bf16 v[86:89], v[146:149], v[172:175], v[86:89]
	v_mfma_f32_16x16x32_bf16 v[90:93], v[146:149], v[176:179], v[90:93]
	v_mfma_f32_16x16x32_bf16 v[74:77], v[146:149], v[194:197], v[74:77]
	ds_read_b128 v[146:149], v19 offset:1024
	s_waitcnt lgkmcnt(0)
	v_mfma_f32_16x16x32_bf16 v[94:97], v[146:149], v[168:171], v[94:97]
	v_mfma_f32_16x16x32_bf16 v[98:101], v[146:149], v[172:175], v[98:101]
	v_mfma_f32_16x16x32_bf16 v[102:105], v[146:149], v[176:179], v[102:105]
	v_mfma_f32_16x16x32_bf16 v[78:81], v[146:149], v[194:197], v[78:81]
	ds_read_b128 v[146:149], v21 offset:1024
	s_waitcnt lgkmcnt(0)
	v_mfma_f32_16x16x32_bf16 v[114:117], v[146:149], v[168:171], v[114:117]
	v_mfma_f32_16x16x32_bf16 v[118:121], v[146:149], v[172:175], v[118:121]
	v_mfma_f32_16x16x32_bf16 v[122:125], v[146:149], v[176:179], v[122:125]
	v_mfma_f32_16x16x32_bf16 v[106:109], v[146:149], v[194:197], v[106:109]
	ds_read_b128 v[146:149], v18 offset:1024
	s_waitcnt lgkmcnt(0)
	v_mfma_f32_16x16x32_bf16 v[130:133], v[146:149], v[168:171], v[130:133]
	v_mfma_f32_16x16x32_bf16 v[134:137], v[146:149], v[172:175], v[134:137]
	v_mfma_f32_16x16x32_bf16 v[138:141], v[146:149], v[176:179], v[138:141]
	v_mfma_f32_16x16x32_bf16 v[110:113], v[146:149], v[194:197], v[110:113]
	ds_read_b128 v[146:149], v20 offset:1024
	s_waitcnt lgkmcnt(0)
	v_mfma_f32_16x16x32_bf16 v[150:153], v[146:149], v[168:171], v[150:153]
	v_mfma_f32_16x16x32_bf16 v[154:157], v[146:149], v[172:175], v[154:157]
	v_mfma_f32_16x16x32_bf16 v[158:161], v[146:149], v[176:179], v[158:161]
	v_mfma_f32_16x16x32_bf16 v[142:145], v[146:149], v[194:197], v[142:145]
	ds_read_b128 v[146:149], v17 offset:1024
	s_waitcnt lgkmcnt(0)
	v_mfma_f32_16x16x32_bf16 v[34:37], v[146:149], v[172:175], v[34:37]
	v_mfma_f32_16x16x32_bf16 v[46:49], v[146:149], v[176:179], v[46:49]
	v_mfma_f32_16x16x32_bf16 v[50:53], v[146:149], v[194:197], v[50:53]
	v_mfma_f32_16x16x32_bf16 v[168:171], v[146:149], v[168:171], v[26:29]
	s_mov_b64 s[42:43], 0x500
	s_mov_b32 m0, s26
	s_nop 0
	v_lshl_add_u64 v[26:27], v[0:1], 0, s[42:43]
	s_waitcnt vmcnt(0)
	s_waitcnt vmcnt(0)
	s_barrier
	global_load_lds_dwordx4 v[26:27], off
	v_lshl_add_u64 v[26:27], v[2:3], 0, s[62:63]
	s_mov_b32 m0, s25
	s_nop 0
	global_load_lds_dwordx4 v[26:27], off
	v_lshl_add_u64 v[26:27], v[4:5], 0, s[42:43]
	s_mov_b32 m0, s27
	s_nop 0
	global_load_lds_dwordx4 v[26:27], off
	v_lshl_add_u64 v[26:27], v[6:7], 0, s[62:63]
	s_mov_b32 m0, s34
	s_nop 0
	global_load_lds_dwordx4 v[26:27], off
	v_lshl_add_u64 v[26:27], v[8:9], 0, s[42:43]
	s_mov_b32 m0, s35
	s_nop 0
	global_load_lds_dwordx4 v[26:27], off
	v_lshl_add_u64 v[26:27], v[10:11], 0, s[62:63]
	s_mov_b32 m0, s36
	s_nop 0
	global_load_lds_dwordx4 v[26:27], off
	v_lshl_add_u64 v[26:27], v[12:13], 0, s[42:43]
	s_mov_b32 m0, s37
	s_nop 0
	global_load_lds_dwordx4 v[26:27], off
	v_lshl_add_u64 v[26:27], v[14:15], 0, s[62:63]
	s_mov_b32 m0, s40
	s_nop 0
	global_load_lds_dwordx4 v[26:27], off
	v_add3_u32 v26, s90, v25, v126
	ds_read_b128 v[146:149], v26
	v_add3_u32 v25, s41, v25, v162
	ds_read_b128 v[172:175], v25
	ds_read_b128 v[176:179], v25 offset:2048
	ds_read_b128 v[194:197], v25 offset:4096
	ds_read_b128 v[198:201], v25 offset:6144
	v_add_u32_e32 v126, s90, v129
	v_add_u32_e32 v27, v126, v127
	v_add_u32_e32 v29, v126, v164
	ds_read_b128 v[202:205], v29
	s_waitcnt lgkmcnt(0)
	v_mfma_f32_16x16x32_bf16 v[38:41], v[146:149], v[172:175], v[38:41]
	v_add_u32_e32 v28, v126, v163
	v_add_u32_e32 v129, v126, v183
	v_mfma_f32_16x16x32_bf16 v[42:45], v[146:149], v[176:179], v[42:45]
	v_mfma_f32_16x16x32_bf16 v[54:57], v[146:149], v[194:197], v[54:57]
	v_mfma_f32_16x16x32_bf16 v[58:61], v[146:149], v[198:201], v[58:61]
	ds_read_b128 v[146:149], v27
	s_waitcnt lgkmcnt(0)
	v_mfma_f32_16x16x32_bf16 v[62:65], v[146:149], v[172:175], v[62:65]
	v_mfma_f32_16x16x32_bf16 v[66:69], v[146:149], v[176:179], v[66:69]
	v_mfma_f32_16x16x32_bf16 v[70:73], v[146:149], v[194:197], v[70:73]
	v_mfma_f32_16x16x32_bf16 v[146:149], v[146:149], v[198:201], v[30:33]
	s_nop 2
	ds_read_b128 v[30:33], v28
	s_waitcnt lgkmcnt(0)
	v_mfma_f32_16x16x32_bf16 v[82:85], v[30:33], v[172:175], v[82:85]
	v_mfma_f32_16x16x32_bf16 v[86:89], v[30:33], v[176:179], v[86:89]
	v_mfma_f32_16x16x32_bf16 v[90:93], v[30:33], v[194:197], v[90:93]
	v_mfma_f32_16x16x32_bf16 v[74:77], v[30:33], v[198:201], v[74:77]
	v_add_u32_e32 v30, v126, v180
	v_add_u32_e32 v31, v126, v182
	v_mfma_f32_16x16x32_bf16 v[94:97], v[202:205], v[172:175], v[94:97]
	v_mfma_f32_16x16x32_bf16 v[98:101], v[202:205], v[176:179], v[98:101]
	v_mfma_f32_16x16x32_bf16 v[102:105], v[202:205], v[194:197], v[102:105]
	v_mfma_f32_16x16x32_bf16 v[78:81], v[202:205], v[198:201], v[78:81]
	ds_read_b128 v[202:205], v30
	s_waitcnt lgkmcnt(0)
	v_mfma_f32_16x16x32_bf16 v[114:117], v[202:205], v[172:175], v[114:117]
	v_mfma_f32_16x16x32_bf16 v[118:121], v[202:205], v[176:179], v[118:121]
	v_mfma_f32_16x16x32_bf16 v[122:125], v[202:205], v[194:197], v[122:125]
	v_mfma_f32_16x16x32_bf16 v[106:109], v[202:205], v[198:201], v[106:109]
	ds_read_b128 v[202:205], v31
	s_waitcnt lgkmcnt(0)
	v_mfma_f32_16x16x32_bf16 v[206:209], v[202:205], v[172:175], v[130:133]
	s_nop 2
	v_add_u32_e32 v130, v126, v193
	v_mfma_f32_16x16x32_bf16 v[132:135], v[202:205], v[176:179], v[134:137]
	v_mfma_f32_16x16x32_bf16 v[136:139], v[202:205], v[194:197], v[138:141]
	v_mfma_f32_16x16x32_bf16 v[110:113], v[202:205], v[198:201], v[110:113]
	ds_read_b128 v[202:205], v129
	s_waitcnt lgkmcnt(0)
	v_mfma_f32_16x16x32_bf16 v[150:153], v[202:205], v[172:175], v[150:153]
	v_mfma_f32_16x16x32_bf16 v[154:157], v[202:205], v[176:179], v[154:157]
	v_mfma_f32_16x16x32_bf16 v[158:161], v[202:205], v[194:197], v[158:161]
	v_mfma_f32_16x16x32_bf16 v[140:143], v[202:205], v[198:201], v[142:145]
	ds_read_b128 v[202:205], v130
	s_waitcnt lgkmcnt(0)
	v_mfma_f32_16x16x32_bf16 v[32:35], v[202:205], v[176:179], v[34:37]
	v_mfma_f32_16x16x32_bf16 v[46:49], v[202:205], v[194:197], v[46:49]
	v_mfma_f32_16x16x32_bf16 v[50:53], v[202:205], v[198:201], v[50:53]
	v_mfma_f32_16x16x32_bf16 v[168:171], v[202:205], v[172:175], v[168:171]
	ds_read_b128 v[172:175], v26 offset:1024
	ds_read_b128 v[176:179], v25 offset:1024
	ds_read_b128 v[194:197], v25 offset:3072
	ds_read_b128 v[198:201], v25 offset:5120
	ds_read_b128 v[202:205], v25 offset:7168
	s_waitcnt lgkmcnt(0)
	v_mfma_f32_16x16x32_bf16 v[36:39], v[172:175], v[176:179], v[38:41]
	v_mfma_f32_16x16x32_bf16 v[40:43], v[172:175], v[194:197], v[42:45]
	v_mfma_f32_16x16x32_bf16 v[54:57], v[172:175], v[198:201], v[54:57]
	v_mfma_f32_16x16x32_bf16 v[58:61], v[172:175], v[202:205], v[58:61]
	ds_read_b128 v[172:175], v27 offset:1024
	s_waitcnt lgkmcnt(0)
	v_mfma_f32_16x16x32_bf16 v[62:65], v[172:175], v[176:179], v[62:65]
	v_mfma_f32_16x16x32_bf16 v[66:69], v[172:175], v[194:197], v[66:69]
	v_mfma_f32_16x16x32_bf16 v[70:73], v[172:175], v[198:201], v[70:73]
	v_mfma_f32_16x16x32_bf16 v[144:147], v[172:175], v[202:205], v[146:149]
	ds_read_b128 v[172:175], v28 offset:1024
	s_waitcnt lgkmcnt(0)
	v_mfma_f32_16x16x32_bf16 v[82:85], v[172:175], v[176:179], v[82:85]
	v_mfma_f32_16x16x32_bf16 v[86:89], v[172:175], v[194:197], v[86:89]
	v_mfma_f32_16x16x32_bf16 v[90:93], v[172:175], v[198:201], v[90:93]
	v_mfma_f32_16x16x32_bf16 v[74:77], v[172:175], v[202:205], v[74:77]
	ds_read_b128 v[172:175], v29 offset:1024
	s_waitcnt lgkmcnt(0)
	v_mfma_f32_16x16x32_bf16 v[94:97], v[172:175], v[176:179], v[94:97]
	v_mfma_f32_16x16x32_bf16 v[98:101], v[172:175], v[194:197], v[98:101]
	v_mfma_f32_16x16x32_bf16 v[102:105], v[172:175], v[198:201], v[102:105]
	v_mfma_f32_16x16x32_bf16 v[78:81], v[172:175], v[202:205], v[78:81]
	ds_read_b128 v[172:175], v30 offset:1024
	s_waitcnt lgkmcnt(0)
	v_mfma_f32_16x16x32_bf16 v[114:117], v[172:175], v[176:179], v[114:117]
	v_mfma_f32_16x16x32_bf16 v[118:121], v[172:175], v[194:197], v[118:121]
	v_mfma_f32_16x16x32_bf16 v[122:125], v[172:175], v[198:201], v[122:125]
	v_mfma_f32_16x16x32_bf16 v[106:109], v[172:175], v[202:205], v[106:109]
	ds_read_b128 v[172:175], v31 offset:1024
	s_waitcnt lgkmcnt(0)
	v_mfma_f32_16x16x32_bf16 v[206:209], v[172:175], v[176:179], v[206:209]
	v_mfma_f32_16x16x32_bf16 v[132:135], v[172:175], v[194:197], v[132:135]
	v_mfma_f32_16x16x32_bf16 v[136:139], v[172:175], v[198:201], v[136:139]
	v_mfma_f32_16x16x32_bf16 v[110:113], v[172:175], v[202:205], v[110:113]
	ds_read_b128 v[172:175], v129 offset:1024
	s_waitcnt lgkmcnt(0)
	v_mfma_f32_16x16x32_bf16 v[148:151], v[172:175], v[176:179], v[150:153]
	v_mfma_f32_16x16x32_bf16 v[152:155], v[172:175], v[194:197], v[154:157]
	v_mfma_f32_16x16x32_bf16 v[156:159], v[172:175], v[198:201], v[158:161]
	s_nop 2
	ds_read_b128 v[160:163], v130 offset:1024
	s_waitcnt lgkmcnt(0)
	v_mfma_f32_16x16x32_bf16 v[32:35], v[160:163], v[194:197], v[32:35]
	v_mfma_f32_16x16x32_bf16 v[44:47], v[160:163], v[198:201], v[46:49]
	v_mfma_f32_16x16x32_bf16 v[48:51], v[160:163], v[202:205], v[50:53]
	v_mfma_f32_16x16x32_bf16 v[140:143], v[172:175], v[202:205], v[140:143]
	v_mfma_f32_16x16x32_bf16 v[168:171], v[160:163], v[176:179], v[168:171]
	s_mov_b64 s[26:27], 0x580
	s_mov_b32 m0, s3
	v_lshl_add_u64 v[0:1], v[0:1], 0, s[26:27]
	s_waitcnt vmcnt(0)
	s_waitcnt vmcnt(0)
	s_barrier
	global_load_lds_dwordx4 v[0:1], off
	v_lshl_add_u64 v[0:1], v[2:3], 0, s[6:7]
	s_mov_b32 m0, s0
	s_nop 0
	global_load_lds_dwordx4 v[0:1], off
	v_lshl_add_u64 v[0:1], v[4:5], 0, s[26:27]
	s_mov_b32 m0, s1
	s_nop 0
	global_load_lds_dwordx4 v[0:1], off
	v_lshl_add_u64 v[0:1], v[6:7], 0, s[6:7]
	s_mov_b32 m0, s2
	s_nop 0
	global_load_lds_dwordx4 v[0:1], off
	v_lshl_add_u64 v[0:1], v[8:9], 0, s[26:27]
	s_mov_b32 m0, s11
	s_nop 0
	global_load_lds_dwordx4 v[0:1], off
	v_lshl_add_u64 v[0:1], v[10:11], 0, s[6:7]
	s_mov_b32 m0, s16
	s_nop 0
	global_load_lds_dwordx4 v[0:1], off
	v_lshl_add_u64 v[0:1], v[12:13], 0, s[26:27]
	s_mov_b32 m0, s21
	s_nop 0
	global_load_lds_dwordx4 v[0:1], off
	v_lshl_add_u64 v[0:1], v[14:15], 0, s[6:7]
	s_mov_b32 m0, s24
	s_nop 0
	global_load_lds_dwordx4 v[0:1], off
	ds_read_b128 v[0:3], v24
	ds_read_b128 v[4:7], v23 offset:32768
	ds_read_b128 v[12:15], v23 offset:34816
	ds_read_b128 v[160:163], v23 offset:38912
	s_waitcnt lgkmcnt(0)
	v_mfma_f32_16x16x32_bf16 v[8:11], v[0:3], v[4:7], v[36:39]
	v_mfma_f32_16x16x32_bf16 v[36:39], v[0:3], v[12:15], v[40:43]
	s_nop 2
	ds_read_b128 v[40:43], v23 offset:36864
	s_waitcnt lgkmcnt(0)
	v_mfma_f32_16x16x32_bf16 v[52:55], v[0:3], v[40:43], v[54:57]
	v_mfma_f32_16x16x32_bf16 v[0:3], v[0:3], v[160:163], v[58:61]
	s_nop 2
	ds_read_b128 v[56:59], v16
	s_waitcnt lgkmcnt(0)
	v_mfma_f32_16x16x32_bf16 v[60:63], v[56:59], v[4:7], v[62:65]
	v_mfma_f32_16x16x32_bf16 v[64:67], v[56:59], v[12:15], v[66:69]
	v_mfma_f32_16x16x32_bf16 v[68:71], v[56:59], v[40:43], v[70:73]
	v_mfma_f32_16x16x32_bf16 v[56:59], v[56:59], v[160:163], v[144:147]
	s_nop 2
	ds_read_b128 v[144:147], v22
	s_waitcnt lgkmcnt(0)
	v_mfma_f32_16x16x32_bf16 v[82:85], v[144:147], v[4:7], v[82:85]
	v_mfma_f32_16x16x32_bf16 v[86:89], v[144:147], v[12:15], v[86:89]
	v_mfma_f32_16x16x32_bf16 v[90:93], v[144:147], v[40:43], v[90:93]
	v_mfma_f32_16x16x32_bf16 v[72:75], v[144:147], v[160:163], v[74:77]
	ds_read_b128 v[144:147], v19
	s_waitcnt lgkmcnt(0)
	v_mfma_f32_16x16x32_bf16 v[94:97], v[144:147], v[4:7], v[94:97]
	v_mfma_f32_16x16x32_bf16 v[98:101], v[144:147], v[12:15], v[98:101]
	v_mfma_f32_16x16x32_bf16 v[102:105], v[144:147], v[40:43], v[102:105]
	v_mfma_f32_16x16x32_bf16 v[76:79], v[144:147], v[160:163], v[78:81]
	ds_read_b128 v[144:147], v21
	s_waitcnt lgkmcnt(0)
	v_mfma_f32_16x16x32_bf16 v[114:117], v[144:147], v[4:7], v[114:117]
	v_mfma_f32_16x16x32_bf16 v[118:121], v[144:147], v[12:15], v[118:121]
	v_mfma_f32_16x16x32_bf16 v[122:125], v[144:147], v[40:43], v[122:125]
	v_mfma_f32_16x16x32_bf16 v[106:109], v[144:147], v[160:163], v[106:109]
	ds_read_b128 v[144:147], v18
	s_waitcnt lgkmcnt(0)
	v_mfma_f32_16x16x32_bf16 v[172:175], v[144:147], v[4:7], v[206:209]
	v_mfma_f32_16x16x32_bf16 v[132:135], v[144:147], v[12:15], v[132:135]
	v_mfma_f32_16x16x32_bf16 v[136:139], v[144:147], v[40:43], v[136:139]
	v_mfma_f32_16x16x32_bf16 v[110:113], v[144:147], v[160:163], v[110:113]
	ds_read_b128 v[144:147], v20
	s_waitcnt lgkmcnt(0)
	v_mfma_f32_16x16x32_bf16 v[148:151], v[144:147], v[4:7], v[148:151]
	v_mfma_f32_16x16x32_bf16 v[152:155], v[144:147], v[12:15], v[152:155]
	v_mfma_f32_16x16x32_bf16 v[156:159], v[144:147], v[40:43], v[156:159]
	v_mfma_f32_16x16x32_bf16 v[140:143], v[144:147], v[160:163], v[140:143]
	ds_read_b128 v[144:147], v17
	s_waitcnt lgkmcnt(0)
	v_mfma_f32_16x16x32_bf16 v[4:7], v[144:147], v[4:7], v[168:171]
	v_mfma_f32_16x16x32_bf16 v[12:15], v[144:147], v[12:15], v[32:35]
	v_mfma_f32_16x16x32_bf16 v[32:35], v[144:147], v[40:43], v[44:47]
	v_mfma_f32_16x16x32_bf16 v[40:43], v[144:147], v[160:163], v[48:51]
	s_nop 1
	ds_read_b128 v[44:47], v24 offset:1024
	ds_read_b128 v[48:51], v23 offset:33792
	ds_read_b128 v[144:147], v23 offset:35840
	ds_read_b128 v[160:163], v23 offset:37888
	ds_read_b128 v[168:171], v23 offset:39936
	s_waitcnt lgkmcnt(0)
	v_mfma_f32_16x16x32_bf16 v[8:11], v[44:47], v[48:51], v[8:11]
	v_mfma_f32_16x16x32_bf16 v[36:39], v[44:47], v[144:147], v[36:39]
	v_mfma_f32_16x16x32_bf16 v[52:55], v[44:47], v[160:163], v[52:55]
	v_mfma_f32_16x16x32_bf16 v[0:3], v[44:47], v[168:171], v[0:3]
	ds_read_b128 v[44:47], v16 offset:1024
	s_waitcnt lgkmcnt(0)
	v_mfma_f32_16x16x32_bf16 v[60:63], v[44:47], v[48:51], v[60:63]
	v_mfma_f32_16x16x32_bf16 v[64:67], v[44:47], v[144:147], v[64:67]
	v_mfma_f32_16x16x32_bf16 v[68:71], v[44:47], v[160:163], v[68:71]
	v_mfma_f32_16x16x32_bf16 v[44:47], v[44:47], v[168:171], v[56:59]
	s_nop 2
	ds_read_b128 v[56:59], v22 offset:1024
	s_waitcnt lgkmcnt(0)
	v_mfma_f32_16x16x32_bf16 v[80:83], v[56:59], v[48:51], v[82:85]
	v_mfma_f32_16x16x32_bf16 v[84:87], v[56:59], v[144:147], v[86:89]
	v_mfma_f32_16x16x32_bf16 v[88:91], v[56:59], v[160:163], v[90:93]
	v_mfma_f32_16x16x32_bf16 v[56:59], v[56:59], v[168:171], v[72:75]
	s_nop 2
	ds_read_b128 v[72:75], v19 offset:1024
	s_waitcnt lgkmcnt(0)
	v_mfma_f32_16x16x32_bf16 v[92:95], v[72:75], v[48:51], v[94:97]
	v_mfma_f32_16x16x32_bf16 v[96:99], v[72:75], v[144:147], v[98:101]
	v_mfma_f32_16x16x32_bf16 v[100:103], v[72:75], v[160:163], v[102:105]
	v_mfma_f32_16x16x32_bf16 v[72:75], v[72:75], v[168:171], v[76:79]
	s_nop 2
	ds_read_b128 v[76:79], v21 offset:1024
	s_waitcnt lgkmcnt(0)
	v_mfma_f32_16x16x32_bf16 v[114:117], v[76:79], v[48:51], v[114:117]
	v_mfma_f32_16x16x32_bf16 v[118:121], v[76:79], v[144:147], v[118:121]
	v_mfma_f32_16x16x32_bf16 v[122:125], v[76:79], v[160:163], v[122:125]
	v_mfma_f32_16x16x32_bf16 v[76:79], v[76:79], v[168:171], v[106:109]
	s_nop 2
	ds_read_b128 v[104:107], v18 offset:1024
	ds_read_b128 v[18:21], v20 offset:1024
	s_waitcnt lgkmcnt(0)
	v_mfma_f32_16x16x32_bf16 v[172:175], v[104:107], v[48:51], v[172:175]
	v_mfma_f32_16x16x32_bf16 v[132:135], v[104:107], v[144:147], v[132:135]
	v_mfma_f32_16x16x32_bf16 v[136:139], v[104:107], v[160:163], v[136:139]
	v_mfma_f32_16x16x32_bf16 v[104:107], v[104:107], v[168:171], v[110:113]
	v_mfma_f32_16x16x32_bf16 v[108:111], v[18:21], v[48:51], v[148:151]
	v_mfma_f32_16x16x32_bf16 v[148:151], v[18:21], v[144:147], v[152:155]
	v_mfma_f32_16x16x32_bf16 v[152:155], v[18:21], v[160:163], v[156:159]
	v_mfma_f32_16x16x32_bf16 v[18:21], v[18:21], v[168:171], v[140:143]
	s_nop 2
	ds_read_b128 v[140:143], v17 offset:1024
	s_waitcnt lgkmcnt(0)
	v_mfma_f32_16x16x32_bf16 v[4:7], v[140:143], v[48:51], v[4:7]
	v_mfma_f32_16x16x32_bf16 v[12:15], v[140:143], v[144:147], v[12:15]
	v_mfma_f32_16x16x32_bf16 v[32:35], v[140:143], v[160:163], v[32:35]
	v_mfma_f32_16x16x32_bf16 v[40:43], v[140:143], v[168:171], v[40:43]
	s_waitcnt vmcnt(0)
	s_waitcnt vmcnt(0)
	s_barrier
	ds_read_b128 v[48:51], v26
	ds_read_b128 v[140:143], v25
	ds_read_b128 v[144:147], v25 offset:2048
	ds_read_b128 v[156:159], v25 offset:4096
	ds_read_b128 v[160:163], v25 offset:6144
	s_waitcnt lgkmcnt(3)
	v_mfma_f32_16x16x32_bf16 v[8:11], v[48:51], v[140:143], v[8:11]
	s_waitcnt lgkmcnt(2)
	v_mfma_f32_16x16x32_bf16 v[36:39], v[48:51], v[144:147], v[36:39]
	s_waitcnt lgkmcnt(1)
	v_mfma_f32_16x16x32_bf16 v[52:55], v[48:51], v[156:159], v[52:55]
	s_waitcnt lgkmcnt(0)
	v_mfma_f32_16x16x32_bf16 v[0:3], v[48:51], v[160:163], v[0:3]
	ds_read_b128 v[48:51], v27
	s_waitcnt lgkmcnt(0)
	v_mfma_f32_16x16x32_bf16 v[60:63], v[48:51], v[140:143], v[60:63]
	v_mfma_f32_16x16x32_bf16 v[64:67], v[48:51], v[144:147], v[64:67]
	v_mfma_f32_16x16x32_bf16 v[68:71], v[48:51], v[156:159], v[68:71]
	v_mfma_f32_16x16x32_bf16 v[44:47], v[48:51], v[160:163], v[44:47]
	ds_read_b128 v[48:51], v28
	s_waitcnt lgkmcnt(0)
	v_mfma_f32_16x16x32_bf16 v[80:83], v[48:51], v[140:143], v[80:83]
	v_mfma_f32_16x16x32_bf16 v[84:87], v[48:51], v[144:147], v[84:87]
	v_mfma_f32_16x16x32_bf16 v[168:171], v[48:51], v[156:159], v[88:91]
	v_mfma_f32_16x16x32_bf16 v[48:51], v[48:51], v[160:163], v[56:59]
	s_nop 2
	ds_read_b128 v[56:59], v29
	s_waitcnt lgkmcnt(0)
	v_mfma_f32_16x16x32_bf16 v[176:179], v[56:59], v[140:143], v[92:95]
	v_mfma_f32_16x16x32_bf16 v[194:197], v[56:59], v[144:147], v[96:99]
	v_mfma_f32_16x16x32_bf16 v[198:201], v[56:59], v[156:159], v[100:103]
	v_mfma_f32_16x16x32_bf16 v[56:59], v[56:59], v[160:163], v[72:75]
	s_nop 2
	ds_read_b128 v[72:75], v30
	s_waitcnt lgkmcnt(0)
	v_mfma_f32_16x16x32_bf16 v[202:205], v[72:75], v[140:143], v[114:117]
	v_mfma_f32_16x16x32_bf16 v[206:209], v[72:75], v[144:147], v[118:121]
	v_mfma_f32_16x16x32_bf16 v[210:213], v[72:75], v[156:159], v[122:125]
	v_mfma_f32_16x16x32_bf16 v[214:217], v[72:75], v[160:163], v[76:79]
	ds_read_b128 v[72:75], v31
	s_waitcnt lgkmcnt(0)
	v_mfma_f32_16x16x32_bf16 v[172:175], v[72:75], v[140:143], v[172:175]
	v_mfma_f32_16x16x32_bf16 v[132:135], v[72:75], v[144:147], v[132:135]
	v_mfma_f32_16x16x32_bf16 v[136:139], v[72:75], v[156:159], v[136:139]
	v_mfma_f32_16x16x32_bf16 v[218:221], v[72:75], v[160:163], v[104:107]
	ds_read_b128 v[72:75], v129
	s_waitcnt lgkmcnt(0)
	v_mfma_f32_16x16x32_bf16 v[16:19], v[72:75], v[160:163], v[18:21]
	s_nop 2
	ds_read_b128 v[20:23], v130
	s_waitcnt lgkmcnt(0)
	v_mfma_f32_16x16x32_bf16 v[4:7], v[20:23], v[140:143], v[4:7]
	v_mfma_f32_16x16x32_bf16 v[222:225], v[72:75], v[140:143], v[108:111]
	v_mfma_f32_16x16x32_bf16 v[148:151], v[72:75], v[144:147], v[148:151]
	v_mfma_f32_16x16x32_bf16 v[152:155], v[72:75], v[156:159], v[152:155]
	v_mfma_f32_16x16x32_bf16 v[140:143], v[20:23], v[144:147], v[12:15]
	v_mfma_f32_16x16x32_bf16 v[144:147], v[20:23], v[156:159], v[32:35]
	v_mfma_f32_16x16x32_bf16 v[156:159], v[20:23], v[160:163], v[40:43]
	s_nop 0
	ds_read_b128 v[12:15], v26 offset:1024
	ds_read_b128 v[160:163], v25 offset:1024
	ds_read_b128 v[230:233], v25 offset:7168
	s_waitcnt lgkmcnt(0)
	v_mfma_f32_16x16x32_bf16 v[112:115], v[12:15], v[230:233], v[0:3]
	s_nop 2
	ds_read_b128 v[0:3], v27 offset:1024
	ds_read_b128 v[226:229], v25 offset:5120
	v_mfma_f32_16x16x32_bf16 v[124:127], v[12:15], v[160:163], v[8:11]
	s_nop 2
	ds_read_b128 v[8:11], v25 offset:3072
	s_waitcnt lgkmcnt(2)
	v_mfma_f32_16x16x32_bf16 v[108:111], v[0:3], v[160:163], v[60:63]
	s_waitcnt lgkmcnt(0)
	v_mfma_f32_16x16x32_bf16 v[104:107], v[0:3], v[8:11], v[64:67]
	v_mfma_f32_16x16x32_bf16 v[100:103], v[0:3], v[226:229], v[68:71]
	v_mfma_f32_16x16x32_bf16 v[96:99], v[0:3], v[230:233], v[44:47]
	ds_read_b128 v[0:3], v28 offset:1024
	s_waitcnt lgkmcnt(0)
	v_mfma_f32_16x16x32_bf16 v[92:95], v[0:3], v[160:163], v[80:83]
	v_mfma_f32_16x16x32_bf16 v[88:91], v[0:3], v[8:11], v[84:87]
	v_mfma_f32_16x16x32_bf16 v[84:87], v[0:3], v[226:229], v[168:171]
	v_mfma_f32_16x16x32_bf16 v[80:83], v[0:3], v[230:233], v[48:51]
	ds_read_b128 v[0:3], v29 offset:1024
	s_waitcnt lgkmcnt(0)
	v_mfma_f32_16x16x32_bf16 v[76:79], v[0:3], v[160:163], v[176:179]
	v_mfma_f32_16x16x32_bf16 v[72:75], v[0:3], v[8:11], v[194:197]
	v_mfma_f32_16x16x32_bf16 v[68:71], v[0:3], v[226:229], v[198:201]
	v_mfma_f32_16x16x32_bf16 v[64:67], v[0:3], v[230:233], v[56:59]
	ds_read_b128 v[0:3], v30 offset:1024
	v_mfma_f32_16x16x32_bf16 v[116:119], v[12:15], v[226:229], v[52:55]
	s_waitcnt lgkmcnt(0)
	v_mfma_f32_16x16x32_bf16 v[60:63], v[0:3], v[160:163], v[202:205]
	v_mfma_f32_16x16x32_bf16 v[56:59], v[0:3], v[8:11], v[206:209]
	v_mfma_f32_16x16x32_bf16 v[52:55], v[0:3], v[226:229], v[210:213]
	v_mfma_f32_16x16x32_bf16 v[48:51], v[0:3], v[230:233], v[214:217]
	ds_read_b128 v[0:3], v31 offset:1024
	v_mfma_f32_16x16x32_bf16 v[120:123], v[12:15], v[8:11], v[36:39]
	s_waitcnt lgkmcnt(0)
	v_mfma_f32_16x16x32_bf16 v[44:47], v[0:3], v[160:163], v[172:175]
	v_mfma_f32_16x16x32_bf16 v[40:43], v[0:3], v[8:11], v[132:135]
	v_mfma_f32_16x16x32_bf16 v[36:39], v[0:3], v[226:229], v[136:139]
	v_mfma_f32_16x16x32_bf16 v[32:35], v[0:3], v[230:233], v[218:221]
	ds_read_b128 v[0:3], v129 offset:1024
	s_waitcnt lgkmcnt(0)
	v_mfma_f32_16x16x32_bf16 v[28:31], v[0:3], v[160:163], v[222:225]
	v_mfma_f32_16x16x32_bf16 v[24:27], v[0:3], v[8:11], v[148:151]
	v_mfma_f32_16x16x32_bf16 v[20:23], v[0:3], v[226:229], v[152:155]
	v_mfma_f32_16x16x32_bf16 v[16:19], v[0:3], v[230:233], v[16:19]
	ds_read_b128 v[0:3], v130 offset:1024
	s_waitcnt lgkmcnt(0)
	v_mfma_f32_16x16x32_bf16 v[12:15], v[0:3], v[160:163], v[4:7]
	v_mfma_f32_16x16x32_bf16 v[8:11], v[0:3], v[8:11], v[140:143]
	v_mfma_f32_16x16x32_bf16 v[4:7], v[0:3], v[226:229], v[144:147]
	v_mfma_f32_16x16x32_bf16 v[0:3], v[0:3], v[230:233], v[156:159]
	s_waitcnt vmcnt(0)
	v_ashrrev_i32_e32 v132, 1, v128
	v_and_b32_e32 v131, 0xffffff80, v132
	v_add_u32_e32 v129, s9, v131
	s_cmp_gt_i32 s8, 63
	s_mov_b64 s[0:1], -1
	s_barrier
	s_cbranch_scc0 .LBB0_943
	v_add_u32_e32 v130, 0xffffc000, v129
	v_ashrrev_i32_e32 v130, 8, v130
	v_and_b32_e32 v164, 0x80, v132
	s_mov_b64 s[0:1], 0
